# v16 variant: progressive A-fragment hoist limited to reads whose last user is MFMA 8 or earlier (4 of 8 reads hoisted, none near the group tail)
# speedup vs baseline: 1.0018x; 1.0018x over previous
; #define PG8_STAGE(bufoff, gbase, voff) do { _Pragma("unroll") for (int _i = 0; _i < 2; ++_i) \
;         __builtin_amdgcn_global_load_lds((const unsigned*)((const char*)(gbase) + (voff)[_i]), (LAS unsigned*)(lds + (bufoff) + ldsw + _i * 8192), 16, 0, 0); } while (0)
; #define PG8_LDA(dst, b, h) do { _Pragma("unroll") for (int m = 0; m < 4; ++m) _Pragma("unroll") for (int k = 0; k < 2; ++k) dst[m][k] = *(const LAS bf16x8*)(lds + PG8_SA(b, h) + aoff + m * 2048 + k * 1024); } while (0)
; #define PG8_WAIT_V(n) asm volatile("s_waitcnt vmcnt(" #n ")" ::: "memory")
; #define PG8_WAIT_L(n) asm volatile("s_waitcnt lgkmcnt(" #n ")" ::: "memory")
; template <class Epi, class Sched>
; __device__ __forceinline__ void gemm_phase(LAS unsigned char* lds, const Gemm g, const Sched& S, const Epi& E) {
;     ...
;     const char* cA = PG8_APANEL(cur.pm); const char* cB = (const char*)g.Bt + (size_t)cur.pn * tstep;
;     PG8_STAGE(PG8_SB(0, 0), cB, voffB); PG8_STAGE(PG8_SA(0, 0), cA, voffA); PG8_STAGE(PG8_SB(0, 1), cB + hstep, voffB); PG8_STAGE(PG8_SA(0, 1), cA + hstep, voffA);
;     if (wr == 1) PG8_BAR;
;     PG8_WAIT_V(4); PG8_BAR;
;     PG8_STAGE(PG8_SB(1, 0), cB + kstep, voffB); PG8_STAGE(PG8_SA(1, 0), cA + kstep, voffA); PG8_STAGE(PG8_SB(1, 1), cB + hstep + kstep, voffB);
;     PG8_WAIT_V(6); PG8_BAR;
;     for (;;) {
;         const bool has_next = S.next(ui + 1, nxt);
;         const char* nA = has_next ? PG8_APANEL(nxt.pm) : cA; const char* nB = has_next ? (const char*)g.Bt + (size_t)nxt.pn * tstep : cB;
;         for (int t = 0; t < nt; t += 2) {
;             const bool last = (t == nt - 2);
;             const char* a1 = cA + (size_t)(t + 1) * kstep;
;             const char* a2 = last ? nA : cA + (size_t)(t + 2) * kstep; const char* b2 = last ? nB : cB + (size_t)(t + 2) * kstep;
;             const char* a3 = a2 + kstep; const char* b3 = b2 + kstep;
;             PG8_LDB(B0, 0, 0); PG8_SCHED; PG8_LDA(At, 0, 0); PG8_STAGE(PG8_SA(1, 1), a1 + hstep, voffA);
;             PG8_WAIT_L(8); PG8_BAR; PG8_WAIT_L(0); PG8_MMA(0, 0, At, B0); PG8_BAR; PG8_SCHED;
;             PG8_LDB(B1, 0, 1); PG8_STAGE(PG8_SB(0, 0), b2, voffB);
;             PG8_BAR; PG8_WAIT_L(0); PG8_MMA(0, 1, At, B1); PG8_BAR;
;             PG8_LDA(At, 0, 1); PG8_STAGE(PG8_SA(0, 0), a2, voffA);
;             PG8_BAR; PG8_WAIT_L(0); PG8_MMA(1, 0, At, B0); PG8_BAR; PG8_SCHED;
.LBB0_164:
	s_cmp_lt_i32 s44, 0x100000
	s_cselect_b32 s24, s20, 0xffffff80
	s_cselect_b32 s25, s11, 0
	s_ashr_i32 s45, s44, 31
	s_lshl_b64 s[34:35], s[44:45], 19
	v_cmp_lt_i64_e32 vcc, s[46:47], v[152:153]
	s_add_u32 s46, s25, s34
	s_addc_u32 s47, s24, s35
	s_and_b64 s[34:35], vcc, exec
	s_cselect_b32 s34, s47, s49
	s_cselect_b32 s45, s46, s48
	s_ashr_i32 s43, s42, 31
	s_lshl_b64 s[60:61], s[42:43], 19
	s_add_u32 s76, s16, s60
	s_addc_u32 s77, s92, s61
	s_and_b64 s[60:61], vcc, exec
	s_cselect_b32 s43, s77, s39
	s_cselect_b32 s79, s76, s38
	s_add_u32 vcc_lo, s38, 0x100
	s_addc_u32 s35, s39, 0
	s_add_u32 s38, s48, 0x40080
	s_addc_u32 s39, s49, 0
	s_mov_b32 s50, -2
	v_add_u32_e32 v249, 0x10000, v167
	ds_read_b128 v[142:145], v249
	ds_read_b128 v[162:165], v249 offset:1024
	ds_read_b128 v[182:185], v249 offset:2048
	ds_read_b128 v[186:189], v249 offset:3072
	ds_read_b128 v[190:193], v169
	ds_read_b128 v[194:197], v169 offset:1024
	ds_read_b128 v[198:201], v169 offset:2048
	ds_read_b128 v[202:205], v169 offset:3072
	s_add_u32 s24, s38, 0xfffc0080
	s_addc_u32 s25, s39, -1
	s_add_i32 vcc_hi, 0, 0x10000
	s_cmp_eq_u32 s50, 12
	s_cselect_b32 s61, s34, s25
	s_cselect_b32 s60, s45, s24
	s_cselect_b32 s49, s43, s35
	s_cselect_b32 s48, s79, vcc_lo
	s_add_i32 m0, s93, 0xc000
	ds_read_b128 v[206:209], v169 offset:4096
	ds_read_b128 v[210:213], v169 offset:5120
	ds_read_b128 v[214:217], v169 offset:6144
	ds_read_b128 v[218:221], v169 offset:7168
	global_load_lds_dwordx4 v140, s[38:39]
	s_add_i32 m0, s93, 0xe000
	s_nop 0
	global_load_lds_dwordx4 v138, s[38:39]
	s_waitcnt lgkmcnt(8)
	s_barrier
	s_waitcnt lgkmcnt(0)
	s_setprio 1
	s_waitcnt lgkmcnt(0)
	v_mfma_f32_16x16x32_bf16 v[126:129], v[142:145], v[190:193], 0
	v_mfma_f32_16x16x32_bf16 v[126:129], v[162:165], v[194:197], v[126:129]
	v_mfma_f32_16x16x32_bf16 v[122:125], v[182:185], v[190:193], 0
	v_mfma_f32_16x16x32_bf16 v[122:125], v[186:189], v[194:197], v[122:125]
	v_mfma_f32_16x16x32_bf16 v[110:113], v[142:145], v[198:201], 0
	v_mfma_f32_16x16x32_bf16 v[110:113], v[162:165], v[202:205], v[110:113]
	v_mfma_f32_16x16x32_bf16 v[106:109], v[182:185], v[198:201], 0
	v_mfma_f32_16x16x32_bf16 v[106:109], v[186:189], v[202:205], v[106:109]
	v_mfma_f32_16x16x32_bf16 v[94:97], v[142:145], v[206:209], 0
	v_mfma_f32_16x16x32_bf16 v[94:97], v[162:165], v[210:213], v[94:97]
	v_mfma_f32_16x16x32_bf16 v[90:93], v[182:185], v[206:209], 0
	v_mfma_f32_16x16x32_bf16 v[90:93], v[186:189], v[210:213], v[90:93]
	v_mfma_f32_16x16x32_bf16 v[78:81], v[142:145], v[214:217], 0
	v_mfma_f32_16x16x32_bf16 v[78:81], v[162:165], v[218:221], v[78:81]
	v_mfma_f32_16x16x32_bf16 v[74:77], v[182:185], v[214:217], 0
	s_barrier
	v_mfma_f32_16x16x32_bf16 v[74:77], v[186:189], v[218:221], v[74:77]
	s_setprio 0
	s_add_i32 s51, 0, 0x14000
	s_add_i32 s24, vcc_hi, s86
	s_mov_b32 m0, s24
	ds_read_b128 v[222:225], v249 offset:16384
	ds_read_b128 v[226:229], v249 offset:17408
	ds_read_b128 v[230:233], v249 offset:18432
	ds_read_b128 v[234:237], v249 offset:19456
	global_load_lds_dwordx4 v134, s[48:49]
	s_add_i32 m0, s24, 0x2000
	s_nop 0
	global_load_lds_dwordx4 v130, s[48:49]
	s_barrier
	s_waitcnt lgkmcnt(0)
	s_setprio 1
	s_waitcnt lgkmcnt(0)
	v_mfma_f32_16x16x32_bf16 v[118:121], v[222:225], v[190:193], 0
	v_mfma_f32_16x16x32_bf16 v[118:121], v[226:229], v[194:197], v[118:121]
	v_mfma_f32_16x16x32_bf16 v[114:117], v[230:233], v[190:193], 0
	v_mfma_f32_16x16x32_bf16 v[114:117], v[234:237], v[194:197], v[114:117]
	v_mfma_f32_16x16x32_bf16 v[102:105], v[222:225], v[198:201], 0
	v_mfma_f32_16x16x32_bf16 v[102:105], v[226:229], v[202:205], v[102:105]
	v_mfma_f32_16x16x32_bf16 v[98:101], v[230:233], v[198:201], 0
	v_mfma_f32_16x16x32_bf16 v[98:101], v[234:237], v[202:205], v[98:101]
	v_mfma_f32_16x16x32_bf16 v[86:89], v[222:225], v[206:209], 0
	v_mfma_f32_16x16x32_bf16 v[86:89], v[226:229], v[210:213], v[86:89]
	v_mfma_f32_16x16x32_bf16 v[82:85], v[230:233], v[206:209], 0
	v_mfma_f32_16x16x32_bf16 v[82:85], v[234:237], v[210:213], v[82:85]
	v_mfma_f32_16x16x32_bf16 v[70:73], v[222:225], v[214:217], 0
	v_mfma_f32_16x16x32_bf16 v[70:73], v[226:229], v[218:221], v[70:73]
	v_mfma_f32_16x16x32_bf16 v[66:69], v[230:233], v[214:217], 0
	s_barrier
	v_mfma_f32_16x16x32_bf16 v[66:69], v[234:237], v[218:221], v[66:69]
	s_setprio 0
	s_mov_b32 m0, s93
	s_mov_b64 s[100:101], s[60:61]
	ds_read_b128 v[190:193], v169 offset:16384
	ds_read_b128 v[194:197], v169 offset:17408
	ds_read_b128 v[198:201], v169 offset:18432
	ds_read_b128 v[202:205], v169 offset:19456
	ds_read_b128 v[206:209], v169 offset:20480
	ds_read_b128 v[210:213], v169 offset:21504
	ds_read_b128 v[214:217], v169 offset:22528
	ds_read_b128 v[218:221], v169 offset:23552
	global_load_lds_dwordx4 v136, s[60:61]
	s_mov_b64 s[100:101], s[60:61]
	s_mov_b32 m0, s98
	s_nop 0
	global_load_lds_dwordx4 v132, s[60:61]
	s_waitcnt vmcnt(8)
	s_barrier
	s_waitcnt lgkmcnt(0)
	s_setprio 1
	s_waitcnt lgkmcnt(0)
	v_mfma_f32_16x16x32_bf16 v[62:65], v[142:145], v[190:193], 0
	v_mfma_f32_16x16x32_bf16 v[62:65], v[162:165], v[194:197], v[62:65]
	v_mfma_f32_16x16x32_bf16 v[58:61], v[182:185], v[190:193], 0
	v_mfma_f32_16x16x32_bf16 v[58:61], v[186:189], v[194:197], v[58:61]
	v_mfma_f32_16x16x32_bf16 v[46:49], v[142:145], v[198:201], 0
	v_mfma_f32_16x16x32_bf16 v[46:49], v[162:165], v[202:205], v[46:49]
	v_mfma_f32_16x16x32_bf16 v[42:45], v[182:185], v[198:201], 0
	v_mfma_f32_16x16x32_bf16 v[42:45], v[186:189], v[202:205], v[42:45]
	v_mfma_f32_16x16x32_bf16 v[30:33], v[142:145], v[206:209], 0
	v_mfma_f32_16x16x32_bf16 v[30:33], v[162:165], v[210:213], v[30:33]
	v_mfma_f32_16x16x32_bf16 v[26:29], v[182:185], v[206:209], 0
	v_mfma_f32_16x16x32_bf16 v[26:29], v[186:189], v[210:213], v[26:29]
	v_mfma_f32_16x16x32_bf16 v[14:17], v[142:145], v[214:217], 0
	v_mfma_f32_16x16x32_bf16 v[14:17], v[162:165], v[218:221], v[14:17]
	v_mfma_f32_16x16x32_bf16 v[10:13], v[182:185], v[214:217], 0
	s_barrier
; #define PG8_STAGE(bufoff, gbase, voff) do { _Pragma("unroll") for (int _i = 0; _i < 2; ++_i) \
;         __builtin_amdgcn_global_load_lds((const unsigned*)((const char*)(gbase) + (voff)[_i]), (LAS unsigned*)(lds + (bufoff) + ldsw + _i * 8192), 16, 0, 0); } while (0)
; #define PG8_LDA(dst, b, h) do { _Pragma("unroll") for (int m = 0; m < 4; ++m) _Pragma("unroll") for (int k = 0; k < 2; ++k) dst[m][k] = *(const LAS bf16x8*)(lds + PG8_SA(b, h) + aoff + m * 2048 + k * 1024); } while (0)
; #define PG8_LDB(dst, b, h) do { _Pragma("unroll") for (int n = 0; n < 2; ++n) _Pragma("unroll") for (int k = 0; k < 2; ++k) dst[n][k] = *(const LAS bf16x8*)(lds + PG8_SB(b, h) + boff + n * 2048 + k * 1024); } while (0)
; #define PG8_MMA(ai, bj, At, Bt) do { __builtin_amdgcn_s_setprio(1); _Pragma("unroll") for (int m = 0; m < 4; ++m) _Pragma("unroll") for (int n = 0; n < 2; ++n) _Pragma("unroll") for (int k = 0; k < 2; ++k) \
;         acc[ai][bj][m][n] = __builtin_amdgcn_mfma_f32_16x16x32_bf16(Bt[n][k], At[m][k], acc[ai][bj][m][n], 0, 0, 0); __builtin_amdgcn_s_setprio(0); } while (0)
; #define PG8_WAIT_V(n) asm volatile("s_waitcnt vmcnt(" #n ")" ::: "memory")
; #define PG8_WAIT_L(n) asm volatile("s_waitcnt lgkmcnt(" #n ")" ::: "memory")
; #define PG8_BAR __builtin_amdgcn_s_barrier()
; #define PG8_SCHED __builtin_amdgcn_sched_barrier(0)
; template <class Epi, class Sched>
; __device__ __forceinline__ void gemm_phase(LAS unsigned char* lds, const Gemm g, const Sched& S, const Epi& E) {
;     ...
;             PG8_BAR; PG8_WAIT_L(0); PG8_MMA(1, 0, At, B0); PG8_BAR; PG8_SCHED;
;             PG8_STAGE(PG8_SB(0, 1), b2 + hstep, voffB);
;             PG8_WAIT_V(6); PG8_BAR; PG8_MMA(1, 1, At, B1); PG8_BAR;
;             PG8_LDB(B0, 1, 0); PG8_SCHED; PG8_LDA(At, 1, 0); PG8_STAGE(PG8_SA(0, 1), a2 + hstep, voffA);
;             PG8_WAIT_L(8); PG8_BAR; PG8_WAIT_L(0); PG8_MMA(0, 0, At, B0); PG8_BAR; PG8_SCHED;
;             PG8_LDB(B1, 1, 1); PG8_STAGE(PG8_SB(1, 0), b3, voffB);
;             PG8_BAR; PG8_WAIT_L(0); PG8_MMA(0, 1, At, B1); PG8_BAR;
;             PG8_LDA(At, 1, 1); PG8_STAGE(PG8_SA(1, 0), a3, voffA);
	v_mfma_f32_16x16x32_bf16 v[10:13], v[186:189], v[218:221], v[10:13]
	s_setprio 0
	s_add_u32 s24, s48, 0x40000
	s_addc_u32 s25, s49, 0
	s_add_i32 s51, s51, s86
	s_mov_b32 m0, s51
	s_nop 0
	global_load_lds_dwordx4 v134, s[24:25]
	s_add_i32 m0, s51, 0x2000
	s_nop 0
	global_load_lds_dwordx4 v130, s[24:25]
	s_waitcnt vmcnt(6)
	s_barrier
	s_setprio 1
	v_mfma_f32_16x16x32_bf16 v[54:57], v[222:225], v[190:193], 0
	ds_read_b128 v[142:145], v249 offset:32768
	ds_read_b128 v[162:165], v249 offset:33792
	v_mfma_f32_16x16x32_bf16 v[54:57], v[226:229], v[194:197], v[54:57]
	ds_read_b128 v[182:185], v249 offset:34816
	ds_read_b128 v[186:189], v249 offset:35840
	v_mfma_f32_16x16x32_bf16 v[50:53], v[230:233], v[190:193], 0
	ds_read_b128 v[190:193], v169 offset:32768
	v_mfma_f32_16x16x32_bf16 v[50:53], v[234:237], v[194:197], v[50:53]
	ds_read_b128 v[194:197], v169 offset:33792
	v_mfma_f32_16x16x32_bf16 v[38:41], v[222:225], v[198:201], 0
	v_mfma_f32_16x16x32_bf16 v[38:41], v[226:229], v[202:205], v[38:41]
	v_mfma_f32_16x16x32_bf16 v[34:37], v[230:233], v[198:201], 0
	ds_read_b128 v[198:201], v169 offset:34816
	v_mfma_f32_16x16x32_bf16 v[34:37], v[234:237], v[202:205], v[34:37]
	ds_read_b128 v[202:205], v169 offset:35840
	v_mfma_f32_16x16x32_bf16 v[22:25], v[222:225], v[206:209], 0
	v_mfma_f32_16x16x32_bf16 v[22:25], v[226:229], v[210:213], v[22:25]
	v_mfma_f32_16x16x32_bf16 v[18:21], v[230:233], v[206:209], 0
	v_mfma_f32_16x16x32_bf16 v[18:21], v[234:237], v[210:213], v[18:21]
	v_mfma_f32_16x16x32_bf16 v[6:9], v[222:225], v[214:217], 0
	v_mfma_f32_16x16x32_bf16 v[6:9], v[226:229], v[218:221], v[6:9]
	v_mfma_f32_16x16x32_bf16 v[2:5], v[230:233], v[214:217], 0
	s_barrier
	v_mfma_f32_16x16x32_bf16 v[2:5], v[234:237], v[218:221], v[2:5]
	s_setprio 0
	s_add_i32 s51, 0, 0x18000
	s_add_u32 s24, s60, 0x40000
	s_addc_u32 s25, s61, 0
	s_mov_b32 m0, s99
	ds_read_b128 v[206:209], v169 offset:36864
	ds_read_b128 v[210:213], v169 offset:37888
	ds_read_b128 v[214:217], v169 offset:38912
	ds_read_b128 v[218:221], v169 offset:39936
	global_load_lds_dwordx4 v136, s[24:25]
	s_mov_b32 m0, s94
	s_nop 0
	global_load_lds_dwordx4 v132, s[24:25]
	s_waitcnt lgkmcnt(8)
	s_barrier
	s_waitcnt lgkmcnt(0)
	s_setprio 1
	s_waitcnt lgkmcnt(0)
	v_mfma_f32_16x16x32_bf16 v[126:129], v[142:145], v[190:193], v[126:129]
	v_mfma_f32_16x16x32_bf16 v[126:129], v[162:165], v[194:197], v[126:129]
	v_mfma_f32_16x16x32_bf16 v[122:125], v[182:185], v[190:193], v[122:125]
	v_mfma_f32_16x16x32_bf16 v[122:125], v[186:189], v[194:197], v[122:125]
	v_mfma_f32_16x16x32_bf16 v[110:113], v[142:145], v[198:201], v[110:113]
	v_mfma_f32_16x16x32_bf16 v[110:113], v[162:165], v[202:205], v[110:113]
	v_mfma_f32_16x16x32_bf16 v[106:109], v[182:185], v[198:201], v[106:109]
	v_mfma_f32_16x16x32_bf16 v[106:109], v[186:189], v[202:205], v[106:109]
	v_mfma_f32_16x16x32_bf16 v[94:97], v[142:145], v[206:209], v[94:97]
	v_mfma_f32_16x16x32_bf16 v[94:97], v[162:165], v[210:213], v[94:97]
	v_mfma_f32_16x16x32_bf16 v[90:93], v[182:185], v[206:209], v[90:93]
	v_mfma_f32_16x16x32_bf16 v[90:93], v[186:189], v[210:213], v[90:93]
	v_mfma_f32_16x16x32_bf16 v[78:81], v[142:145], v[214:217], v[78:81]
	v_mfma_f32_16x16x32_bf16 v[78:81], v[162:165], v[218:221], v[78:81]
	v_mfma_f32_16x16x32_bf16 v[74:77], v[182:185], v[214:217], v[74:77]
	s_barrier
	v_mfma_f32_16x16x32_bf16 v[74:77], v[186:189], v[218:221], v[74:77]
	s_setprio 0
	s_add_i32 s60, 0, 0x1c000
	s_add_i32 s24, s51, s86
	s_add_i32 m0, s24, 0xffffff80
	ds_read_b128 v[222:225], v249 offset:49152
	ds_read_b128 v[226:229], v249 offset:50176
	ds_read_b128 v[230:233], v249 offset:51200
	ds_read_b128 v[234:237], v249 offset:52224
	global_load_lds_dwordx4 v134, s[48:49] offset:128
	s_add_i32 m0, s24, 0x1f80
	s_nop 0
	global_load_lds_dwordx4 v130, s[48:49] offset:128
	s_barrier
	s_waitcnt lgkmcnt(0)
	s_setprio 1
	s_waitcnt lgkmcnt(0)
	v_mfma_f32_16x16x32_bf16 v[118:121], v[222:225], v[190:193], v[118:121]
	v_mfma_f32_16x16x32_bf16 v[118:121], v[226:229], v[194:197], v[118:121]
	v_mfma_f32_16x16x32_bf16 v[114:117], v[230:233], v[190:193], v[114:117]
	v_mfma_f32_16x16x32_bf16 v[114:117], v[234:237], v[194:197], v[114:117]
	v_mfma_f32_16x16x32_bf16 v[102:105], v[222:225], v[198:201], v[102:105]
	v_mfma_f32_16x16x32_bf16 v[102:105], v[226:229], v[202:205], v[102:105]
	v_mfma_f32_16x16x32_bf16 v[98:101], v[230:233], v[198:201], v[98:101]
	v_mfma_f32_16x16x32_bf16 v[98:101], v[234:237], v[202:205], v[98:101]
	v_mfma_f32_16x16x32_bf16 v[86:89], v[222:225], v[206:209], v[86:89]
	v_mfma_f32_16x16x32_bf16 v[86:89], v[226:229], v[210:213], v[86:89]
	v_mfma_f32_16x16x32_bf16 v[82:85], v[230:233], v[206:209], v[82:85]
	v_mfma_f32_16x16x32_bf16 v[82:85], v[234:237], v[210:213], v[82:85]
	v_mfma_f32_16x16x32_bf16 v[70:73], v[222:225], v[214:217], v[70:73]
	v_mfma_f32_16x16x32_bf16 v[70:73], v[226:229], v[218:221], v[70:73]
	v_mfma_f32_16x16x32_bf16 v[66:69], v[230:233], v[214:217], v[66:69]
	s_barrier
	v_mfma_f32_16x16x32_bf16 v[66:69], v[234:237], v[218:221], v[66:69]
	s_setprio 0
	s_add_i32 m0, s95, 0xffffff80
	ds_read_b128 v[190:193], v169 offset:49152
	ds_read_b128 v[194:197], v169 offset:50176
	ds_read_b128 v[198:201], v169 offset:51200
	ds_read_b128 v[202:205], v169 offset:52224
	ds_read_b128 v[206:209], v169 offset:53248
	ds_read_b128 v[210:213], v169 offset:54272
	ds_read_b128 v[214:217], v169 offset:55296
	ds_read_b128 v[218:221], v169 offset:56320
	global_load_lds_dwordx4 v136, s[100:101] offset:128
	s_add_i32 m0, s96, 0xffffff80
	s_nop 0
	global_load_lds_dwordx4 v132, s[100:101] offset:128
	s_waitcnt vmcnt(8)
	s_barrier
; #define PG8_STAGE(bufoff, gbase, voff) do { _Pragma("unroll") for (int _i = 0; _i < 2; ++_i) \
;         __builtin_amdgcn_global_load_lds((const unsigned*)((const char*)(gbase) + (voff)[_i]), (LAS unsigned*)(lds + (bufoff) + ldsw + _i * 8192), 16, 0, 0); } while (0)
; #define PG8_LDA(dst, b, h) do { _Pragma("unroll") for (int m = 0; m < 4; ++m) _Pragma("unroll") for (int k = 0; k < 2; ++k) dst[m][k] = *(const LAS bf16x8*)(lds + PG8_SA(b, h) + aoff + m * 2048 + k * 1024); } while (0)
; #define PG8_LDB(dst, b, h) do { _Pragma("unroll") for (int n = 0; n < 2; ++n) _Pragma("unroll") for (int k = 0; k < 2; ++k) dst[n][k] = *(const LAS bf16x8*)(lds + PG8_SB(b, h) + boff + n * 2048 + k * 1024); } while (0)
; #define PG8_WAIT_V(n) asm volatile("s_waitcnt vmcnt(" #n ")" ::: "memory")
; #define PG8_WAIT_L(n) asm volatile("s_waitcnt lgkmcnt(" #n ")" ::: "memory")
; #define PG8_BAR __builtin_amdgcn_s_barrier()
; #define PG8_SCHED __builtin_amdgcn_sched_barrier(0)
; template <class Epi, class Sched>
; __device__ __forceinline__ void gemm_phase(LAS unsigned char* lds, const Gemm g, const Sched& S, const Epi& E) {
;     ...
;             const bool last = (t == nt - 2);
;             const char* a1 = cA + (size_t)(t + 1) * kstep;
;             const char* a2 = last ? nA : cA + (size_t)(t + 2) * kstep; const char* b2 = last ? nB : cB + (size_t)(t + 2) * kstep;
;             const char* a3 = a2 + kstep; const char* b3 = b2 + kstep;
;             PG8_LDB(B0, 0, 0); PG8_SCHED; PG8_LDA(At, 0, 0); PG8_STAGE(PG8_SA(1, 1), a1 + hstep, voffA);
;             PG8_WAIT_L(8); PG8_BAR; PG8_WAIT_L(0); PG8_MMA(0, 0, At, B0); PG8_BAR; PG8_SCHED;
;             PG8_LDB(B1, 0, 1); PG8_STAGE(PG8_SB(0, 0), b2, voffB);
;     ...
;             PG8_LDB(B0, 1, 0); PG8_SCHED; PG8_LDA(At, 1, 0); PG8_STAGE(PG8_SA(0, 1), a2 + hstep, voffA);
;             PG8_WAIT_L(8); PG8_BAR; PG8_WAIT_L(0); PG8_MMA(0, 0, At, B0); PG8_BAR; PG8_SCHED;
;             PG8_LDB(B1, 1, 1); PG8_STAGE(PG8_SB(1, 0), b3, voffB);
;             PG8_BAR; PG8_WAIT_L(0); PG8_MMA(0, 1, At, B1); PG8_BAR;
;             PG8_LDA(At, 1, 1); PG8_STAGE(PG8_SA(1, 0), a3, voffA);
;             PG8_BAR; PG8_WAIT_L(0); PG8_MMA(1, 0, At, B0); PG8_BAR; PG8_SCHED;
;             PG8_STAGE(PG8_SB(1, 1), b3 + hstep, voffB);
;             PG8_WAIT_V(6); PG8_BAR; PG8_MMA(1, 1, At, B1); PG8_BAR;
	s_waitcnt lgkmcnt(0)
	s_setprio 1
	s_waitcnt lgkmcnt(0)
	v_mfma_f32_16x16x32_bf16 v[62:65], v[142:145], v[190:193], v[62:65]
	v_mfma_f32_16x16x32_bf16 v[62:65], v[162:165], v[194:197], v[62:65]
	v_mfma_f32_16x16x32_bf16 v[58:61], v[182:185], v[190:193], v[58:61]
	v_mfma_f32_16x16x32_bf16 v[58:61], v[186:189], v[194:197], v[58:61]
	v_mfma_f32_16x16x32_bf16 v[46:49], v[142:145], v[198:201], v[46:49]
	v_mfma_f32_16x16x32_bf16 v[46:49], v[162:165], v[202:205], v[46:49]
	v_mfma_f32_16x16x32_bf16 v[42:45], v[182:185], v[198:201], v[42:45]
	v_mfma_f32_16x16x32_bf16 v[42:45], v[186:189], v[202:205], v[42:45]
	v_mfma_f32_16x16x32_bf16 v[30:33], v[142:145], v[206:209], v[30:33]
	v_mfma_f32_16x16x32_bf16 v[30:33], v[162:165], v[210:213], v[30:33]
	v_mfma_f32_16x16x32_bf16 v[26:29], v[182:185], v[206:209], v[26:29]
	v_mfma_f32_16x16x32_bf16 v[26:29], v[186:189], v[210:213], v[26:29]
	v_mfma_f32_16x16x32_bf16 v[14:17], v[142:145], v[214:217], v[14:17]
	v_mfma_f32_16x16x32_bf16 v[14:17], v[162:165], v[218:221], v[14:17]
	v_mfma_f32_16x16x32_bf16 v[10:13], v[182:185], v[214:217], v[10:13]
	s_barrier
	v_mfma_f32_16x16x32_bf16 v[10:13], v[186:189], v[218:221], v[10:13]
	s_setprio 0
	s_add_u32 s24, s48, 0x40080
	s_addc_u32 s25, s49, 0
	s_add_i32 s48, s60, s86
	s_mov_b32 m0, s48
	s_nop 0
	global_load_lds_dwordx4 v134, s[24:25]
	s_add_i32 m0, s48, 0x2000
	s_nop 0
	global_load_lds_dwordx4 v130, s[24:25]
	s_waitcnt vmcnt(6)
	s_barrier
	s_setprio 1
	v_mfma_f32_16x16x32_bf16 v[54:57], v[222:225], v[190:193], v[54:57]
	ds_read_b128 v[142:145], v249
	ds_read_b128 v[162:165], v249 offset:1024
	v_mfma_f32_16x16x32_bf16 v[54:57], v[226:229], v[194:197], v[54:57]
	ds_read_b128 v[182:185], v249 offset:2048
	ds_read_b128 v[186:189], v249 offset:3072
	v_mfma_f32_16x16x32_bf16 v[50:53], v[230:233], v[190:193], v[50:53]
	ds_read_b128 v[190:193], v169
	v_mfma_f32_16x16x32_bf16 v[50:53], v[234:237], v[194:197], v[50:53]
	ds_read_b128 v[194:197], v169 offset:1024
	v_mfma_f32_16x16x32_bf16 v[38:41], v[222:225], v[198:201], v[38:41]
	v_mfma_f32_16x16x32_bf16 v[38:41], v[226:229], v[202:205], v[38:41]
	v_mfma_f32_16x16x32_bf16 v[34:37], v[230:233], v[198:201], v[34:37]
	ds_read_b128 v[198:201], v169 offset:2048
	v_mfma_f32_16x16x32_bf16 v[34:37], v[234:237], v[202:205], v[34:37]
	ds_read_b128 v[202:205], v169 offset:3072
	v_mfma_f32_16x16x32_bf16 v[22:25], v[222:225], v[206:209], v[22:25]
	v_mfma_f32_16x16x32_bf16 v[22:25], v[226:229], v[210:213], v[22:25]
	v_mfma_f32_16x16x32_bf16 v[18:21], v[230:233], v[206:209], v[18:21]
	v_mfma_f32_16x16x32_bf16 v[18:21], v[234:237], v[210:213], v[18:21]
	v_mfma_f32_16x16x32_bf16 v[6:9], v[222:225], v[214:217], v[6:9]
	v_mfma_f32_16x16x32_bf16 v[6:9], v[226:229], v[218:221], v[6:9]
	v_mfma_f32_16x16x32_bf16 v[2:5], v[230:233], v[214:217], v[2:5]
	s_barrier
	v_mfma_f32_16x16x32_bf16 v[2:5], v[234:237], v[218:221], v[2:5]
	s_setprio 0
	s_add_i32 s50, s50, 2
	s_add_u32 vcc_lo, vcc_lo, 0x100
	s_addc_u32 s35, s35, 0
	s_add_u32 s38, s38, 0x100
	s_addc_u32 s39, s39, 0
	s_cmp_gt_u32 s50, 13
.LBB0_165:
	s_add_u32 s24, s38, 0xfffc0080
	s_addc_u32 s25, s39, -1
	s_add_i32 vcc_hi, 0, 0x10000
	s_cmp_eq_u32 s50, 12
	s_cselect_b32 s61, s34, s25
	s_cselect_b32 s60, s45, s24
	s_cselect_b32 s49, s43, s35
	s_cselect_b32 s48, s79, vcc_lo
	s_add_i32 m0, s93, 0xc000
	ds_read_b128 v[206:209], v169 offset:4096
	ds_read_b128 v[210:213], v169 offset:5120
	ds_read_b128 v[214:217], v169 offset:6144
	ds_read_b128 v[218:221], v169 offset:7168
	global_load_lds_dwordx4 v140, s[38:39]
	s_add_i32 m0, s93, 0xe000
	s_nop 0
	global_load_lds_dwordx4 v138, s[38:39]
	s_waitcnt lgkmcnt(8)
	s_barrier
	s_waitcnt lgkmcnt(0)
	s_setprio 1
	s_waitcnt lgkmcnt(0)
	v_mfma_f32_16x16x32_bf16 v[126:129], v[142:145], v[190:193], v[126:129]
	v_mfma_f32_16x16x32_bf16 v[126:129], v[162:165], v[194:197], v[126:129]
	v_mfma_f32_16x16x32_bf16 v[122:125], v[182:185], v[190:193], v[122:125]
	v_mfma_f32_16x16x32_bf16 v[122:125], v[186:189], v[194:197], v[122:125]
	v_mfma_f32_16x16x32_bf16 v[110:113], v[142:145], v[198:201], v[110:113]
	v_mfma_f32_16x16x32_bf16 v[110:113], v[162:165], v[202:205], v[110:113]
	v_mfma_f32_16x16x32_bf16 v[106:109], v[182:185], v[198:201], v[106:109]
	v_mfma_f32_16x16x32_bf16 v[106:109], v[186:189], v[202:205], v[106:109]
	v_mfma_f32_16x16x32_bf16 v[94:97], v[142:145], v[206:209], v[94:97]
	v_mfma_f32_16x16x32_bf16 v[94:97], v[162:165], v[210:213], v[94:97]
	v_mfma_f32_16x16x32_bf16 v[90:93], v[182:185], v[206:209], v[90:93]
	v_mfma_f32_16x16x32_bf16 v[90:93], v[186:189], v[210:213], v[90:93]
	v_mfma_f32_16x16x32_bf16 v[78:81], v[142:145], v[214:217], v[78:81]
	v_mfma_f32_16x16x32_bf16 v[78:81], v[162:165], v[218:221], v[78:81]
	v_mfma_f32_16x16x32_bf16 v[74:77], v[182:185], v[214:217], v[74:77]
	s_barrier
	v_mfma_f32_16x16x32_bf16 v[74:77], v[186:189], v[218:221], v[74:77]
	s_setprio 0
	s_add_i32 s51, 0, 0x14000
	s_add_i32 s24, vcc_hi, s86
	s_mov_b32 m0, s24
	ds_read_b128 v[222:225], v249 offset:16384
	ds_read_b128 v[226:229], v249 offset:17408
	ds_read_b128 v[230:233], v249 offset:18432
	ds_read_b128 v[234:237], v249 offset:19456
	global_load_lds_dwordx4 v134, s[48:49]
	s_add_i32 m0, s24, 0x2000
	s_nop 0
	global_load_lds_dwordx4 v130, s[48:49]
	s_barrier
; #define PG8_STAGE(bufoff, gbase, voff) do { _Pragma("unroll") for (int _i = 0; _i < 2; ++_i) \
;         __builtin_amdgcn_global_load_lds((const unsigned*)((const char*)(gbase) + (voff)[_i]), (LAS unsigned*)(lds + (bufoff) + ldsw + _i * 8192), 16, 0, 0); } while (0)
; #define PG8_LDA(dst, b, h) do { _Pragma("unroll") for (int m = 0; m < 4; ++m) _Pragma("unroll") for (int k = 0; k < 2; ++k) dst[m][k] = *(const LAS bf16x8*)(lds + PG8_SA(b, h) + aoff + m * 2048 + k * 1024); } while (0)
; #define PG8_LDB(dst, b, h) do { _Pragma("unroll") for (int n = 0; n < 2; ++n) _Pragma("unroll") for (int k = 0; k < 2; ++k) dst[n][k] = *(const LAS bf16x8*)(lds + PG8_SB(b, h) + boff + n * 2048 + k * 1024); } while (0)
; #define PG8_MMA(ai, bj, At, Bt) do { __builtin_amdgcn_s_setprio(1); _Pragma("unroll") for (int m = 0; m < 4; ++m) _Pragma("unroll") for (int n = 0; n < 2; ++n) _Pragma("unroll") for (int k = 0; k < 2; ++k) \
;         acc[ai][bj][m][n] = __builtin_amdgcn_mfma_f32_16x16x32_bf16(Bt[n][k], At[m][k], acc[ai][bj][m][n], 0, 0, 0); __builtin_amdgcn_s_setprio(0); } while (0)
; #define PG8_WAIT_V(n) asm volatile("s_waitcnt vmcnt(" #n ")" ::: "memory")
; #define PG8_WAIT_L(n) asm volatile("s_waitcnt lgkmcnt(" #n ")" ::: "memory")
; #define PG8_BAR __builtin_amdgcn_s_barrier()
; #define PG8_SCHED __builtin_amdgcn_sched_barrier(0)
; template <class Epi, class Sched>
; __device__ __forceinline__ void gemm_phase(LAS unsigned char* lds, const Gemm g, const Sched& S, const Epi& E) {
;     ...
;             PG8_BAR; PG8_WAIT_L(0); PG8_MMA(0, 1, At, B1); PG8_BAR;
;             PG8_LDA(At, 0, 1); PG8_STAGE(PG8_SA(0, 0), a2, voffA);
;             PG8_BAR; PG8_WAIT_L(0); PG8_MMA(1, 0, At, B0); PG8_BAR; PG8_SCHED;
;             PG8_STAGE(PG8_SB(0, 1), b2 + hstep, voffB);
;             PG8_WAIT_V(6); PG8_BAR; PG8_MMA(1, 1, At, B1); PG8_BAR;
;             PG8_LDB(B0, 1, 0); PG8_SCHED; PG8_LDA(At, 1, 0); PG8_STAGE(PG8_SA(0, 1), a2 + hstep, voffA);
;             PG8_WAIT_L(8); PG8_BAR; PG8_WAIT_L(0); PG8_MMA(0, 0, At, B0); PG8_BAR; PG8_SCHED;
	s_waitcnt lgkmcnt(0)
	s_setprio 1
	s_waitcnt lgkmcnt(0)
	v_mfma_f32_16x16x32_bf16 v[118:121], v[222:225], v[190:193], v[118:121]
	v_mfma_f32_16x16x32_bf16 v[118:121], v[226:229], v[194:197], v[118:121]
	v_mfma_f32_16x16x32_bf16 v[114:117], v[230:233], v[190:193], v[114:117]
	v_mfma_f32_16x16x32_bf16 v[114:117], v[234:237], v[194:197], v[114:117]
	v_mfma_f32_16x16x32_bf16 v[102:105], v[222:225], v[198:201], v[102:105]
	v_mfma_f32_16x16x32_bf16 v[102:105], v[226:229], v[202:205], v[102:105]
	v_mfma_f32_16x16x32_bf16 v[98:101], v[230:233], v[198:201], v[98:101]
	v_mfma_f32_16x16x32_bf16 v[98:101], v[234:237], v[202:205], v[98:101]
	v_mfma_f32_16x16x32_bf16 v[86:89], v[222:225], v[206:209], v[86:89]
	v_mfma_f32_16x16x32_bf16 v[86:89], v[226:229], v[210:213], v[86:89]
	v_mfma_f32_16x16x32_bf16 v[82:85], v[230:233], v[206:209], v[82:85]
	v_mfma_f32_16x16x32_bf16 v[82:85], v[234:237], v[210:213], v[82:85]
	v_mfma_f32_16x16x32_bf16 v[70:73], v[222:225], v[214:217], v[70:73]
	v_mfma_f32_16x16x32_bf16 v[70:73], v[226:229], v[218:221], v[70:73]
	v_mfma_f32_16x16x32_bf16 v[66:69], v[230:233], v[214:217], v[66:69]
	s_barrier
	v_mfma_f32_16x16x32_bf16 v[66:69], v[234:237], v[218:221], v[66:69]
	s_setprio 0
	s_mov_b32 m0, s93
	s_mov_b64 s[100:101], s[60:61]
	ds_read_b128 v[190:193], v169 offset:16384
	ds_read_b128 v[194:197], v169 offset:17408
	ds_read_b128 v[198:201], v169 offset:18432
	ds_read_b128 v[202:205], v169 offset:19456
	ds_read_b128 v[206:209], v169 offset:20480
	ds_read_b128 v[210:213], v169 offset:21504
	ds_read_b128 v[214:217], v169 offset:22528
	ds_read_b128 v[218:221], v169 offset:23552
	global_load_lds_dwordx4 v136, s[60:61]
	s_mov_b64 s[100:101], s[60:61]
	s_mov_b32 m0, s98
	s_nop 0
	global_load_lds_dwordx4 v132, s[60:61]
	s_waitcnt vmcnt(8)
	s_barrier
	s_waitcnt lgkmcnt(0)
	s_setprio 1
	s_waitcnt lgkmcnt(0)
	v_mfma_f32_16x16x32_bf16 v[62:65], v[142:145], v[190:193], v[62:65]
	v_mfma_f32_16x16x32_bf16 v[62:65], v[162:165], v[194:197], v[62:65]
	v_mfma_f32_16x16x32_bf16 v[58:61], v[182:185], v[190:193], v[58:61]
	v_mfma_f32_16x16x32_bf16 v[58:61], v[186:189], v[194:197], v[58:61]
	v_mfma_f32_16x16x32_bf16 v[46:49], v[142:145], v[198:201], v[46:49]
	v_mfma_f32_16x16x32_bf16 v[46:49], v[162:165], v[202:205], v[46:49]
	v_mfma_f32_16x16x32_bf16 v[42:45], v[182:185], v[198:201], v[42:45]
	v_mfma_f32_16x16x32_bf16 v[42:45], v[186:189], v[202:205], v[42:45]
	v_mfma_f32_16x16x32_bf16 v[30:33], v[142:145], v[206:209], v[30:33]
	v_mfma_f32_16x16x32_bf16 v[30:33], v[162:165], v[210:213], v[30:33]
	v_mfma_f32_16x16x32_bf16 v[26:29], v[182:185], v[206:209], v[26:29]
	v_mfma_f32_16x16x32_bf16 v[26:29], v[186:189], v[210:213], v[26:29]
	v_mfma_f32_16x16x32_bf16 v[14:17], v[142:145], v[214:217], v[14:17]
	v_mfma_f32_16x16x32_bf16 v[14:17], v[162:165], v[218:221], v[14:17]
	v_mfma_f32_16x16x32_bf16 v[10:13], v[182:185], v[214:217], v[10:13]
	s_barrier
	v_mfma_f32_16x16x32_bf16 v[10:13], v[186:189], v[218:221], v[10:13]
	s_setprio 0
	s_add_u32 s24, s48, 0x40000
	s_addc_u32 s25, s49, 0
	s_add_i32 s51, s51, s86
	s_mov_b32 m0, s51
	s_nop 0
	global_load_lds_dwordx4 v134, s[24:25]
	s_add_i32 m0, s51, 0x2000
	s_nop 0
	global_load_lds_dwordx4 v130, s[24:25]
	s_waitcnt vmcnt(6)
	s_barrier
	s_setprio 1
	v_mfma_f32_16x16x32_bf16 v[54:57], v[222:225], v[190:193], v[54:57]
	ds_read_b128 v[142:145], v249 offset:32768
	ds_read_b128 v[162:165], v249 offset:33792
	v_mfma_f32_16x16x32_bf16 v[54:57], v[226:229], v[194:197], v[54:57]
	ds_read_b128 v[182:185], v249 offset:34816
	ds_read_b128 v[186:189], v249 offset:35840
	v_mfma_f32_16x16x32_bf16 v[50:53], v[230:233], v[190:193], v[50:53]
	ds_read_b128 v[190:193], v169 offset:32768
	v_mfma_f32_16x16x32_bf16 v[50:53], v[234:237], v[194:197], v[50:53]
	ds_read_b128 v[194:197], v169 offset:33792
	v_mfma_f32_16x16x32_bf16 v[38:41], v[222:225], v[198:201], v[38:41]
	v_mfma_f32_16x16x32_bf16 v[38:41], v[226:229], v[202:205], v[38:41]
	v_mfma_f32_16x16x32_bf16 v[34:37], v[230:233], v[198:201], v[34:37]
	ds_read_b128 v[198:201], v169 offset:34816
	v_mfma_f32_16x16x32_bf16 v[34:37], v[234:237], v[202:205], v[34:37]
	ds_read_b128 v[202:205], v169 offset:35840
	v_mfma_f32_16x16x32_bf16 v[22:25], v[222:225], v[206:209], v[22:25]
	v_mfma_f32_16x16x32_bf16 v[22:25], v[226:229], v[210:213], v[22:25]
	v_mfma_f32_16x16x32_bf16 v[18:21], v[230:233], v[206:209], v[18:21]
	v_mfma_f32_16x16x32_bf16 v[18:21], v[234:237], v[210:213], v[18:21]
	v_mfma_f32_16x16x32_bf16 v[6:9], v[222:225], v[214:217], v[6:9]
	v_mfma_f32_16x16x32_bf16 v[6:9], v[226:229], v[218:221], v[6:9]
	v_mfma_f32_16x16x32_bf16 v[2:5], v[230:233], v[214:217], v[2:5]
	s_barrier
	v_mfma_f32_16x16x32_bf16 v[2:5], v[234:237], v[218:221], v[2:5]
	s_setprio 0
	s_add_i32 s51, 0, 0x18000
	s_add_u32 s24, s60, 0x40000
	s_addc_u32 s25, s61, 0
	s_mov_b32 m0, s99
	ds_read_b128 v[206:209], v169 offset:36864
	ds_read_b128 v[210:213], v169 offset:37888
	ds_read_b128 v[214:217], v169 offset:38912
	ds_read_b128 v[218:221], v169 offset:39936
	global_load_lds_dwordx4 v136, s[24:25]
	s_mov_b32 m0, s94
	s_nop 0
	global_load_lds_dwordx4 v132, s[24:25]
	s_waitcnt lgkmcnt(8)
	s_barrier
; #define PG8_STAGE(bufoff, gbase, voff) do { _Pragma("unroll") for (int _i = 0; _i < 2; ++_i) \
;         __builtin_amdgcn_global_load_lds((const unsigned*)((const char*)(gbase) + (voff)[_i]), (LAS unsigned*)(lds + (bufoff) + ldsw + _i * 8192), 16, 0, 0); } while (0)
; #define PG8_LDA(dst, b, h) do { _Pragma("unroll") for (int m = 0; m < 4; ++m) _Pragma("unroll") for (int k = 0; k < 2; ++k) dst[m][k] = *(const LAS bf16x8*)(lds + PG8_SA(b, h) + aoff + m * 2048 + k * 1024); } while (0)
; #define PG8_LDB(dst, b, h) do { _Pragma("unroll") for (int n = 0; n < 2; ++n) _Pragma("unroll") for (int k = 0; k < 2; ++k) dst[n][k] = *(const LAS bf16x8*)(lds + PG8_SB(b, h) + boff + n * 2048 + k * 1024); } while (0)
; #define PG8_MMA(ai, bj, At, Bt) do { __builtin_amdgcn_s_setprio(1); _Pragma("unroll") for (int m = 0; m < 4; ++m) _Pragma("unroll") for (int n = 0; n < 2; ++n) _Pragma("unroll") for (int k = 0; k < 2; ++k) \
;         acc[ai][bj][m][n] = __builtin_amdgcn_mfma_f32_16x16x32_bf16(Bt[n][k], At[m][k], acc[ai][bj][m][n], 0, 0, 0); __builtin_amdgcn_s_setprio(0); } while (0)
; #define PG8_WAIT_V(n) asm volatile("s_waitcnt vmcnt(" #n ")" ::: "memory")
; #define PG8_WAIT_L(n) asm volatile("s_waitcnt lgkmcnt(" #n ")" ::: "memory")
; #define PG8_BAR __builtin_amdgcn_s_barrier()
; #define PG8_SCHED __builtin_amdgcn_sched_barrier(0)
; template <class Epi, class Sched>
; __device__ __forceinline__ void gemm_phase(LAS unsigned char* lds, const Gemm g, const Sched& S, const Epi& E) {
;     ...
;             PG8_WAIT_L(8); PG8_BAR; PG8_WAIT_L(0); PG8_MMA(0, 0, At, B0); PG8_BAR; PG8_SCHED;
;             PG8_LDB(B1, 1, 1); PG8_STAGE(PG8_SB(1, 0), b3, voffB);
;             PG8_BAR; PG8_WAIT_L(0); PG8_MMA(0, 1, At, B1); PG8_BAR;
;             PG8_LDA(At, 1, 1); PG8_STAGE(PG8_SA(1, 0), a3, voffA);
;             PG8_BAR; PG8_WAIT_L(0); PG8_MMA(1, 0, At, B0); PG8_BAR; PG8_SCHED;
;             PG8_STAGE(PG8_SB(1, 1), b3 + hstep, voffB);
;             PG8_WAIT_V(6); PG8_BAR; PG8_MMA(1, 1, At, B1); PG8_BAR;
;         }
;         if (wr == 0) PG8_BAR;
	s_waitcnt lgkmcnt(0)
	s_setprio 1
	s_waitcnt lgkmcnt(0)
	v_mfma_f32_16x16x32_bf16 v[126:129], v[142:145], v[190:193], v[126:129]
	v_mfma_f32_16x16x32_bf16 v[126:129], v[162:165], v[194:197], v[126:129]
	v_mfma_f32_16x16x32_bf16 v[122:125], v[182:185], v[190:193], v[122:125]
	v_mfma_f32_16x16x32_bf16 v[122:125], v[186:189], v[194:197], v[122:125]
	v_mfma_f32_16x16x32_bf16 v[110:113], v[142:145], v[198:201], v[110:113]
	v_mfma_f32_16x16x32_bf16 v[110:113], v[162:165], v[202:205], v[110:113]
	v_mfma_f32_16x16x32_bf16 v[106:109], v[182:185], v[198:201], v[106:109]
	v_mfma_f32_16x16x32_bf16 v[106:109], v[186:189], v[202:205], v[106:109]
	v_mfma_f32_16x16x32_bf16 v[94:97], v[142:145], v[206:209], v[94:97]
	v_mfma_f32_16x16x32_bf16 v[94:97], v[162:165], v[210:213], v[94:97]
	v_mfma_f32_16x16x32_bf16 v[90:93], v[182:185], v[206:209], v[90:93]
	v_mfma_f32_16x16x32_bf16 v[90:93], v[186:189], v[210:213], v[90:93]
	v_mfma_f32_16x16x32_bf16 v[78:81], v[142:145], v[214:217], v[78:81]
	v_mfma_f32_16x16x32_bf16 v[78:81], v[162:165], v[218:221], v[78:81]
	v_mfma_f32_16x16x32_bf16 v[74:77], v[182:185], v[214:217], v[74:77]
	s_barrier
	v_mfma_f32_16x16x32_bf16 v[74:77], v[186:189], v[218:221], v[74:77]
	s_setprio 0
	s_add_i32 s60, 0, 0x1c000
	s_add_i32 s24, s51, s86
	s_add_i32 m0, s24, 0xffffff80
	ds_read_b128 v[222:225], v249 offset:49152
	ds_read_b128 v[226:229], v249 offset:50176
	ds_read_b128 v[230:233], v249 offset:51200
	ds_read_b128 v[234:237], v249 offset:52224
	global_load_lds_dwordx4 v134, s[48:49] offset:128
	s_add_i32 m0, s24, 0x1f80
	s_nop 0
	global_load_lds_dwordx4 v130, s[48:49] offset:128
	s_barrier
	s_waitcnt lgkmcnt(0)
	s_setprio 1
	s_waitcnt lgkmcnt(0)
	v_mfma_f32_16x16x32_bf16 v[118:121], v[222:225], v[190:193], v[118:121]
	v_mfma_f32_16x16x32_bf16 v[118:121], v[226:229], v[194:197], v[118:121]
	v_mfma_f32_16x16x32_bf16 v[114:117], v[230:233], v[190:193], v[114:117]
	v_mfma_f32_16x16x32_bf16 v[114:117], v[234:237], v[194:197], v[114:117]
	v_mfma_f32_16x16x32_bf16 v[102:105], v[222:225], v[198:201], v[102:105]
	v_mfma_f32_16x16x32_bf16 v[102:105], v[226:229], v[202:205], v[102:105]
	v_mfma_f32_16x16x32_bf16 v[98:101], v[230:233], v[198:201], v[98:101]
	v_mfma_f32_16x16x32_bf16 v[98:101], v[234:237], v[202:205], v[98:101]
	v_mfma_f32_16x16x32_bf16 v[86:89], v[222:225], v[206:209], v[86:89]
	v_mfma_f32_16x16x32_bf16 v[86:89], v[226:229], v[210:213], v[86:89]
	v_mfma_f32_16x16x32_bf16 v[82:85], v[230:233], v[206:209], v[82:85]
	v_mfma_f32_16x16x32_bf16 v[82:85], v[234:237], v[210:213], v[82:85]
	v_mfma_f32_16x16x32_bf16 v[70:73], v[222:225], v[214:217], v[70:73]
	v_mfma_f32_16x16x32_bf16 v[70:73], v[226:229], v[218:221], v[70:73]
	v_mfma_f32_16x16x32_bf16 v[66:69], v[230:233], v[214:217], v[66:69]
	s_barrier
	v_mfma_f32_16x16x32_bf16 v[66:69], v[234:237], v[218:221], v[66:69]
	s_setprio 0
	s_add_i32 m0, s95, 0xffffff80
	ds_read_b128 v[190:193], v169 offset:49152
	ds_read_b128 v[194:197], v169 offset:50176
	ds_read_b128 v[198:201], v169 offset:51200
	ds_read_b128 v[202:205], v169 offset:52224
	ds_read_b128 v[206:209], v169 offset:53248
	ds_read_b128 v[210:213], v169 offset:54272
	ds_read_b128 v[214:217], v169 offset:55296
	ds_read_b128 v[218:221], v169 offset:56320
	global_load_lds_dwordx4 v136, s[100:101] offset:128
	s_add_i32 m0, s96, 0xffffff80
	s_nop 0
	global_load_lds_dwordx4 v132, s[100:101] offset:128
	s_waitcnt vmcnt(8)
	s_barrier
	s_waitcnt lgkmcnt(0)
	s_setprio 1
	s_waitcnt lgkmcnt(0)
	v_mfma_f32_16x16x32_bf16 v[62:65], v[142:145], v[190:193], v[62:65]
	v_mfma_f32_16x16x32_bf16 v[62:65], v[162:165], v[194:197], v[62:65]
	v_mfma_f32_16x16x32_bf16 v[58:61], v[182:185], v[190:193], v[58:61]
	v_mfma_f32_16x16x32_bf16 v[58:61], v[186:189], v[194:197], v[58:61]
	v_mfma_f32_16x16x32_bf16 v[46:49], v[142:145], v[198:201], v[46:49]
	v_mfma_f32_16x16x32_bf16 v[46:49], v[162:165], v[202:205], v[46:49]
	v_mfma_f32_16x16x32_bf16 v[42:45], v[182:185], v[198:201], v[42:45]
	v_mfma_f32_16x16x32_bf16 v[42:45], v[186:189], v[202:205], v[42:45]
	v_mfma_f32_16x16x32_bf16 v[30:33], v[142:145], v[206:209], v[30:33]
	v_mfma_f32_16x16x32_bf16 v[30:33], v[162:165], v[210:213], v[30:33]
	v_mfma_f32_16x16x32_bf16 v[26:29], v[182:185], v[206:209], v[26:29]
	v_mfma_f32_16x16x32_bf16 v[26:29], v[186:189], v[210:213], v[26:29]
	v_mfma_f32_16x16x32_bf16 v[14:17], v[142:145], v[214:217], v[14:17]
	v_mfma_f32_16x16x32_bf16 v[14:17], v[162:165], v[218:221], v[14:17]
	v_mfma_f32_16x16x32_bf16 v[10:13], v[182:185], v[214:217], v[10:13]
	s_barrier
	v_mfma_f32_16x16x32_bf16 v[10:13], v[186:189], v[218:221], v[10:13]
	s_setprio 0
	s_add_u32 s24, s48, 0x40080
	s_addc_u32 s25, s49, 0
	s_add_i32 s48, s60, s86
	s_mov_b32 m0, s48
	s_nop 0
	global_load_lds_dwordx4 v134, s[24:25]
	s_add_i32 m0, s48, 0x2000
	s_nop 0
	global_load_lds_dwordx4 v130, s[24:25]
	s_waitcnt vmcnt(6)
	s_barrier
	s_setprio 1
	v_mfma_f32_16x16x32_bf16 v[54:57], v[222:225], v[190:193], v[54:57]
	ds_read_b128 v[142:145], v249
	ds_read_b128 v[162:165], v249 offset:1024
	v_mfma_f32_16x16x32_bf16 v[54:57], v[226:229], v[194:197], v[54:57]
	ds_read_b128 v[182:185], v249 offset:2048
	ds_read_b128 v[186:189], v249 offset:3072
	v_mfma_f32_16x16x32_bf16 v[50:53], v[230:233], v[190:193], v[50:53]
	ds_read_b128 v[190:193], v169
	v_mfma_f32_16x16x32_bf16 v[50:53], v[234:237], v[194:197], v[50:53]
	ds_read_b128 v[194:197], v169 offset:1024
	v_mfma_f32_16x16x32_bf16 v[38:41], v[222:225], v[198:201], v[38:41]
	v_mfma_f32_16x16x32_bf16 v[38:41], v[226:229], v[202:205], v[38:41]
	v_mfma_f32_16x16x32_bf16 v[34:37], v[230:233], v[198:201], v[34:37]
	ds_read_b128 v[198:201], v169 offset:2048
	v_mfma_f32_16x16x32_bf16 v[34:37], v[234:237], v[202:205], v[34:37]
	ds_read_b128 v[202:205], v169 offset:3072
	v_mfma_f32_16x16x32_bf16 v[22:25], v[222:225], v[206:209], v[22:25]
	v_mfma_f32_16x16x32_bf16 v[22:25], v[226:229], v[210:213], v[22:25]
	v_mfma_f32_16x16x32_bf16 v[18:21], v[230:233], v[206:209], v[18:21]
	v_mfma_f32_16x16x32_bf16 v[18:21], v[234:237], v[210:213], v[18:21]
	v_mfma_f32_16x16x32_bf16 v[6:9], v[222:225], v[214:217], v[6:9]
	v_mfma_f32_16x16x32_bf16 v[6:9], v[226:229], v[218:221], v[6:9]
	v_mfma_f32_16x16x32_bf16 v[2:5], v[230:233], v[214:217], v[2:5]
	s_barrier
	v_mfma_f32_16x16x32_bf16 v[2:5], v[234:237], v[218:221], v[2:5]
	s_setprio 0
	s_add_i32 s50, s50, 2
	s_add_u32 vcc_lo, vcc_lo, 0x100
	s_addc_u32 s35, s35, 0
	s_add_u32 s38, s38, 0x100
	s_addc_u32 s39, s39, 0
	s_cmp_gt_u32 s50, 13
	s_cbranch_scc0 .LBB0_165
	s_waitcnt lgkmcnt(0)
	s_and_b64 vcc, exec, s[40:41]
	s_cbranch_vccz .LBB0_168
	s_barrier

; #define PG8_STAGE(bufoff, gbase, voff) do { _Pragma("unroll") for (int _i = 0; _i < 2; ++_i) \
;         __builtin_amdgcn_global_load_lds((const unsigned*)((const char*)(gbase) + (voff)[_i]), (LAS unsigned*)(lds + (bufoff) + ldsw + _i * 8192), 16, 0, 0); } while (0)
; #define PG8_LDA(dst, b, h) do { _Pragma("unroll") for (int m = 0; m < 4; ++m) _Pragma("unroll") for (int k = 0; k < 2; ++k) dst[m][k] = *(const LAS bf16x8*)(lds + PG8_SA(b, h) + aoff + m * 2048 + k * 1024); } while (0)
; #define PG8_LDB(dst, b, h) do { _Pragma("unroll") for (int n = 0; n < 2; ++n) _Pragma("unroll") for (int k = 0; k < 2; ++k) dst[n][k] = *(const LAS bf16x8*)(lds + PG8_SB(b, h) + boff + n * 2048 + k * 1024); } while (0)
; #define PG8_MMA(ai, bj, At, Bt) do { __builtin_amdgcn_s_setprio(1); _Pragma("unroll") for (int m = 0; m < 4; ++m) _Pragma("unroll") for (int n = 0; n < 2; ++n) _Pragma("unroll") for (int k = 0; k < 2; ++k) \
;         acc[ai][bj][m][n] = __builtin_amdgcn_mfma_f32_16x16x32_bf16(Bt[n][k], At[m][k], acc[ai][bj][m][n], 0, 0, 0); __builtin_amdgcn_s_setprio(0); } while (0)
; #define PG8_WAIT_L(n) asm volatile("s_waitcnt lgkmcnt(" #n ")" ::: "memory")
; template <class Epi, class Sched>
; __device__ __forceinline__ void gemm_phase(LAS unsigned char* lds, const Gemm g, const Sched& S, const Epi& E) {
;     ...
;         const bool has_next = S.next(ui + 1, nxt);
;         const char* nA = has_next ? PG8_APANEL(nxt.pm) : cA; const char* nB = has_next ? (const char*)g.Bt + (size_t)nxt.pn * tstep : cB;
;         for (int t = 0; t < nt; t += 2) {
;             const bool last = (t == nt - 2);
;             const char* a1 = cA + (size_t)(t + 1) * kstep;
;             const char* a2 = last ? nA : cA + (size_t)(t + 2) * kstep; const char* b2 = last ? nB : cB + (size_t)(t + 2) * kstep;
;             const char* a3 = a2 + kstep; const char* b3 = b2 + kstep;
;             PG8_LDB(B0, 0, 0); PG8_SCHED; PG8_LDA(At, 0, 0); PG8_STAGE(PG8_SA(1, 1), a1 + hstep, voffA);
;             PG8_WAIT_L(8); PG8_BAR; PG8_WAIT_L(0); PG8_MMA(0, 0, At, B0); PG8_BAR; PG8_SCHED;
;             PG8_LDB(B1, 0, 1); PG8_STAGE(PG8_SB(0, 0), b2, voffB);
;             PG8_BAR; PG8_WAIT_L(0); PG8_MMA(0, 1, At, B1); PG8_BAR;
;             PG8_LDA(At, 0, 1); PG8_STAGE(PG8_SA(0, 0), a2, voffA);
;             PG8_BAR; PG8_WAIT_L(0); PG8_MMA(1, 0, At, B0); PG8_BAR; PG8_SCHED;
.LBB0_415:
	s_ashr_i32 s47, s46, 31
	s_lshl_b64 s[24:25], s[46:47], 19
	s_add_u32 s48, s82, s24
	s_addc_u32 s49, s83, s25
	s_and_b64 s[0:1], s[0:1], exec
	s_cselect_b32 s47, s49, s37
	s_cselect_b32 s61, s48, s36
	s_add_u32 s35, s36, 0x100
	s_addc_u32 s50, s37, 0
	s_add_u32 s0, s38, 0x40080
	s_addc_u32 s1, s39, 0
	s_mov_b32 s38, -2
	v_add_u32_e32 v249, 0x10000, v144
	ds_read_b128 v[164:167], v249
	ds_read_b128 v[182:185], v249 offset:1024
	ds_read_b128 v[186:189], v249 offset:2048
	ds_read_b128 v[190:193], v249 offset:3072
	ds_read_b128 v[194:197], v162
	ds_read_b128 v[198:201], v162 offset:1024
	ds_read_b128 v[202:205], v162 offset:2048
	ds_read_b128 v[206:209], v162 offset:3072
	s_add_u32 s24, s0, 0xfffc0080
	s_addc_u32 s25, s1, -1
	s_add_i32 s39, 0, 0x10000
	s_cmp_eq_u32 s38, 12
	s_cselect_b32 vcc_hi, s77, s25
	s_cselect_b32 vcc_lo, s76, s24
	s_cselect_b32 s37, s47, s50
	s_cselect_b32 s36, s61, s35
	s_add_i32 m0, s93, 0xc000
	ds_read_b128 v[210:213], v162 offset:4096
	ds_read_b128 v[214:217], v162 offset:5120
	ds_read_b128 v[218:221], v162 offset:6144
	ds_read_b128 v[222:225], v162 offset:7168
	global_load_lds_dwordx4 v140, s[0:1]
	s_add_i32 m0, s93, 0xe000
	s_nop 0
	global_load_lds_dwordx4 v138, s[0:1]
	s_waitcnt lgkmcnt(8)
	s_barrier
	s_waitcnt lgkmcnt(0)
	s_setprio 1
	s_waitcnt lgkmcnt(0)
	v_mfma_f32_16x16x32_bf16 v[126:129], v[164:167], v[194:197], 0
	v_mfma_f32_16x16x32_bf16 v[126:129], v[182:185], v[198:201], v[126:129]
	v_mfma_f32_16x16x32_bf16 v[122:125], v[186:189], v[194:197], 0
	v_mfma_f32_16x16x32_bf16 v[122:125], v[190:193], v[198:201], v[122:125]
	v_mfma_f32_16x16x32_bf16 v[118:121], v[164:167], v[202:205], 0
	v_mfma_f32_16x16x32_bf16 v[118:121], v[182:185], v[206:209], v[118:121]
	v_mfma_f32_16x16x32_bf16 v[110:113], v[186:189], v[202:205], 0
	v_mfma_f32_16x16x32_bf16 v[110:113], v[190:193], v[206:209], v[110:113]
	v_mfma_f32_16x16x32_bf16 v[102:105], v[164:167], v[210:213], 0
	v_mfma_f32_16x16x32_bf16 v[102:105], v[182:185], v[214:217], v[102:105]
	v_mfma_f32_16x16x32_bf16 v[94:97], v[186:189], v[210:213], 0
	v_mfma_f32_16x16x32_bf16 v[94:97], v[190:193], v[214:217], v[94:97]
	v_mfma_f32_16x16x32_bf16 v[86:89], v[164:167], v[218:221], 0
	v_mfma_f32_16x16x32_bf16 v[86:89], v[182:185], v[222:225], v[86:89]
	v_mfma_f32_16x16x32_bf16 v[78:81], v[186:189], v[218:221], 0
	s_barrier
	v_mfma_f32_16x16x32_bf16 v[78:81], v[190:193], v[222:225], v[78:81]
	s_setprio 0
	s_add_i32 s51, 0, 0x14000
	s_add_i32 s24, s39, s86
	ds_read_b128 v[226:229], v249 offset:16384
	ds_read_b128 v[230:233], v249 offset:17408
	ds_read_b128 v[234:237], v249 offset:18432
	ds_read_b128 v[238:241], v249 offset:19456
	s_mov_b32 m0, s24
	global_load_lds_dwordx4 v134, s[36:37]
	s_add_i32 m0, s24, 0x2000
	s_nop 0
	global_load_lds_dwordx4 v130, s[36:37]
	s_barrier
	s_waitcnt lgkmcnt(0)
	s_setprio 1
	s_waitcnt lgkmcnt(0)
	v_mfma_f32_16x16x32_bf16 v[114:117], v[226:229], v[194:197], 0
	v_mfma_f32_16x16x32_bf16 v[114:117], v[230:233], v[198:201], v[114:117]
	v_mfma_f32_16x16x32_bf16 v[106:109], v[234:237], v[194:197], 0
	v_mfma_f32_16x16x32_bf16 v[106:109], v[238:241], v[198:201], v[106:109]
	v_mfma_f32_16x16x32_bf16 v[98:101], v[226:229], v[202:205], 0
	v_mfma_f32_16x16x32_bf16 v[98:101], v[230:233], v[206:209], v[98:101]
	v_mfma_f32_16x16x32_bf16 v[90:93], v[234:237], v[202:205], 0
	v_mfma_f32_16x16x32_bf16 v[90:93], v[238:241], v[206:209], v[90:93]
	v_mfma_f32_16x16x32_bf16 v[82:85], v[226:229], v[210:213], 0
	v_mfma_f32_16x16x32_bf16 v[82:85], v[230:233], v[214:217], v[82:85]
	v_mfma_f32_16x16x32_bf16 v[74:77], v[234:237], v[210:213], 0
	v_mfma_f32_16x16x32_bf16 v[74:77], v[238:241], v[214:217], v[74:77]
	v_mfma_f32_16x16x32_bf16 v[70:73], v[226:229], v[218:221], 0
	v_mfma_f32_16x16x32_bf16 v[70:73], v[230:233], v[222:225], v[70:73]
	v_mfma_f32_16x16x32_bf16 v[66:69], v[234:237], v[218:221], 0
	s_barrier
	v_mfma_f32_16x16x32_bf16 v[66:69], v[238:241], v[222:225], v[66:69]
	s_setprio 0
	s_mov_b32 m0, s93
	ds_read_b128 v[194:197], v162 offset:16384
	ds_read_b128 v[198:201], v162 offset:17408
	ds_read_b128 v[202:205], v162 offset:18432
	ds_read_b128 v[206:209], v162 offset:19456
	ds_read_b128 v[210:213], v162 offset:20480
	ds_read_b128 v[214:217], v162 offset:21504
	ds_read_b128 v[218:221], v162 offset:22528
	ds_read_b128 v[222:225], v162 offset:23552
	global_load_lds_dwordx4 v136, vcc
	s_mov_b32 m0, s94
	s_nop 0
	global_load_lds_dwordx4 v132, vcc
	s_waitcnt vmcnt(8)
	s_barrier
	s_waitcnt lgkmcnt(0)
	s_setprio 1
	s_waitcnt lgkmcnt(0)
	v_mfma_f32_16x16x32_bf16 v[62:65], v[164:167], v[194:197], 0
	v_mfma_f32_16x16x32_bf16 v[62:65], v[182:185], v[198:201], v[62:65]
	v_mfma_f32_16x16x32_bf16 v[58:61], v[186:189], v[194:197], 0
	v_mfma_f32_16x16x32_bf16 v[58:61], v[190:193], v[198:201], v[58:61]
	v_mfma_f32_16x16x32_bf16 v[54:57], v[164:167], v[202:205], 0
	v_mfma_f32_16x16x32_bf16 v[54:57], v[182:185], v[206:209], v[54:57]
	v_mfma_f32_16x16x32_bf16 v[46:49], v[186:189], v[202:205], 0
	v_mfma_f32_16x16x32_bf16 v[46:49], v[190:193], v[206:209], v[46:49]
	v_mfma_f32_16x16x32_bf16 v[38:41], v[164:167], v[210:213], 0
	v_mfma_f32_16x16x32_bf16 v[38:41], v[182:185], v[214:217], v[38:41]
	v_mfma_f32_16x16x32_bf16 v[30:33], v[186:189], v[210:213], 0
	v_mfma_f32_16x16x32_bf16 v[30:33], v[190:193], v[214:217], v[30:33]
	v_mfma_f32_16x16x32_bf16 v[22:25], v[164:167], v[218:221], 0
	v_mfma_f32_16x16x32_bf16 v[22:25], v[182:185], v[222:225], v[22:25]
	v_mfma_f32_16x16x32_bf16 v[14:17], v[186:189], v[218:221], 0
	s_barrier
; #define PG8_STAGE(bufoff, gbase, voff) do { _Pragma("unroll") for (int _i = 0; _i < 2; ++_i) \
;         __builtin_amdgcn_global_load_lds((const unsigned*)((const char*)(gbase) + (voff)[_i]), (LAS unsigned*)(lds + (bufoff) + ldsw + _i * 8192), 16, 0, 0); } while (0)
; #define PG8_LDA(dst, b, h) do { _Pragma("unroll") for (int m = 0; m < 4; ++m) _Pragma("unroll") for (int k = 0; k < 2; ++k) dst[m][k] = *(const LAS bf16x8*)(lds + PG8_SA(b, h) + aoff + m * 2048 + k * 1024); } while (0)
; #define PG8_LDB(dst, b, h) do { _Pragma("unroll") for (int n = 0; n < 2; ++n) _Pragma("unroll") for (int k = 0; k < 2; ++k) dst[n][k] = *(const LAS bf16x8*)(lds + PG8_SB(b, h) + boff + n * 2048 + k * 1024); } while (0)
; #define PG8_MMA(ai, bj, At, Bt) do { __builtin_amdgcn_s_setprio(1); _Pragma("unroll") for (int m = 0; m < 4; ++m) _Pragma("unroll") for (int n = 0; n < 2; ++n) _Pragma("unroll") for (int k = 0; k < 2; ++k) \
;         acc[ai][bj][m][n] = __builtin_amdgcn_mfma_f32_16x16x32_bf16(Bt[n][k], At[m][k], acc[ai][bj][m][n], 0, 0, 0); __builtin_amdgcn_s_setprio(0); } while (0)
; #define PG8_WAIT_V(n) asm volatile("s_waitcnt vmcnt(" #n ")" ::: "memory")
; #define PG8_WAIT_L(n) asm volatile("s_waitcnt lgkmcnt(" #n ")" ::: "memory")
; #define PG8_BAR __builtin_amdgcn_s_barrier()
; #define PG8_SCHED __builtin_amdgcn_sched_barrier(0)
; template <class Epi, class Sched>
; __device__ __forceinline__ void gemm_phase(LAS unsigned char* lds, const Gemm g, const Sched& S, const Epi& E) {
;     ...
;             PG8_BAR; PG8_WAIT_L(0); PG8_MMA(1, 0, At, B0); PG8_BAR; PG8_SCHED;
;             PG8_STAGE(PG8_SB(0, 1), b2 + hstep, voffB);
;             PG8_WAIT_V(6); PG8_BAR; PG8_MMA(1, 1, At, B1); PG8_BAR;
;             PG8_LDB(B0, 1, 0); PG8_SCHED; PG8_LDA(At, 1, 0); PG8_STAGE(PG8_SA(0, 1), a2 + hstep, voffA);
;             PG8_WAIT_L(8); PG8_BAR; PG8_WAIT_L(0); PG8_MMA(0, 0, At, B0); PG8_BAR; PG8_SCHED;
;             PG8_LDB(B1, 1, 1); PG8_STAGE(PG8_SB(1, 0), b3, voffB);
;             PG8_BAR; PG8_WAIT_L(0); PG8_MMA(0, 1, At, B1); PG8_BAR;
;             PG8_LDA(At, 1, 1); PG8_STAGE(PG8_SA(1, 0), a3, voffA);
	v_mfma_f32_16x16x32_bf16 v[14:17], v[190:193], v[222:225], v[14:17]
	s_setprio 0
	s_add_u32 s24, s36, 0x40000
	s_addc_u32 s25, s37, 0
	s_add_i32 s39, s51, s86
	s_mov_b32 m0, s39
	s_nop 0
	global_load_lds_dwordx4 v134, s[24:25]
	s_add_i32 m0, s39, 0x2000
	s_nop 0
	global_load_lds_dwordx4 v130, s[24:25]
	s_waitcnt vmcnt(6)
	s_barrier
	s_setprio 1
	v_mfma_f32_16x16x32_bf16 v[50:53], v[226:229], v[194:197], 0
	ds_read_b128 v[164:167], v249 offset:32768
	ds_read_b128 v[182:185], v249 offset:33792
	v_mfma_f32_16x16x32_bf16 v[50:53], v[230:233], v[198:201], v[50:53]
	ds_read_b128 v[186:189], v249 offset:34816
	ds_read_b128 v[190:193], v249 offset:35840
	v_mfma_f32_16x16x32_bf16 v[42:45], v[234:237], v[194:197], 0
	ds_read_b128 v[194:197], v162 offset:32768
	v_mfma_f32_16x16x32_bf16 v[42:45], v[238:241], v[198:201], v[42:45]
	ds_read_b128 v[198:201], v162 offset:33792
	v_mfma_f32_16x16x32_bf16 v[34:37], v[226:229], v[202:205], 0
	v_mfma_f32_16x16x32_bf16 v[34:37], v[230:233], v[206:209], v[34:37]
	v_mfma_f32_16x16x32_bf16 v[26:29], v[234:237], v[202:205], 0
	ds_read_b128 v[202:205], v162 offset:34816
	v_mfma_f32_16x16x32_bf16 v[26:29], v[238:241], v[206:209], v[26:29]
	ds_read_b128 v[206:209], v162 offset:35840
	v_mfma_f32_16x16x32_bf16 v[18:21], v[226:229], v[210:213], 0
	v_mfma_f32_16x16x32_bf16 v[18:21], v[230:233], v[214:217], v[18:21]
	v_mfma_f32_16x16x32_bf16 v[10:13], v[234:237], v[210:213], 0
	v_mfma_f32_16x16x32_bf16 v[10:13], v[238:241], v[214:217], v[10:13]
	v_mfma_f32_16x16x32_bf16 v[6:9], v[226:229], v[218:221], 0
	v_mfma_f32_16x16x32_bf16 v[6:9], v[230:233], v[222:225], v[6:9]
	v_mfma_f32_16x16x32_bf16 v[2:5], v[234:237], v[218:221], 0
	s_barrier
	v_mfma_f32_16x16x32_bf16 v[2:5], v[238:241], v[222:225], v[2:5]
	s_setprio 0
	s_add_i32 s39, 0, 0x18000
	s_add_u32 s24, vcc_lo, 0x40000
	s_addc_u32 s25, vcc_hi, 0
	s_mov_b32 m0, s95
	ds_read_b128 v[210:213], v162 offset:36864
	ds_read_b128 v[214:217], v162 offset:37888
	ds_read_b128 v[218:221], v162 offset:38912
	ds_read_b128 v[222:225], v162 offset:39936
	global_load_lds_dwordx4 v136, s[24:25]
	s_mov_b32 m0, s96
	s_nop 0
	global_load_lds_dwordx4 v132, s[24:25]
	s_waitcnt lgkmcnt(8)
	s_barrier
	s_waitcnt lgkmcnt(0)
	s_setprio 1
	s_waitcnt lgkmcnt(0)
	v_mfma_f32_16x16x32_bf16 v[126:129], v[164:167], v[194:197], v[126:129]
	v_mfma_f32_16x16x32_bf16 v[126:129], v[182:185], v[198:201], v[126:129]
	v_mfma_f32_16x16x32_bf16 v[122:125], v[186:189], v[194:197], v[122:125]
	v_mfma_f32_16x16x32_bf16 v[122:125], v[190:193], v[198:201], v[122:125]
	v_mfma_f32_16x16x32_bf16 v[118:121], v[164:167], v[202:205], v[118:121]
	v_mfma_f32_16x16x32_bf16 v[118:121], v[182:185], v[206:209], v[118:121]
	v_mfma_f32_16x16x32_bf16 v[110:113], v[186:189], v[202:205], v[110:113]
	v_mfma_f32_16x16x32_bf16 v[110:113], v[190:193], v[206:209], v[110:113]
	v_mfma_f32_16x16x32_bf16 v[102:105], v[164:167], v[210:213], v[102:105]
	v_mfma_f32_16x16x32_bf16 v[102:105], v[182:185], v[214:217], v[102:105]
	v_mfma_f32_16x16x32_bf16 v[94:97], v[186:189], v[210:213], v[94:97]
	v_mfma_f32_16x16x32_bf16 v[94:97], v[190:193], v[214:217], v[94:97]
	v_mfma_f32_16x16x32_bf16 v[86:89], v[164:167], v[218:221], v[86:89]
	v_mfma_f32_16x16x32_bf16 v[86:89], v[182:185], v[222:225], v[86:89]
	v_mfma_f32_16x16x32_bf16 v[78:81], v[186:189], v[218:221], v[78:81]
	s_barrier
	v_mfma_f32_16x16x32_bf16 v[78:81], v[190:193], v[222:225], v[78:81]
	s_setprio 0
	s_add_i32 s51, 0, 0x1c000
	s_add_i32 s24, s39, s86
	s_add_i32 m0, s24, 0xffffff80
	ds_read_b128 v[226:229], v249 offset:49152
	ds_read_b128 v[230:233], v249 offset:50176
	ds_read_b128 v[234:237], v249 offset:51200
	ds_read_b128 v[238:241], v249 offset:52224
	global_load_lds_dwordx4 v134, s[36:37] offset:128
	s_add_i32 m0, s24, 0x1f80
	s_nop 0
	global_load_lds_dwordx4 v130, s[36:37] offset:128
	s_barrier
	s_waitcnt lgkmcnt(0)
	s_setprio 1
	s_waitcnt lgkmcnt(0)
	v_mfma_f32_16x16x32_bf16 v[114:117], v[226:229], v[194:197], v[114:117]
	v_mfma_f32_16x16x32_bf16 v[114:117], v[230:233], v[198:201], v[114:117]
	v_mfma_f32_16x16x32_bf16 v[106:109], v[234:237], v[194:197], v[106:109]
	v_mfma_f32_16x16x32_bf16 v[106:109], v[238:241], v[198:201], v[106:109]
	v_mfma_f32_16x16x32_bf16 v[98:101], v[226:229], v[202:205], v[98:101]
	v_mfma_f32_16x16x32_bf16 v[98:101], v[230:233], v[206:209], v[98:101]
	v_mfma_f32_16x16x32_bf16 v[90:93], v[234:237], v[202:205], v[90:93]
	v_mfma_f32_16x16x32_bf16 v[90:93], v[238:241], v[206:209], v[90:93]
	v_mfma_f32_16x16x32_bf16 v[82:85], v[226:229], v[210:213], v[82:85]
	v_mfma_f32_16x16x32_bf16 v[82:85], v[230:233], v[214:217], v[82:85]
	v_mfma_f32_16x16x32_bf16 v[74:77], v[234:237], v[210:213], v[74:77]
	v_mfma_f32_16x16x32_bf16 v[74:77], v[238:241], v[214:217], v[74:77]
	v_mfma_f32_16x16x32_bf16 v[70:73], v[226:229], v[218:221], v[70:73]
	v_mfma_f32_16x16x32_bf16 v[70:73], v[230:233], v[222:225], v[70:73]
	v_mfma_f32_16x16x32_bf16 v[66:69], v[234:237], v[218:221], v[66:69]
	s_barrier
	v_mfma_f32_16x16x32_bf16 v[66:69], v[238:241], v[222:225], v[66:69]
	s_setprio 0
	s_add_i32 m0, s97, 0xffffff80
	ds_read_b128 v[194:197], v162 offset:49152
	ds_read_b128 v[198:201], v162 offset:50176
	ds_read_b128 v[202:205], v162 offset:51200
	ds_read_b128 v[206:209], v162 offset:52224
	ds_read_b128 v[210:213], v162 offset:53248
	ds_read_b128 v[214:217], v162 offset:54272
	ds_read_b128 v[218:221], v162 offset:55296
	ds_read_b128 v[222:225], v162 offset:56320
	global_load_lds_dwordx4 v136, vcc offset:128
	s_add_i32 m0, s98, 0xffffff80
	s_nop 0
	global_load_lds_dwordx4 v132, vcc offset:128
	s_waitcnt vmcnt(8)
	s_barrier
; #define PG8_STAGE(bufoff, gbase, voff) do { _Pragma("unroll") for (int _i = 0; _i < 2; ++_i) \
;         __builtin_amdgcn_global_load_lds((const unsigned*)((const char*)(gbase) + (voff)[_i]), (LAS unsigned*)(lds + (bufoff) + ldsw + _i * 8192), 16, 0, 0); } while (0)
; #define PG8_LDA(dst, b, h) do { _Pragma("unroll") for (int m = 0; m < 4; ++m) _Pragma("unroll") for (int k = 0; k < 2; ++k) dst[m][k] = *(const LAS bf16x8*)(lds + PG8_SA(b, h) + aoff + m * 2048 + k * 1024); } while (0)
; #define PG8_LDB(dst, b, h) do { _Pragma("unroll") for (int n = 0; n < 2; ++n) _Pragma("unroll") for (int k = 0; k < 2; ++k) dst[n][k] = *(const LAS bf16x8*)(lds + PG8_SB(b, h) + boff + n * 2048 + k * 1024); } while (0)
; #define PG8_WAIT_V(n) asm volatile("s_waitcnt vmcnt(" #n ")" ::: "memory")
; #define PG8_WAIT_L(n) asm volatile("s_waitcnt lgkmcnt(" #n ")" ::: "memory")
; #define PG8_BAR __builtin_amdgcn_s_barrier()
; #define PG8_SCHED __builtin_amdgcn_sched_barrier(0)
; template <class Epi, class Sched>
; __device__ __forceinline__ void gemm_phase(LAS unsigned char* lds, const Gemm g, const Sched& S, const Epi& E) {
;     ...
;             PG8_LDB(B0, 0, 0); PG8_SCHED; PG8_LDA(At, 0, 0); PG8_STAGE(PG8_SA(1, 1), a1 + hstep, voffA);
;             PG8_WAIT_L(8); PG8_BAR; PG8_WAIT_L(0); PG8_MMA(0, 0, At, B0); PG8_BAR; PG8_SCHED;
;             PG8_LDB(B1, 0, 1); PG8_STAGE(PG8_SB(0, 0), b2, voffB);
;             PG8_BAR; PG8_WAIT_L(0); PG8_MMA(0, 1, At, B1); PG8_BAR;
;             PG8_LDA(At, 0, 1); PG8_STAGE(PG8_SA(0, 0), a2, voffA);
;             PG8_BAR; PG8_WAIT_L(0); PG8_MMA(1, 0, At, B0); PG8_BAR; PG8_SCHED;
;             PG8_STAGE(PG8_SB(0, 1), b2 + hstep, voffB);
;             PG8_WAIT_V(6); PG8_BAR; PG8_MMA(1, 1, At, B1); PG8_BAR;
;             PG8_LDB(B0, 1, 0); PG8_SCHED; PG8_LDA(At, 1, 0); PG8_STAGE(PG8_SA(0, 1), a2 + hstep, voffA);
;             PG8_WAIT_L(8); PG8_BAR; PG8_WAIT_L(0); PG8_MMA(0, 0, At, B0); PG8_BAR; PG8_SCHED;
;             PG8_LDB(B1, 1, 1); PG8_STAGE(PG8_SB(1, 0), b3, voffB);
;             PG8_BAR; PG8_WAIT_L(0); PG8_MMA(0, 1, At, B1); PG8_BAR;
;             PG8_LDA(At, 1, 1); PG8_STAGE(PG8_SA(1, 0), a3, voffA);
;             PG8_BAR; PG8_WAIT_L(0); PG8_MMA(1, 0, At, B0); PG8_BAR; PG8_SCHED;
;             PG8_STAGE(PG8_SB(1, 1), b3 + hstep, voffB);
;             PG8_WAIT_V(6); PG8_BAR; PG8_MMA(1, 1, At, B1); PG8_BAR;
	s_waitcnt lgkmcnt(0)
	s_setprio 1
	s_waitcnt lgkmcnt(0)
	v_mfma_f32_16x16x32_bf16 v[62:65], v[164:167], v[194:197], v[62:65]
	v_mfma_f32_16x16x32_bf16 v[62:65], v[182:185], v[198:201], v[62:65]
	v_mfma_f32_16x16x32_bf16 v[58:61], v[186:189], v[194:197], v[58:61]
	v_mfma_f32_16x16x32_bf16 v[58:61], v[190:193], v[198:201], v[58:61]
	v_mfma_f32_16x16x32_bf16 v[54:57], v[164:167], v[202:205], v[54:57]
	v_mfma_f32_16x16x32_bf16 v[54:57], v[182:185], v[206:209], v[54:57]
	v_mfma_f32_16x16x32_bf16 v[46:49], v[186:189], v[202:205], v[46:49]
	v_mfma_f32_16x16x32_bf16 v[46:49], v[190:193], v[206:209], v[46:49]
	v_mfma_f32_16x16x32_bf16 v[38:41], v[164:167], v[210:213], v[38:41]
	v_mfma_f32_16x16x32_bf16 v[38:41], v[182:185], v[214:217], v[38:41]
	v_mfma_f32_16x16x32_bf16 v[30:33], v[186:189], v[210:213], v[30:33]
	v_mfma_f32_16x16x32_bf16 v[30:33], v[190:193], v[214:217], v[30:33]
	v_mfma_f32_16x16x32_bf16 v[22:25], v[164:167], v[218:221], v[22:25]
	v_mfma_f32_16x16x32_bf16 v[22:25], v[182:185], v[222:225], v[22:25]
	v_mfma_f32_16x16x32_bf16 v[14:17], v[186:189], v[218:221], v[14:17]
	s_barrier
	v_mfma_f32_16x16x32_bf16 v[14:17], v[190:193], v[222:225], v[14:17]
	s_setprio 0
	s_add_u32 s24, s36, 0x40080
	s_addc_u32 s25, s37, 0
	s_add_i32 s36, s51, s86
	s_mov_b32 m0, s36
	s_nop 0
	global_load_lds_dwordx4 v134, s[24:25]
	s_add_i32 m0, s36, 0x2000
	s_nop 0
	global_load_lds_dwordx4 v130, s[24:25]
	s_waitcnt vmcnt(6)
	s_barrier
	s_setprio 1
	v_mfma_f32_16x16x32_bf16 v[50:53], v[226:229], v[194:197], v[50:53]
	ds_read_b128 v[164:167], v249
	ds_read_b128 v[182:185], v249 offset:1024
	v_mfma_f32_16x16x32_bf16 v[50:53], v[230:233], v[198:201], v[50:53]
	ds_read_b128 v[186:189], v249 offset:2048
	ds_read_b128 v[190:193], v249 offset:3072
	v_mfma_f32_16x16x32_bf16 v[42:45], v[234:237], v[194:197], v[42:45]
	ds_read_b128 v[194:197], v162
	v_mfma_f32_16x16x32_bf16 v[42:45], v[238:241], v[198:201], v[42:45]
	ds_read_b128 v[198:201], v162 offset:1024
	v_mfma_f32_16x16x32_bf16 v[34:37], v[226:229], v[202:205], v[34:37]
	v_mfma_f32_16x16x32_bf16 v[34:37], v[230:233], v[206:209], v[34:37]
	v_mfma_f32_16x16x32_bf16 v[26:29], v[234:237], v[202:205], v[26:29]
	ds_read_b128 v[202:205], v162 offset:2048
	v_mfma_f32_16x16x32_bf16 v[26:29], v[238:241], v[206:209], v[26:29]
	ds_read_b128 v[206:209], v162 offset:3072
	v_mfma_f32_16x16x32_bf16 v[18:21], v[226:229], v[210:213], v[18:21]
	v_mfma_f32_16x16x32_bf16 v[18:21], v[230:233], v[214:217], v[18:21]
	v_mfma_f32_16x16x32_bf16 v[10:13], v[234:237], v[210:213], v[10:13]
	v_mfma_f32_16x16x32_bf16 v[10:13], v[238:241], v[214:217], v[10:13]
	v_mfma_f32_16x16x32_bf16 v[6:9], v[226:229], v[218:221], v[6:9]
	v_mfma_f32_16x16x32_bf16 v[6:9], v[230:233], v[222:225], v[6:9]
	v_mfma_f32_16x16x32_bf16 v[2:5], v[234:237], v[218:221], v[2:5]
	s_barrier
	v_mfma_f32_16x16x32_bf16 v[2:5], v[238:241], v[222:225], v[2:5]
	s_setprio 0
	s_add_i32 s38, s38, 2
	s_add_u32 s35, s35, 0x100
	s_addc_u32 s50, s50, 0
	s_add_u32 s0, s0, 0x100
	s_addc_u32 s1, s1, 0
	s_cmp_gt_u32 s38, 13
.LBB0_416:
	s_add_u32 s24, s0, 0xfffc0080
	s_addc_u32 s25, s1, -1
	s_add_i32 s39, 0, 0x10000
	s_cmp_eq_u32 s38, 12
	s_cselect_b32 vcc_hi, s77, s25
	s_cselect_b32 vcc_lo, s76, s24
	s_cselect_b32 s37, s47, s50
	s_cselect_b32 s36, s61, s35
	s_add_i32 m0, s93, 0xc000
	ds_read_b128 v[210:213], v162 offset:4096
	ds_read_b128 v[214:217], v162 offset:5120
	ds_read_b128 v[218:221], v162 offset:6144
	ds_read_b128 v[222:225], v162 offset:7168
	global_load_lds_dwordx4 v140, s[0:1]
	s_add_i32 m0, s93, 0xe000
	s_nop 0
	global_load_lds_dwordx4 v138, s[0:1]
	s_waitcnt lgkmcnt(8)
	s_barrier
	s_waitcnt lgkmcnt(0)
	s_setprio 1
	s_waitcnt lgkmcnt(0)
	v_mfma_f32_16x16x32_bf16 v[126:129], v[164:167], v[194:197], v[126:129]
	v_mfma_f32_16x16x32_bf16 v[126:129], v[182:185], v[198:201], v[126:129]
	v_mfma_f32_16x16x32_bf16 v[122:125], v[186:189], v[194:197], v[122:125]
	v_mfma_f32_16x16x32_bf16 v[122:125], v[190:193], v[198:201], v[122:125]
	v_mfma_f32_16x16x32_bf16 v[118:121], v[164:167], v[202:205], v[118:121]
	v_mfma_f32_16x16x32_bf16 v[118:121], v[182:185], v[206:209], v[118:121]
	v_mfma_f32_16x16x32_bf16 v[110:113], v[186:189], v[202:205], v[110:113]
	v_mfma_f32_16x16x32_bf16 v[110:113], v[190:193], v[206:209], v[110:113]
	v_mfma_f32_16x16x32_bf16 v[102:105], v[164:167], v[210:213], v[102:105]
	v_mfma_f32_16x16x32_bf16 v[102:105], v[182:185], v[214:217], v[102:105]
	v_mfma_f32_16x16x32_bf16 v[94:97], v[186:189], v[210:213], v[94:97]
	v_mfma_f32_16x16x32_bf16 v[94:97], v[190:193], v[214:217], v[94:97]
	v_mfma_f32_16x16x32_bf16 v[86:89], v[164:167], v[218:221], v[86:89]
	v_mfma_f32_16x16x32_bf16 v[86:89], v[182:185], v[222:225], v[86:89]
	v_mfma_f32_16x16x32_bf16 v[78:81], v[186:189], v[218:221], v[78:81]
	s_barrier
	v_mfma_f32_16x16x32_bf16 v[78:81], v[190:193], v[222:225], v[78:81]
	s_setprio 0
	s_add_i32 s51, 0, 0x14000
	s_add_i32 s24, s39, s86
	ds_read_b128 v[226:229], v249 offset:16384
	ds_read_b128 v[230:233], v249 offset:17408
	ds_read_b128 v[234:237], v249 offset:18432
	ds_read_b128 v[238:241], v249 offset:19456
	s_mov_b32 m0, s24
	global_load_lds_dwordx4 v134, s[36:37]
	s_add_i32 m0, s24, 0x2000
	s_nop 0
	global_load_lds_dwordx4 v130, s[36:37]
	s_barrier
; #define PG8_STAGE(bufoff, gbase, voff) do { _Pragma("unroll") for (int _i = 0; _i < 2; ++_i) \
;         __builtin_amdgcn_global_load_lds((const unsigned*)((const char*)(gbase) + (voff)[_i]), (LAS unsigned*)(lds + (bufoff) + ldsw + _i * 8192), 16, 0, 0); } while (0)
; #define PG8_LDA(dst, b, h) do { _Pragma("unroll") for (int m = 0; m < 4; ++m) _Pragma("unroll") for (int k = 0; k < 2; ++k) dst[m][k] = *(const LAS bf16x8*)(lds + PG8_SA(b, h) + aoff + m * 2048 + k * 1024); } while (0)
; #define PG8_LDB(dst, b, h) do { _Pragma("unroll") for (int n = 0; n < 2; ++n) _Pragma("unroll") for (int k = 0; k < 2; ++k) dst[n][k] = *(const LAS bf16x8*)(lds + PG8_SB(b, h) + boff + n * 2048 + k * 1024); } while (0)
; #define PG8_MMA(ai, bj, At, Bt) do { __builtin_amdgcn_s_setprio(1); _Pragma("unroll") for (int m = 0; m < 4; ++m) _Pragma("unroll") for (int n = 0; n < 2; ++n) _Pragma("unroll") for (int k = 0; k < 2; ++k) \
;         acc[ai][bj][m][n] = __builtin_amdgcn_mfma_f32_16x16x32_bf16(Bt[n][k], At[m][k], acc[ai][bj][m][n], 0, 0, 0); __builtin_amdgcn_s_setprio(0); } while (0)
; #define PG8_WAIT_V(n) asm volatile("s_waitcnt vmcnt(" #n ")" ::: "memory")
; #define PG8_WAIT_L(n) asm volatile("s_waitcnt lgkmcnt(" #n ")" ::: "memory")
; #define PG8_BAR __builtin_amdgcn_s_barrier()
; #define PG8_SCHED __builtin_amdgcn_sched_barrier(0)
; template <class Epi, class Sched>
; __device__ __forceinline__ void gemm_phase(LAS unsigned char* lds, const Gemm g, const Sched& S, const Epi& E) {
;     ...
;             PG8_BAR; PG8_WAIT_L(0); PG8_MMA(0, 1, At, B1); PG8_BAR;
;             PG8_LDA(At, 0, 1); PG8_STAGE(PG8_SA(0, 0), a2, voffA);
;             PG8_BAR; PG8_WAIT_L(0); PG8_MMA(1, 0, At, B0); PG8_BAR; PG8_SCHED;
;             PG8_STAGE(PG8_SB(0, 1), b2 + hstep, voffB);
;             PG8_WAIT_V(6); PG8_BAR; PG8_MMA(1, 1, At, B1); PG8_BAR;
;             PG8_LDB(B0, 1, 0); PG8_SCHED; PG8_LDA(At, 1, 0); PG8_STAGE(PG8_SA(0, 1), a2 + hstep, voffA);
;             PG8_WAIT_L(8); PG8_BAR; PG8_WAIT_L(0); PG8_MMA(0, 0, At, B0); PG8_BAR; PG8_SCHED;
	s_waitcnt lgkmcnt(0)
	s_setprio 1
	s_waitcnt lgkmcnt(0)
	v_mfma_f32_16x16x32_bf16 v[114:117], v[226:229], v[194:197], v[114:117]
	v_mfma_f32_16x16x32_bf16 v[114:117], v[230:233], v[198:201], v[114:117]
	v_mfma_f32_16x16x32_bf16 v[106:109], v[234:237], v[194:197], v[106:109]
	v_mfma_f32_16x16x32_bf16 v[106:109], v[238:241], v[198:201], v[106:109]
	v_mfma_f32_16x16x32_bf16 v[98:101], v[226:229], v[202:205], v[98:101]
	v_mfma_f32_16x16x32_bf16 v[98:101], v[230:233], v[206:209], v[98:101]
	v_mfma_f32_16x16x32_bf16 v[90:93], v[234:237], v[202:205], v[90:93]
	v_mfma_f32_16x16x32_bf16 v[90:93], v[238:241], v[206:209], v[90:93]
	v_mfma_f32_16x16x32_bf16 v[82:85], v[226:229], v[210:213], v[82:85]
	v_mfma_f32_16x16x32_bf16 v[82:85], v[230:233], v[214:217], v[82:85]
	v_mfma_f32_16x16x32_bf16 v[74:77], v[234:237], v[210:213], v[74:77]
	v_mfma_f32_16x16x32_bf16 v[74:77], v[238:241], v[214:217], v[74:77]
	v_mfma_f32_16x16x32_bf16 v[70:73], v[226:229], v[218:221], v[70:73]
	v_mfma_f32_16x16x32_bf16 v[70:73], v[230:233], v[222:225], v[70:73]
	v_mfma_f32_16x16x32_bf16 v[66:69], v[234:237], v[218:221], v[66:69]
	s_barrier
	v_mfma_f32_16x16x32_bf16 v[66:69], v[238:241], v[222:225], v[66:69]
	s_setprio 0
	s_mov_b32 m0, s93
	ds_read_b128 v[194:197], v162 offset:16384
	ds_read_b128 v[198:201], v162 offset:17408
	ds_read_b128 v[202:205], v162 offset:18432
	ds_read_b128 v[206:209], v162 offset:19456
	ds_read_b128 v[210:213], v162 offset:20480
	ds_read_b128 v[214:217], v162 offset:21504
	ds_read_b128 v[218:221], v162 offset:22528
	ds_read_b128 v[222:225], v162 offset:23552
	global_load_lds_dwordx4 v136, vcc
	s_mov_b32 m0, s94
	s_nop 0
	global_load_lds_dwordx4 v132, vcc
	s_waitcnt vmcnt(8)
	s_barrier
	s_waitcnt lgkmcnt(0)
	s_setprio 1
	s_waitcnt lgkmcnt(0)
	v_mfma_f32_16x16x32_bf16 v[62:65], v[164:167], v[194:197], v[62:65]
	v_mfma_f32_16x16x32_bf16 v[62:65], v[182:185], v[198:201], v[62:65]
	v_mfma_f32_16x16x32_bf16 v[58:61], v[186:189], v[194:197], v[58:61]
	v_mfma_f32_16x16x32_bf16 v[58:61], v[190:193], v[198:201], v[58:61]
	v_mfma_f32_16x16x32_bf16 v[54:57], v[164:167], v[202:205], v[54:57]
	v_mfma_f32_16x16x32_bf16 v[54:57], v[182:185], v[206:209], v[54:57]
	v_mfma_f32_16x16x32_bf16 v[46:49], v[186:189], v[202:205], v[46:49]
	v_mfma_f32_16x16x32_bf16 v[46:49], v[190:193], v[206:209], v[46:49]
	v_mfma_f32_16x16x32_bf16 v[38:41], v[164:167], v[210:213], v[38:41]
	v_mfma_f32_16x16x32_bf16 v[38:41], v[182:185], v[214:217], v[38:41]
	v_mfma_f32_16x16x32_bf16 v[30:33], v[186:189], v[210:213], v[30:33]
	v_mfma_f32_16x16x32_bf16 v[30:33], v[190:193], v[214:217], v[30:33]
	v_mfma_f32_16x16x32_bf16 v[22:25], v[164:167], v[218:221], v[22:25]
	v_mfma_f32_16x16x32_bf16 v[22:25], v[182:185], v[222:225], v[22:25]
	v_mfma_f32_16x16x32_bf16 v[14:17], v[186:189], v[218:221], v[14:17]
	s_barrier
	v_mfma_f32_16x16x32_bf16 v[14:17], v[190:193], v[222:225], v[14:17]
	s_setprio 0
	s_add_u32 s24, s36, 0x40000
	s_addc_u32 s25, s37, 0
	s_add_i32 s39, s51, s86
	s_mov_b32 m0, s39
	s_nop 0
	global_load_lds_dwordx4 v134, s[24:25]
	s_add_i32 m0, s39, 0x2000
	s_nop 0
	global_load_lds_dwordx4 v130, s[24:25]
	s_waitcnt vmcnt(6)
	s_barrier
	s_setprio 1
	v_mfma_f32_16x16x32_bf16 v[50:53], v[226:229], v[194:197], v[50:53]
	ds_read_b128 v[164:167], v249 offset:32768
	ds_read_b128 v[182:185], v249 offset:33792
	v_mfma_f32_16x16x32_bf16 v[50:53], v[230:233], v[198:201], v[50:53]
	ds_read_b128 v[186:189], v249 offset:34816
	ds_read_b128 v[190:193], v249 offset:35840
	v_mfma_f32_16x16x32_bf16 v[42:45], v[234:237], v[194:197], v[42:45]
	ds_read_b128 v[194:197], v162 offset:32768
	v_mfma_f32_16x16x32_bf16 v[42:45], v[238:241], v[198:201], v[42:45]
	ds_read_b128 v[198:201], v162 offset:33792
	v_mfma_f32_16x16x32_bf16 v[34:37], v[226:229], v[202:205], v[34:37]
	v_mfma_f32_16x16x32_bf16 v[34:37], v[230:233], v[206:209], v[34:37]
	v_mfma_f32_16x16x32_bf16 v[26:29], v[234:237], v[202:205], v[26:29]
	ds_read_b128 v[202:205], v162 offset:34816
	v_mfma_f32_16x16x32_bf16 v[26:29], v[238:241], v[206:209], v[26:29]
	ds_read_b128 v[206:209], v162 offset:35840
	v_mfma_f32_16x16x32_bf16 v[18:21], v[226:229], v[210:213], v[18:21]
	v_mfma_f32_16x16x32_bf16 v[18:21], v[230:233], v[214:217], v[18:21]
	v_mfma_f32_16x16x32_bf16 v[10:13], v[234:237], v[210:213], v[10:13]
	v_mfma_f32_16x16x32_bf16 v[10:13], v[238:241], v[214:217], v[10:13]
	v_mfma_f32_16x16x32_bf16 v[6:9], v[226:229], v[218:221], v[6:9]
	v_mfma_f32_16x16x32_bf16 v[6:9], v[230:233], v[222:225], v[6:9]
	v_mfma_f32_16x16x32_bf16 v[2:5], v[234:237], v[218:221], v[2:5]
	s_barrier
	v_mfma_f32_16x16x32_bf16 v[2:5], v[238:241], v[222:225], v[2:5]
	s_setprio 0
	s_add_i32 s39, 0, 0x18000
	s_add_u32 s24, vcc_lo, 0x40000
	s_addc_u32 s25, vcc_hi, 0
	s_mov_b32 m0, s95
	ds_read_b128 v[210:213], v162 offset:36864
	ds_read_b128 v[214:217], v162 offset:37888
	ds_read_b128 v[218:221], v162 offset:38912
	ds_read_b128 v[222:225], v162 offset:39936
	global_load_lds_dwordx4 v136, s[24:25]
	s_mov_b32 m0, s96
	s_nop 0
	global_load_lds_dwordx4 v132, s[24:25]
	s_waitcnt lgkmcnt(8)
	s_barrier
	s_waitcnt lgkmcnt(0)
	s_setprio 1
	s_waitcnt lgkmcnt(0)
	v_mfma_f32_16x16x32_bf16 v[126:129], v[164:167], v[194:197], v[126:129]
	v_mfma_f32_16x16x32_bf16 v[126:129], v[182:185], v[198:201], v[126:129]
	v_mfma_f32_16x16x32_bf16 v[122:125], v[186:189], v[194:197], v[122:125]
	v_mfma_f32_16x16x32_bf16 v[122:125], v[190:193], v[198:201], v[122:125]
	v_mfma_f32_16x16x32_bf16 v[118:121], v[164:167], v[202:205], v[118:121]
	v_mfma_f32_16x16x32_bf16 v[118:121], v[182:185], v[206:209], v[118:121]
	v_mfma_f32_16x16x32_bf16 v[110:113], v[186:189], v[202:205], v[110:113]
	v_mfma_f32_16x16x32_bf16 v[110:113], v[190:193], v[206:209], v[110:113]
	v_mfma_f32_16x16x32_bf16 v[102:105], v[164:167], v[210:213], v[102:105]
	v_mfma_f32_16x16x32_bf16 v[102:105], v[182:185], v[214:217], v[102:105]
	v_mfma_f32_16x16x32_bf16 v[94:97], v[186:189], v[210:213], v[94:97]
	v_mfma_f32_16x16x32_bf16 v[94:97], v[190:193], v[214:217], v[94:97]
	v_mfma_f32_16x16x32_bf16 v[86:89], v[164:167], v[218:221], v[86:89]
	v_mfma_f32_16x16x32_bf16 v[86:89], v[182:185], v[222:225], v[86:89]
	v_mfma_f32_16x16x32_bf16 v[78:81], v[186:189], v[218:221], v[78:81]
	s_barrier
; #define PG8_STAGE(bufoff, gbase, voff) do { _Pragma("unroll") for (int _i = 0; _i < 2; ++_i) \
;         __builtin_amdgcn_global_load_lds((const unsigned*)((const char*)(gbase) + (voff)[_i]), (LAS unsigned*)(lds + (bufoff) + ldsw + _i * 8192), 16, 0, 0); } while (0)
; #define PG8_LDA(dst, b, h) do { _Pragma("unroll") for (int m = 0; m < 4; ++m) _Pragma("unroll") for (int k = 0; k < 2; ++k) dst[m][k] = *(const LAS bf16x8*)(lds + PG8_SA(b, h) + aoff + m * 2048 + k * 1024); } while (0)
; #define PG8_LDB(dst, b, h) do { _Pragma("unroll") for (int n = 0; n < 2; ++n) _Pragma("unroll") for (int k = 0; k < 2; ++k) dst[n][k] = *(const LAS bf16x8*)(lds + PG8_SB(b, h) + boff + n * 2048 + k * 1024); } while (0)
; #define PG8_MMA(ai, bj, At, Bt) do { __builtin_amdgcn_s_setprio(1); _Pragma("unroll") for (int m = 0; m < 4; ++m) _Pragma("unroll") for (int n = 0; n < 2; ++n) _Pragma("unroll") for (int k = 0; k < 2; ++k) \
;         acc[ai][bj][m][n] = __builtin_amdgcn_mfma_f32_16x16x32_bf16(Bt[n][k], At[m][k], acc[ai][bj][m][n], 0, 0, 0); __builtin_amdgcn_s_setprio(0); } while (0)
; #define PG8_WAIT_V(n) asm volatile("s_waitcnt vmcnt(" #n ")" ::: "memory")
; #define PG8_WAIT_L(n) asm volatile("s_waitcnt lgkmcnt(" #n ")" ::: "memory")
; #define PG8_BAR __builtin_amdgcn_s_barrier()
; #define PG8_SCHED __builtin_amdgcn_sched_barrier(0)
; template <class Epi, class Sched>
; __device__ __forceinline__ void gemm_phase(LAS unsigned char* lds, const Gemm g, const Sched& S, const Epi& E) {
;     ...
;             PG8_WAIT_L(8); PG8_BAR; PG8_WAIT_L(0); PG8_MMA(0, 0, At, B0); PG8_BAR; PG8_SCHED;
;             PG8_LDB(B1, 1, 1); PG8_STAGE(PG8_SB(1, 0), b3, voffB);
;             PG8_BAR; PG8_WAIT_L(0); PG8_MMA(0, 1, At, B1); PG8_BAR;
;             PG8_LDA(At, 1, 1); PG8_STAGE(PG8_SA(1, 0), a3, voffA);
;             PG8_BAR; PG8_WAIT_L(0); PG8_MMA(1, 0, At, B0); PG8_BAR; PG8_SCHED;
;             PG8_STAGE(PG8_SB(1, 1), b3 + hstep, voffB);
;             PG8_WAIT_V(6); PG8_BAR; PG8_MMA(1, 1, At, B1); PG8_BAR;
;         }
;         if (wr == 0) PG8_BAR;
	v_mfma_f32_16x16x32_bf16 v[78:81], v[190:193], v[222:225], v[78:81]
	s_setprio 0
	s_add_i32 s51, 0, 0x1c000
	s_add_i32 s24, s39, s86
	s_add_i32 m0, s24, 0xffffff80
	ds_read_b128 v[226:229], v249 offset:49152
	ds_read_b128 v[230:233], v249 offset:50176
	ds_read_b128 v[234:237], v249 offset:51200
	ds_read_b128 v[238:241], v249 offset:52224
	global_load_lds_dwordx4 v134, s[36:37] offset:128
	s_add_i32 m0, s24, 0x1f80
	s_nop 0
	global_load_lds_dwordx4 v130, s[36:37] offset:128
	s_barrier
	s_waitcnt lgkmcnt(0)
	s_setprio 1
	s_waitcnt lgkmcnt(0)
	v_mfma_f32_16x16x32_bf16 v[114:117], v[226:229], v[194:197], v[114:117]
	v_mfma_f32_16x16x32_bf16 v[114:117], v[230:233], v[198:201], v[114:117]
	v_mfma_f32_16x16x32_bf16 v[106:109], v[234:237], v[194:197], v[106:109]
	v_mfma_f32_16x16x32_bf16 v[106:109], v[238:241], v[198:201], v[106:109]
	v_mfma_f32_16x16x32_bf16 v[98:101], v[226:229], v[202:205], v[98:101]
	v_mfma_f32_16x16x32_bf16 v[98:101], v[230:233], v[206:209], v[98:101]
	v_mfma_f32_16x16x32_bf16 v[90:93], v[234:237], v[202:205], v[90:93]
	v_mfma_f32_16x16x32_bf16 v[90:93], v[238:241], v[206:209], v[90:93]
	v_mfma_f32_16x16x32_bf16 v[82:85], v[226:229], v[210:213], v[82:85]
	v_mfma_f32_16x16x32_bf16 v[82:85], v[230:233], v[214:217], v[82:85]
	v_mfma_f32_16x16x32_bf16 v[74:77], v[234:237], v[210:213], v[74:77]
	v_mfma_f32_16x16x32_bf16 v[74:77], v[238:241], v[214:217], v[74:77]
	v_mfma_f32_16x16x32_bf16 v[70:73], v[226:229], v[218:221], v[70:73]
	v_mfma_f32_16x16x32_bf16 v[70:73], v[230:233], v[222:225], v[70:73]
	v_mfma_f32_16x16x32_bf16 v[66:69], v[234:237], v[218:221], v[66:69]
	s_barrier
	v_mfma_f32_16x16x32_bf16 v[66:69], v[238:241], v[222:225], v[66:69]
	s_setprio 0
	s_add_i32 m0, s97, 0xffffff80
	ds_read_b128 v[194:197], v162 offset:49152
	ds_read_b128 v[198:201], v162 offset:50176
	ds_read_b128 v[202:205], v162 offset:51200
	ds_read_b128 v[206:209], v162 offset:52224
	ds_read_b128 v[210:213], v162 offset:53248
	ds_read_b128 v[214:217], v162 offset:54272
	ds_read_b128 v[218:221], v162 offset:55296
	ds_read_b128 v[222:225], v162 offset:56320
	global_load_lds_dwordx4 v136, vcc offset:128
	s_add_i32 m0, s98, 0xffffff80
	s_nop 0
	global_load_lds_dwordx4 v132, vcc offset:128
	s_waitcnt vmcnt(8)
	s_barrier
	s_waitcnt lgkmcnt(0)
	s_setprio 1
	s_waitcnt lgkmcnt(0)
	v_mfma_f32_16x16x32_bf16 v[62:65], v[164:167], v[194:197], v[62:65]
	v_mfma_f32_16x16x32_bf16 v[62:65], v[182:185], v[198:201], v[62:65]
	v_mfma_f32_16x16x32_bf16 v[58:61], v[186:189], v[194:197], v[58:61]
	v_mfma_f32_16x16x32_bf16 v[58:61], v[190:193], v[198:201], v[58:61]
	v_mfma_f32_16x16x32_bf16 v[54:57], v[164:167], v[202:205], v[54:57]
	v_mfma_f32_16x16x32_bf16 v[54:57], v[182:185], v[206:209], v[54:57]
	v_mfma_f32_16x16x32_bf16 v[46:49], v[186:189], v[202:205], v[46:49]
	v_mfma_f32_16x16x32_bf16 v[46:49], v[190:193], v[206:209], v[46:49]
	v_mfma_f32_16x16x32_bf16 v[38:41], v[164:167], v[210:213], v[38:41]
	v_mfma_f32_16x16x32_bf16 v[38:41], v[182:185], v[214:217], v[38:41]
	v_mfma_f32_16x16x32_bf16 v[30:33], v[186:189], v[210:213], v[30:33]
	v_mfma_f32_16x16x32_bf16 v[30:33], v[190:193], v[214:217], v[30:33]
	v_mfma_f32_16x16x32_bf16 v[22:25], v[164:167], v[218:221], v[22:25]
	v_mfma_f32_16x16x32_bf16 v[22:25], v[182:185], v[222:225], v[22:25]
	v_mfma_f32_16x16x32_bf16 v[14:17], v[186:189], v[218:221], v[14:17]
	s_barrier
	v_mfma_f32_16x16x32_bf16 v[14:17], v[190:193], v[222:225], v[14:17]
	s_setprio 0
	s_add_u32 s24, s36, 0x40080
	s_addc_u32 s25, s37, 0
	s_add_i32 s36, s51, s86
	s_mov_b32 m0, s36
	s_nop 0
	global_load_lds_dwordx4 v134, s[24:25]
	s_add_i32 m0, s36, 0x2000
	s_nop 0
	global_load_lds_dwordx4 v130, s[24:25]
	s_waitcnt vmcnt(6)
	s_barrier
	s_setprio 1
	v_mfma_f32_16x16x32_bf16 v[50:53], v[226:229], v[194:197], v[50:53]
	ds_read_b128 v[164:167], v249
	ds_read_b128 v[182:185], v249 offset:1024
	v_mfma_f32_16x16x32_bf16 v[50:53], v[230:233], v[198:201], v[50:53]
	ds_read_b128 v[186:189], v249 offset:2048
	ds_read_b128 v[190:193], v249 offset:3072
	v_mfma_f32_16x16x32_bf16 v[42:45], v[234:237], v[194:197], v[42:45]
	ds_read_b128 v[194:197], v162
	v_mfma_f32_16x16x32_bf16 v[42:45], v[238:241], v[198:201], v[42:45]
	ds_read_b128 v[198:201], v162 offset:1024
	v_mfma_f32_16x16x32_bf16 v[34:37], v[226:229], v[202:205], v[34:37]
	v_mfma_f32_16x16x32_bf16 v[34:37], v[230:233], v[206:209], v[34:37]
	v_mfma_f32_16x16x32_bf16 v[26:29], v[234:237], v[202:205], v[26:29]
	ds_read_b128 v[202:205], v162 offset:2048
	v_mfma_f32_16x16x32_bf16 v[26:29], v[238:241], v[206:209], v[26:29]
	ds_read_b128 v[206:209], v162 offset:3072
	v_mfma_f32_16x16x32_bf16 v[18:21], v[226:229], v[210:213], v[18:21]
	v_mfma_f32_16x16x32_bf16 v[18:21], v[230:233], v[214:217], v[18:21]
	v_mfma_f32_16x16x32_bf16 v[10:13], v[234:237], v[210:213], v[10:13]
	v_mfma_f32_16x16x32_bf16 v[10:13], v[238:241], v[214:217], v[10:13]
	v_mfma_f32_16x16x32_bf16 v[6:9], v[226:229], v[218:221], v[6:9]
	v_mfma_f32_16x16x32_bf16 v[6:9], v[230:233], v[222:225], v[6:9]
	v_mfma_f32_16x16x32_bf16 v[2:5], v[234:237], v[218:221], v[2:5]
	s_barrier
	v_mfma_f32_16x16x32_bf16 v[2:5], v[238:241], v[222:225], v[2:5]
	s_setprio 0
	s_add_i32 s38, s38, 2
	s_add_u32 s35, s35, 0x100
	s_addc_u32 s50, s50, 0
	s_add_u32 s0, s0, 0x100
	s_addc_u32 s1, s1, 0
	s_cmp_gt_u32 s38, 13
	s_cbranch_scc0 .LBB0_416
	s_waitcnt lgkmcnt(0)
	s_and_b64 vcc, exec, s[44:45]
	s_cbranch_vccz .LBB0_419
	s_barrier

; #define PG8_STAGE(bufoff, gbase, voff) do { _Pragma("unroll") for (int _i = 0; _i < 2; ++_i) \
;         __builtin_amdgcn_global_load_lds((const unsigned*)((const char*)(gbase) + (voff)[_i]), (LAS unsigned*)(lds + (bufoff) + ldsw + _i * 8192), 16, 0, 0); } while (0)
; #define PG8_LDA(dst, b, h) do { _Pragma("unroll") for (int m = 0; m < 4; ++m) _Pragma("unroll") for (int k = 0; k < 2; ++k) dst[m][k] = *(const LAS bf16x8*)(lds + PG8_SA(b, h) + aoff + m * 2048 + k * 1024); } while (0)
; #define PG8_LDB(dst, b, h) do { _Pragma("unroll") for (int n = 0; n < 2; ++n) _Pragma("unroll") for (int k = 0; k < 2; ++k) dst[n][k] = *(const LAS bf16x8*)(lds + PG8_SB(b, h) + boff + n * 2048 + k * 1024); } while (0)
; #define PG8_MMA(ai, bj, At, Bt) do { __builtin_amdgcn_s_setprio(1); _Pragma("unroll") for (int m = 0; m < 4; ++m) _Pragma("unroll") for (int n = 0; n < 2; ++n) _Pragma("unroll") for (int k = 0; k < 2; ++k) \
;         acc[ai][bj][m][n] = __builtin_amdgcn_mfma_f32_16x16x32_bf16(Bt[n][k], At[m][k], acc[ai][bj][m][n], 0, 0, 0); __builtin_amdgcn_s_setprio(0); } while (0)
; #define PG8_WAIT_L(n) asm volatile("s_waitcnt lgkmcnt(" #n ")" ::: "memory")
; template <class Epi, class Sched>
; __device__ __forceinline__ void gemm_phase(LAS unsigned char* lds, const Gemm g, const Sched& S, const Epi& E) {
;     ...
;         const bool has_next = S.next(ui + 1, nxt);
;         const char* nA = has_next ? PG8_APANEL(nxt.pm) : cA; const char* nB = has_next ? (const char*)g.Bt + (size_t)nxt.pn * tstep : cB;
;         for (int t = 0; t < nt; t += 2) {
;             const bool last = (t == nt - 2);
;             const char* a1 = cA + (size_t)(t + 1) * kstep;
;             const char* a2 = last ? nA : cA + (size_t)(t + 2) * kstep; const char* b2 = last ? nB : cB + (size_t)(t + 2) * kstep;
;             const char* a3 = a2 + kstep; const char* b3 = b2 + kstep;
;             PG8_LDB(B0, 0, 0); PG8_SCHED; PG8_LDA(At, 0, 0); PG8_STAGE(PG8_SA(1, 1), a1 + hstep, voffA);
;             PG8_WAIT_L(8); PG8_BAR; PG8_WAIT_L(0); PG8_MMA(0, 0, At, B0); PG8_BAR; PG8_SCHED;
;             PG8_LDB(B1, 0, 1); PG8_STAGE(PG8_SB(0, 0), b2, voffB);
;             PG8_BAR; PG8_WAIT_L(0); PG8_MMA(0, 1, At, B1); PG8_BAR;
;             PG8_LDA(At, 0, 1); PG8_STAGE(PG8_SA(0, 0), a2, voffA);
;             PG8_BAR; PG8_WAIT_L(0); PG8_MMA(1, 0, At, B0); PG8_BAR; PG8_SCHED;
.LBB0_556:
	s_ashr_i32 s45, s44, 31
	s_lshl_b64 s[24:25], s[44:45], 19
	s_add_u32 s60, s86, s24
	s_addc_u32 s61, s93, s25
	s_and_b64 s[0:1], s[0:1], exec
	s_cselect_b32 s45, s61, s49
	s_cselect_b32 s47, s60, s48
	s_add_u32 s35, s48, 0x100
	s_addc_u32 s50, s49, 0
	s_add_u32 s0, s38, 0x40080
	s_addc_u32 s1, s39, 0
	s_mov_b32 s38, -2
	v_add_u32_e32 v249, 0x10000, v164
	ds_read_b128 v[142:145], v249
	ds_read_b128 v[182:185], v249 offset:1024
	ds_read_b128 v[186:189], v249 offset:2048
	ds_read_b128 v[190:193], v249 offset:3072
	ds_read_b128 v[194:197], v166
	ds_read_b128 v[198:201], v166 offset:1024
	ds_read_b128 v[202:205], v166 offset:2048
	ds_read_b128 v[206:209], v166 offset:3072
	s_add_u32 s24, s0, 0xfffc0080
	s_addc_u32 s25, s1, -1
	s_add_i32 s39, 0, 0x10000
	s_cmp_eq_u32 s38, 12
	s_cselect_b32 vcc_hi, s77, s25
	s_cselect_b32 vcc_lo, s76, s24
	s_cselect_b32 s49, s45, s50
	s_cselect_b32 s48, s47, s35
	s_add_i32 m0, s95, 0xc000
	ds_read_b128 v[210:213], v166 offset:4096
	ds_read_b128 v[214:217], v166 offset:5120
	ds_read_b128 v[218:221], v166 offset:6144
	ds_read_b128 v[222:225], v166 offset:7168
	global_load_lds_dwordx4 v140, s[0:1]
	s_add_i32 m0, s95, 0xe000
	s_nop 0
	global_load_lds_dwordx4 v138, s[0:1]
	s_waitcnt lgkmcnt(8)
	s_barrier
	s_waitcnt lgkmcnt(0)
	s_setprio 1
	s_waitcnt lgkmcnt(0)
	v_mfma_f32_16x16x32_bf16 v[126:129], v[142:145], v[194:197], 0
	v_mfma_f32_16x16x32_bf16 v[126:129], v[182:185], v[198:201], v[126:129]
	v_mfma_f32_16x16x32_bf16 v[122:125], v[186:189], v[194:197], 0
	v_mfma_f32_16x16x32_bf16 v[122:125], v[190:193], v[198:201], v[122:125]
	v_mfma_f32_16x16x32_bf16 v[110:113], v[142:145], v[202:205], 0
	v_mfma_f32_16x16x32_bf16 v[110:113], v[182:185], v[206:209], v[110:113]
	v_mfma_f32_16x16x32_bf16 v[106:109], v[186:189], v[202:205], 0
	v_mfma_f32_16x16x32_bf16 v[106:109], v[190:193], v[206:209], v[106:109]
	v_mfma_f32_16x16x32_bf16 v[94:97], v[142:145], v[210:213], 0
	v_mfma_f32_16x16x32_bf16 v[94:97], v[182:185], v[214:217], v[94:97]
	v_mfma_f32_16x16x32_bf16 v[90:93], v[186:189], v[210:213], 0
	v_mfma_f32_16x16x32_bf16 v[90:93], v[190:193], v[214:217], v[90:93]
	v_mfma_f32_16x16x32_bf16 v[78:81], v[142:145], v[218:221], 0
	v_mfma_f32_16x16x32_bf16 v[78:81], v[182:185], v[222:225], v[78:81]
	v_mfma_f32_16x16x32_bf16 v[74:77], v[186:189], v[218:221], 0
	s_barrier
	v_mfma_f32_16x16x32_bf16 v[74:77], v[190:193], v[222:225], v[74:77]
	s_setprio 0
	s_add_i32 s51, 0, 0x14000
	s_add_i32 s24, s39, s94
	ds_read_b128 v[226:229], v249 offset:16384
	ds_read_b128 v[230:233], v249 offset:17408
	ds_read_b128 v[234:237], v249 offset:18432
	ds_read_b128 v[238:241], v249 offset:19456
	s_mov_b32 m0, s24
	global_load_lds_dwordx4 v134, s[48:49]
	s_add_i32 m0, s24, 0x2000
	s_nop 0
	global_load_lds_dwordx4 v130, s[48:49]
	s_barrier
	s_waitcnt lgkmcnt(0)
	s_setprio 1
	s_waitcnt lgkmcnt(0)
	v_mfma_f32_16x16x32_bf16 v[118:121], v[226:229], v[194:197], 0
	v_mfma_f32_16x16x32_bf16 v[118:121], v[230:233], v[198:201], v[118:121]
	v_mfma_f32_16x16x32_bf16 v[114:117], v[234:237], v[194:197], 0
	v_mfma_f32_16x16x32_bf16 v[114:117], v[238:241], v[198:201], v[114:117]
	v_mfma_f32_16x16x32_bf16 v[102:105], v[226:229], v[202:205], 0
	v_mfma_f32_16x16x32_bf16 v[102:105], v[230:233], v[206:209], v[102:105]
	v_mfma_f32_16x16x32_bf16 v[98:101], v[234:237], v[202:205], 0
	v_mfma_f32_16x16x32_bf16 v[98:101], v[238:241], v[206:209], v[98:101]
	v_mfma_f32_16x16x32_bf16 v[86:89], v[226:229], v[210:213], 0
	v_mfma_f32_16x16x32_bf16 v[86:89], v[230:233], v[214:217], v[86:89]
	v_mfma_f32_16x16x32_bf16 v[82:85], v[234:237], v[210:213], 0
	v_mfma_f32_16x16x32_bf16 v[82:85], v[238:241], v[214:217], v[82:85]
	v_mfma_f32_16x16x32_bf16 v[70:73], v[226:229], v[218:221], 0
	v_mfma_f32_16x16x32_bf16 v[70:73], v[230:233], v[222:225], v[70:73]
	v_mfma_f32_16x16x32_bf16 v[66:69], v[234:237], v[218:221], 0
	s_barrier
	v_mfma_f32_16x16x32_bf16 v[66:69], v[238:241], v[222:225], v[66:69]
	s_setprio 0
	s_mov_b32 m0, s95
	ds_read_b128 v[194:197], v166 offset:16384
	ds_read_b128 v[198:201], v166 offset:17408
	ds_read_b128 v[202:205], v166 offset:18432
	ds_read_b128 v[206:209], v166 offset:19456
	ds_read_b128 v[210:213], v166 offset:20480
	ds_read_b128 v[214:217], v166 offset:21504
	ds_read_b128 v[218:221], v166 offset:22528
	ds_read_b128 v[222:225], v166 offset:23552
	global_load_lds_dwordx4 v136, vcc
	s_mov_b32 m0, s96
	s_nop 0
	global_load_lds_dwordx4 v132, vcc
	s_waitcnt vmcnt(8)
	s_barrier
	s_waitcnt lgkmcnt(0)
	s_setprio 1
	s_waitcnt lgkmcnt(0)
	v_mfma_f32_16x16x32_bf16 v[62:65], v[142:145], v[194:197], 0
	v_mfma_f32_16x16x32_bf16 v[62:65], v[182:185], v[198:201], v[62:65]
	v_mfma_f32_16x16x32_bf16 v[58:61], v[186:189], v[194:197], 0
	v_mfma_f32_16x16x32_bf16 v[58:61], v[190:193], v[198:201], v[58:61]
	v_mfma_f32_16x16x32_bf16 v[46:49], v[142:145], v[202:205], 0
	v_mfma_f32_16x16x32_bf16 v[46:49], v[182:185], v[206:209], v[46:49]
	v_mfma_f32_16x16x32_bf16 v[42:45], v[186:189], v[202:205], 0
	v_mfma_f32_16x16x32_bf16 v[42:45], v[190:193], v[206:209], v[42:45]
	v_mfma_f32_16x16x32_bf16 v[30:33], v[142:145], v[210:213], 0
	v_mfma_f32_16x16x32_bf16 v[30:33], v[182:185], v[214:217], v[30:33]
	v_mfma_f32_16x16x32_bf16 v[26:29], v[186:189], v[210:213], 0
	v_mfma_f32_16x16x32_bf16 v[26:29], v[190:193], v[214:217], v[26:29]
	v_mfma_f32_16x16x32_bf16 v[14:17], v[142:145], v[218:221], 0
	v_mfma_f32_16x16x32_bf16 v[14:17], v[182:185], v[222:225], v[14:17]
	v_mfma_f32_16x16x32_bf16 v[10:13], v[186:189], v[218:221], 0
	s_barrier
; #define PG8_STAGE(bufoff, gbase, voff) do { _Pragma("unroll") for (int _i = 0; _i < 2; ++_i) \
;         __builtin_amdgcn_global_load_lds((const unsigned*)((const char*)(gbase) + (voff)[_i]), (LAS unsigned*)(lds + (bufoff) + ldsw + _i * 8192), 16, 0, 0); } while (0)
; #define PG8_LDA(dst, b, h) do { _Pragma("unroll") for (int m = 0; m < 4; ++m) _Pragma("unroll") for (int k = 0; k < 2; ++k) dst[m][k] = *(const LAS bf16x8*)(lds + PG8_SA(b, h) + aoff + m * 2048 + k * 1024); } while (0)
; #define PG8_LDB(dst, b, h) do { _Pragma("unroll") for (int n = 0; n < 2; ++n) _Pragma("unroll") for (int k = 0; k < 2; ++k) dst[n][k] = *(const LAS bf16x8*)(lds + PG8_SB(b, h) + boff + n * 2048 + k * 1024); } while (0)
; #define PG8_MMA(ai, bj, At, Bt) do { __builtin_amdgcn_s_setprio(1); _Pragma("unroll") for (int m = 0; m < 4; ++m) _Pragma("unroll") for (int n = 0; n < 2; ++n) _Pragma("unroll") for (int k = 0; k < 2; ++k) \
;         acc[ai][bj][m][n] = __builtin_amdgcn_mfma_f32_16x16x32_bf16(Bt[n][k], At[m][k], acc[ai][bj][m][n], 0, 0, 0); __builtin_amdgcn_s_setprio(0); } while (0)
; #define PG8_WAIT_V(n) asm volatile("s_waitcnt vmcnt(" #n ")" ::: "memory")
; #define PG8_WAIT_L(n) asm volatile("s_waitcnt lgkmcnt(" #n ")" ::: "memory")
; #define PG8_BAR __builtin_amdgcn_s_barrier()
; #define PG8_SCHED __builtin_amdgcn_sched_barrier(0)
; template <class Epi, class Sched>
; __device__ __forceinline__ void gemm_phase(LAS unsigned char* lds, const Gemm g, const Sched& S, const Epi& E) {
;     ...
;             PG8_BAR; PG8_WAIT_L(0); PG8_MMA(1, 0, At, B0); PG8_BAR; PG8_SCHED;
;             PG8_STAGE(PG8_SB(0, 1), b2 + hstep, voffB);
;             PG8_WAIT_V(6); PG8_BAR; PG8_MMA(1, 1, At, B1); PG8_BAR;
;             PG8_LDB(B0, 1, 0); PG8_SCHED; PG8_LDA(At, 1, 0); PG8_STAGE(PG8_SA(0, 1), a2 + hstep, voffA);
;             PG8_WAIT_L(8); PG8_BAR; PG8_WAIT_L(0); PG8_MMA(0, 0, At, B0); PG8_BAR; PG8_SCHED;
;             PG8_LDB(B1, 1, 1); PG8_STAGE(PG8_SB(1, 0), b3, voffB);
;             PG8_BAR; PG8_WAIT_L(0); PG8_MMA(0, 1, At, B1); PG8_BAR;
;             PG8_LDA(At, 1, 1); PG8_STAGE(PG8_SA(1, 0), a3, voffA);
	v_mfma_f32_16x16x32_bf16 v[10:13], v[190:193], v[222:225], v[10:13]
	s_setprio 0
	s_add_u32 s24, s48, 0x40000
	s_addc_u32 s25, s49, 0
	s_add_i32 s39, s51, s94
	s_mov_b32 m0, s39
	s_nop 0
	global_load_lds_dwordx4 v134, s[24:25]
	s_add_i32 m0, s39, 0x2000
	s_nop 0
	global_load_lds_dwordx4 v130, s[24:25]
	s_waitcnt vmcnt(6)
	s_barrier
	s_setprio 1
	v_mfma_f32_16x16x32_bf16 v[54:57], v[226:229], v[194:197], 0
	ds_read_b128 v[142:145], v249 offset:32768
	ds_read_b128 v[182:185], v249 offset:33792
	v_mfma_f32_16x16x32_bf16 v[54:57], v[230:233], v[198:201], v[54:57]
	ds_read_b128 v[186:189], v249 offset:34816
	ds_read_b128 v[190:193], v249 offset:35840
	v_mfma_f32_16x16x32_bf16 v[50:53], v[234:237], v[194:197], 0
	ds_read_b128 v[194:197], v166 offset:32768
	v_mfma_f32_16x16x32_bf16 v[50:53], v[238:241], v[198:201], v[50:53]
	ds_read_b128 v[198:201], v166 offset:33792
	v_mfma_f32_16x16x32_bf16 v[38:41], v[226:229], v[202:205], 0
	v_mfma_f32_16x16x32_bf16 v[38:41], v[230:233], v[206:209], v[38:41]
	v_mfma_f32_16x16x32_bf16 v[34:37], v[234:237], v[202:205], 0
	ds_read_b128 v[202:205], v166 offset:34816
	v_mfma_f32_16x16x32_bf16 v[34:37], v[238:241], v[206:209], v[34:37]
	ds_read_b128 v[206:209], v166 offset:35840
	v_mfma_f32_16x16x32_bf16 v[22:25], v[226:229], v[210:213], 0
	v_mfma_f32_16x16x32_bf16 v[22:25], v[230:233], v[214:217], v[22:25]
	v_mfma_f32_16x16x32_bf16 v[18:21], v[234:237], v[210:213], 0
	v_mfma_f32_16x16x32_bf16 v[18:21], v[238:241], v[214:217], v[18:21]
	v_mfma_f32_16x16x32_bf16 v[6:9], v[226:229], v[218:221], 0
	v_mfma_f32_16x16x32_bf16 v[6:9], v[230:233], v[222:225], v[6:9]
	v_mfma_f32_16x16x32_bf16 v[2:5], v[234:237], v[218:221], 0
	s_barrier
	v_mfma_f32_16x16x32_bf16 v[2:5], v[238:241], v[222:225], v[2:5]
	s_setprio 0
	s_add_i32 s39, 0, 0x18000
	s_add_u32 s24, vcc_lo, 0x40000
	s_addc_u32 s25, vcc_hi, 0
	s_mov_b32 m0, s97
	ds_read_b128 v[210:213], v166 offset:36864
	ds_read_b128 v[214:217], v166 offset:37888
	ds_read_b128 v[218:221], v166 offset:38912
	ds_read_b128 v[222:225], v166 offset:39936
	global_load_lds_dwordx4 v136, s[24:25]
	s_mov_b32 m0, s98
	s_nop 0
	global_load_lds_dwordx4 v132, s[24:25]
	s_waitcnt lgkmcnt(8)
	s_barrier
	s_waitcnt lgkmcnt(0)
	s_setprio 1
	s_waitcnt lgkmcnt(0)
	v_mfma_f32_16x16x32_bf16 v[126:129], v[142:145], v[194:197], v[126:129]
	v_mfma_f32_16x16x32_bf16 v[126:129], v[182:185], v[198:201], v[126:129]
	v_mfma_f32_16x16x32_bf16 v[122:125], v[186:189], v[194:197], v[122:125]
	v_mfma_f32_16x16x32_bf16 v[122:125], v[190:193], v[198:201], v[122:125]
	v_mfma_f32_16x16x32_bf16 v[110:113], v[142:145], v[202:205], v[110:113]
	v_mfma_f32_16x16x32_bf16 v[110:113], v[182:185], v[206:209], v[110:113]
	v_mfma_f32_16x16x32_bf16 v[106:109], v[186:189], v[202:205], v[106:109]
	v_mfma_f32_16x16x32_bf16 v[106:109], v[190:193], v[206:209], v[106:109]
	v_mfma_f32_16x16x32_bf16 v[94:97], v[142:145], v[210:213], v[94:97]
	v_mfma_f32_16x16x32_bf16 v[94:97], v[182:185], v[214:217], v[94:97]
	v_mfma_f32_16x16x32_bf16 v[90:93], v[186:189], v[210:213], v[90:93]
	v_mfma_f32_16x16x32_bf16 v[90:93], v[190:193], v[214:217], v[90:93]
	v_mfma_f32_16x16x32_bf16 v[78:81], v[142:145], v[218:221], v[78:81]
	v_mfma_f32_16x16x32_bf16 v[78:81], v[182:185], v[222:225], v[78:81]
	v_mfma_f32_16x16x32_bf16 v[74:77], v[186:189], v[218:221], v[74:77]
	s_barrier
	v_mfma_f32_16x16x32_bf16 v[74:77], v[190:193], v[222:225], v[74:77]
	s_setprio 0
	s_add_i32 s51, 0, 0x1c000
	s_add_i32 s24, s39, s94
	s_add_i32 m0, s24, 0xffffff80
	ds_read_b128 v[226:229], v249 offset:49152
	ds_read_b128 v[230:233], v249 offset:50176
	ds_read_b128 v[234:237], v249 offset:51200
	ds_read_b128 v[238:241], v249 offset:52224
	global_load_lds_dwordx4 v134, s[48:49] offset:128
	s_add_i32 m0, s24, 0x1f80
	s_nop 0
	global_load_lds_dwordx4 v130, s[48:49] offset:128
	s_barrier
	s_waitcnt lgkmcnt(0)
	s_setprio 1
	s_waitcnt lgkmcnt(0)
	v_mfma_f32_16x16x32_bf16 v[118:121], v[226:229], v[194:197], v[118:121]
	v_mfma_f32_16x16x32_bf16 v[118:121], v[230:233], v[198:201], v[118:121]
	v_mfma_f32_16x16x32_bf16 v[114:117], v[234:237], v[194:197], v[114:117]
	v_mfma_f32_16x16x32_bf16 v[114:117], v[238:241], v[198:201], v[114:117]
	v_mfma_f32_16x16x32_bf16 v[102:105], v[226:229], v[202:205], v[102:105]
	v_mfma_f32_16x16x32_bf16 v[102:105], v[230:233], v[206:209], v[102:105]
	v_mfma_f32_16x16x32_bf16 v[98:101], v[234:237], v[202:205], v[98:101]
	v_mfma_f32_16x16x32_bf16 v[98:101], v[238:241], v[206:209], v[98:101]
	v_mfma_f32_16x16x32_bf16 v[86:89], v[226:229], v[210:213], v[86:89]
	v_mfma_f32_16x16x32_bf16 v[86:89], v[230:233], v[214:217], v[86:89]
	v_mfma_f32_16x16x32_bf16 v[82:85], v[234:237], v[210:213], v[82:85]
	v_mfma_f32_16x16x32_bf16 v[82:85], v[238:241], v[214:217], v[82:85]
	v_mfma_f32_16x16x32_bf16 v[70:73], v[226:229], v[218:221], v[70:73]
	v_mfma_f32_16x16x32_bf16 v[70:73], v[230:233], v[222:225], v[70:73]
	v_mfma_f32_16x16x32_bf16 v[66:69], v[234:237], v[218:221], v[66:69]
	s_barrier
	v_mfma_f32_16x16x32_bf16 v[66:69], v[238:241], v[222:225], v[66:69]
	s_setprio 0
	s_add_i32 m0, s99, 0xffffff80
	ds_read_b128 v[194:197], v166 offset:49152
	ds_read_b128 v[198:201], v166 offset:50176
	ds_read_b128 v[202:205], v166 offset:51200
	ds_read_b128 v[206:209], v166 offset:52224
	ds_read_b128 v[210:213], v166 offset:53248
	ds_read_b128 v[214:217], v166 offset:54272
	ds_read_b128 v[218:221], v166 offset:55296
	ds_read_b128 v[222:225], v166 offset:56320
	global_load_lds_dwordx4 v136, vcc offset:128
	s_add_i32 m0, s82, 0xffffff80
	s_nop 0
	global_load_lds_dwordx4 v132, vcc offset:128
	s_waitcnt vmcnt(8)
	s_barrier
; #define PG8_STAGE(bufoff, gbase, voff) do { _Pragma("unroll") for (int _i = 0; _i < 2; ++_i) \
;         __builtin_amdgcn_global_load_lds((const unsigned*)((const char*)(gbase) + (voff)[_i]), (LAS unsigned*)(lds + (bufoff) + ldsw + _i * 8192), 16, 0, 0); } while (0)
; #define PG8_LDA(dst, b, h) do { _Pragma("unroll") for (int m = 0; m < 4; ++m) _Pragma("unroll") for (int k = 0; k < 2; ++k) dst[m][k] = *(const LAS bf16x8*)(lds + PG8_SA(b, h) + aoff + m * 2048 + k * 1024); } while (0)
; #define PG8_LDB(dst, b, h) do { _Pragma("unroll") for (int n = 0; n < 2; ++n) _Pragma("unroll") for (int k = 0; k < 2; ++k) dst[n][k] = *(const LAS bf16x8*)(lds + PG8_SB(b, h) + boff + n * 2048 + k * 1024); } while (0)
; #define PG8_WAIT_V(n) asm volatile("s_waitcnt vmcnt(" #n ")" ::: "memory")
; #define PG8_WAIT_L(n) asm volatile("s_waitcnt lgkmcnt(" #n ")" ::: "memory")
; #define PG8_BAR __builtin_amdgcn_s_barrier()
; #define PG8_SCHED __builtin_amdgcn_sched_barrier(0)
; template <class Epi, class Sched>
; __device__ __forceinline__ void gemm_phase(LAS unsigned char* lds, const Gemm g, const Sched& S, const Epi& E) {
;     ...
;             PG8_LDB(B0, 0, 0); PG8_SCHED; PG8_LDA(At, 0, 0); PG8_STAGE(PG8_SA(1, 1), a1 + hstep, voffA);
;             PG8_WAIT_L(8); PG8_BAR; PG8_WAIT_L(0); PG8_MMA(0, 0, At, B0); PG8_BAR; PG8_SCHED;
;             PG8_LDB(B1, 0, 1); PG8_STAGE(PG8_SB(0, 0), b2, voffB);
;             PG8_BAR; PG8_WAIT_L(0); PG8_MMA(0, 1, At, B1); PG8_BAR;
;             PG8_LDA(At, 0, 1); PG8_STAGE(PG8_SA(0, 0), a2, voffA);
;             PG8_BAR; PG8_WAIT_L(0); PG8_MMA(1, 0, At, B0); PG8_BAR; PG8_SCHED;
;             PG8_STAGE(PG8_SB(0, 1), b2 + hstep, voffB);
;             PG8_WAIT_V(6); PG8_BAR; PG8_MMA(1, 1, At, B1); PG8_BAR;
;             PG8_LDB(B0, 1, 0); PG8_SCHED; PG8_LDA(At, 1, 0); PG8_STAGE(PG8_SA(0, 1), a2 + hstep, voffA);
;             PG8_WAIT_L(8); PG8_BAR; PG8_WAIT_L(0); PG8_MMA(0, 0, At, B0); PG8_BAR; PG8_SCHED;
;             PG8_LDB(B1, 1, 1); PG8_STAGE(PG8_SB(1, 0), b3, voffB);
;             PG8_BAR; PG8_WAIT_L(0); PG8_MMA(0, 1, At, B1); PG8_BAR;
;             PG8_LDA(At, 1, 1); PG8_STAGE(PG8_SA(1, 0), a3, voffA);
;             PG8_BAR; PG8_WAIT_L(0); PG8_MMA(1, 0, At, B0); PG8_BAR; PG8_SCHED;
;             PG8_STAGE(PG8_SB(1, 1), b3 + hstep, voffB);
;             PG8_WAIT_V(6); PG8_BAR; PG8_MMA(1, 1, At, B1); PG8_BAR;
	s_waitcnt lgkmcnt(0)
	s_setprio 1
	s_waitcnt lgkmcnt(0)
	v_mfma_f32_16x16x32_bf16 v[62:65], v[142:145], v[194:197], v[62:65]
	v_mfma_f32_16x16x32_bf16 v[62:65], v[182:185], v[198:201], v[62:65]
	v_mfma_f32_16x16x32_bf16 v[58:61], v[186:189], v[194:197], v[58:61]
	v_mfma_f32_16x16x32_bf16 v[58:61], v[190:193], v[198:201], v[58:61]
	v_mfma_f32_16x16x32_bf16 v[46:49], v[142:145], v[202:205], v[46:49]
	v_mfma_f32_16x16x32_bf16 v[46:49], v[182:185], v[206:209], v[46:49]
	v_mfma_f32_16x16x32_bf16 v[42:45], v[186:189], v[202:205], v[42:45]
	v_mfma_f32_16x16x32_bf16 v[42:45], v[190:193], v[206:209], v[42:45]
	v_mfma_f32_16x16x32_bf16 v[30:33], v[142:145], v[210:213], v[30:33]
	v_mfma_f32_16x16x32_bf16 v[30:33], v[182:185], v[214:217], v[30:33]
	v_mfma_f32_16x16x32_bf16 v[26:29], v[186:189], v[210:213], v[26:29]
	v_mfma_f32_16x16x32_bf16 v[26:29], v[190:193], v[214:217], v[26:29]
	v_mfma_f32_16x16x32_bf16 v[14:17], v[142:145], v[218:221], v[14:17]
	v_mfma_f32_16x16x32_bf16 v[14:17], v[182:185], v[222:225], v[14:17]
	v_mfma_f32_16x16x32_bf16 v[10:13], v[186:189], v[218:221], v[10:13]
	s_barrier
	v_mfma_f32_16x16x32_bf16 v[10:13], v[190:193], v[222:225], v[10:13]
	s_setprio 0
	s_add_u32 s24, s48, 0x40080
	s_addc_u32 s25, s49, 0
	s_add_i32 s39, s51, s94
	s_mov_b32 m0, s39
	s_nop 0
	global_load_lds_dwordx4 v134, s[24:25]
	s_add_i32 m0, s39, 0x2000
	s_nop 0
	global_load_lds_dwordx4 v130, s[24:25]
	s_waitcnt vmcnt(6)
	s_barrier
	s_setprio 1
	v_mfma_f32_16x16x32_bf16 v[54:57], v[226:229], v[194:197], v[54:57]
	ds_read_b128 v[142:145], v249
	ds_read_b128 v[182:185], v249 offset:1024
	v_mfma_f32_16x16x32_bf16 v[54:57], v[230:233], v[198:201], v[54:57]
	ds_read_b128 v[186:189], v249 offset:2048
	ds_read_b128 v[190:193], v249 offset:3072
	v_mfma_f32_16x16x32_bf16 v[50:53], v[234:237], v[194:197], v[50:53]
	ds_read_b128 v[194:197], v166
	v_mfma_f32_16x16x32_bf16 v[50:53], v[238:241], v[198:201], v[50:53]
	ds_read_b128 v[198:201], v166 offset:1024
	v_mfma_f32_16x16x32_bf16 v[38:41], v[226:229], v[202:205], v[38:41]
	v_mfma_f32_16x16x32_bf16 v[38:41], v[230:233], v[206:209], v[38:41]
	v_mfma_f32_16x16x32_bf16 v[34:37], v[234:237], v[202:205], v[34:37]
	ds_read_b128 v[202:205], v166 offset:2048
	v_mfma_f32_16x16x32_bf16 v[34:37], v[238:241], v[206:209], v[34:37]
	ds_read_b128 v[206:209], v166 offset:3072
	v_mfma_f32_16x16x32_bf16 v[22:25], v[226:229], v[210:213], v[22:25]
	v_mfma_f32_16x16x32_bf16 v[22:25], v[230:233], v[214:217], v[22:25]
	v_mfma_f32_16x16x32_bf16 v[18:21], v[234:237], v[210:213], v[18:21]
	v_mfma_f32_16x16x32_bf16 v[18:21], v[238:241], v[214:217], v[18:21]
	v_mfma_f32_16x16x32_bf16 v[6:9], v[226:229], v[218:221], v[6:9]
	v_mfma_f32_16x16x32_bf16 v[6:9], v[230:233], v[222:225], v[6:9]
	v_mfma_f32_16x16x32_bf16 v[2:5], v[234:237], v[218:221], v[2:5]
	s_barrier
	v_mfma_f32_16x16x32_bf16 v[2:5], v[238:241], v[222:225], v[2:5]
	s_setprio 0
	s_add_i32 s38, s38, 2
	s_add_u32 s35, s35, 0x100
	s_addc_u32 s50, s50, 0
	s_add_u32 s0, s0, 0x100
	s_addc_u32 s1, s1, 0
	s_cmp_gt_u32 s38, 13
.LBB0_557:
	s_add_u32 s24, s0, 0xfffc0080
	s_addc_u32 s25, s1, -1
	s_add_i32 s39, 0, 0x10000
	s_cmp_eq_u32 s38, 12
	s_cselect_b32 vcc_hi, s77, s25
	s_cselect_b32 vcc_lo, s76, s24
	s_cselect_b32 s49, s45, s50
	s_cselect_b32 s48, s47, s35
	s_add_i32 m0, s95, 0xc000
	ds_read_b128 v[210:213], v166 offset:4096
	ds_read_b128 v[214:217], v166 offset:5120
	ds_read_b128 v[218:221], v166 offset:6144
	ds_read_b128 v[222:225], v166 offset:7168
	global_load_lds_dwordx4 v140, s[0:1]
	s_add_i32 m0, s95, 0xe000
	s_nop 0
	global_load_lds_dwordx4 v138, s[0:1]
	s_waitcnt lgkmcnt(8)
	s_barrier
	s_waitcnt lgkmcnt(0)
	s_setprio 1
	s_waitcnt lgkmcnt(0)
	v_mfma_f32_16x16x32_bf16 v[126:129], v[142:145], v[194:197], v[126:129]
	v_mfma_f32_16x16x32_bf16 v[126:129], v[182:185], v[198:201], v[126:129]
	v_mfma_f32_16x16x32_bf16 v[122:125], v[186:189], v[194:197], v[122:125]
	v_mfma_f32_16x16x32_bf16 v[122:125], v[190:193], v[198:201], v[122:125]
	v_mfma_f32_16x16x32_bf16 v[110:113], v[142:145], v[202:205], v[110:113]
	v_mfma_f32_16x16x32_bf16 v[110:113], v[182:185], v[206:209], v[110:113]
	v_mfma_f32_16x16x32_bf16 v[106:109], v[186:189], v[202:205], v[106:109]
	v_mfma_f32_16x16x32_bf16 v[106:109], v[190:193], v[206:209], v[106:109]
	v_mfma_f32_16x16x32_bf16 v[94:97], v[142:145], v[210:213], v[94:97]
	v_mfma_f32_16x16x32_bf16 v[94:97], v[182:185], v[214:217], v[94:97]
	v_mfma_f32_16x16x32_bf16 v[90:93], v[186:189], v[210:213], v[90:93]
	v_mfma_f32_16x16x32_bf16 v[90:93], v[190:193], v[214:217], v[90:93]
	v_mfma_f32_16x16x32_bf16 v[78:81], v[142:145], v[218:221], v[78:81]
	v_mfma_f32_16x16x32_bf16 v[78:81], v[182:185], v[222:225], v[78:81]
	v_mfma_f32_16x16x32_bf16 v[74:77], v[186:189], v[218:221], v[74:77]
	s_barrier
	v_mfma_f32_16x16x32_bf16 v[74:77], v[190:193], v[222:225], v[74:77]
	s_setprio 0
	s_add_i32 s51, 0, 0x14000
	s_add_i32 s24, s39, s94
	ds_read_b128 v[226:229], v249 offset:16384
	ds_read_b128 v[230:233], v249 offset:17408
	ds_read_b128 v[234:237], v249 offset:18432
	ds_read_b128 v[238:241], v249 offset:19456
	s_mov_b32 m0, s24
	global_load_lds_dwordx4 v134, s[48:49]
	s_add_i32 m0, s24, 0x2000
	s_nop 0
	global_load_lds_dwordx4 v130, s[48:49]
	s_barrier
; #define PG8_STAGE(bufoff, gbase, voff) do { _Pragma("unroll") for (int _i = 0; _i < 2; ++_i) \
;         __builtin_amdgcn_global_load_lds((const unsigned*)((const char*)(gbase) + (voff)[_i]), (LAS unsigned*)(lds + (bufoff) + ldsw + _i * 8192), 16, 0, 0); } while (0)
; #define PG8_LDA(dst, b, h) do { _Pragma("unroll") for (int m = 0; m < 4; ++m) _Pragma("unroll") for (int k = 0; k < 2; ++k) dst[m][k] = *(const LAS bf16x8*)(lds + PG8_SA(b, h) + aoff + m * 2048 + k * 1024); } while (0)
; #define PG8_LDB(dst, b, h) do { _Pragma("unroll") for (int n = 0; n < 2; ++n) _Pragma("unroll") for (int k = 0; k < 2; ++k) dst[n][k] = *(const LAS bf16x8*)(lds + PG8_SB(b, h) + boff + n * 2048 + k * 1024); } while (0)
; #define PG8_MMA(ai, bj, At, Bt) do { __builtin_amdgcn_s_setprio(1); _Pragma("unroll") for (int m = 0; m < 4; ++m) _Pragma("unroll") for (int n = 0; n < 2; ++n) _Pragma("unroll") for (int k = 0; k < 2; ++k) \
;         acc[ai][bj][m][n] = __builtin_amdgcn_mfma_f32_16x16x32_bf16(Bt[n][k], At[m][k], acc[ai][bj][m][n], 0, 0, 0); __builtin_amdgcn_s_setprio(0); } while (0)
; #define PG8_WAIT_V(n) asm volatile("s_waitcnt vmcnt(" #n ")" ::: "memory")
; #define PG8_WAIT_L(n) asm volatile("s_waitcnt lgkmcnt(" #n ")" ::: "memory")
; #define PG8_BAR __builtin_amdgcn_s_barrier()
; #define PG8_SCHED __builtin_amdgcn_sched_barrier(0)
; template <class Epi, class Sched>
; __device__ __forceinline__ void gemm_phase(LAS unsigned char* lds, const Gemm g, const Sched& S, const Epi& E) {
;     ...
;             PG8_BAR; PG8_WAIT_L(0); PG8_MMA(0, 1, At, B1); PG8_BAR;
;             PG8_LDA(At, 0, 1); PG8_STAGE(PG8_SA(0, 0), a2, voffA);
;             PG8_BAR; PG8_WAIT_L(0); PG8_MMA(1, 0, At, B0); PG8_BAR; PG8_SCHED;
;             PG8_STAGE(PG8_SB(0, 1), b2 + hstep, voffB);
;             PG8_WAIT_V(6); PG8_BAR; PG8_MMA(1, 1, At, B1); PG8_BAR;
;             PG8_LDB(B0, 1, 0); PG8_SCHED; PG8_LDA(At, 1, 0); PG8_STAGE(PG8_SA(0, 1), a2 + hstep, voffA);
;             PG8_WAIT_L(8); PG8_BAR; PG8_WAIT_L(0); PG8_MMA(0, 0, At, B0); PG8_BAR; PG8_SCHED;
	s_waitcnt lgkmcnt(0)
	s_setprio 1
	s_waitcnt lgkmcnt(0)
	v_mfma_f32_16x16x32_bf16 v[118:121], v[226:229], v[194:197], v[118:121]
	v_mfma_f32_16x16x32_bf16 v[118:121], v[230:233], v[198:201], v[118:121]
	v_mfma_f32_16x16x32_bf16 v[114:117], v[234:237], v[194:197], v[114:117]
	v_mfma_f32_16x16x32_bf16 v[114:117], v[238:241], v[198:201], v[114:117]
	v_mfma_f32_16x16x32_bf16 v[102:105], v[226:229], v[202:205], v[102:105]
	v_mfma_f32_16x16x32_bf16 v[102:105], v[230:233], v[206:209], v[102:105]
	v_mfma_f32_16x16x32_bf16 v[98:101], v[234:237], v[202:205], v[98:101]
	v_mfma_f32_16x16x32_bf16 v[98:101], v[238:241], v[206:209], v[98:101]
	v_mfma_f32_16x16x32_bf16 v[86:89], v[226:229], v[210:213], v[86:89]
	v_mfma_f32_16x16x32_bf16 v[86:89], v[230:233], v[214:217], v[86:89]
	v_mfma_f32_16x16x32_bf16 v[82:85], v[234:237], v[210:213], v[82:85]
	v_mfma_f32_16x16x32_bf16 v[82:85], v[238:241], v[214:217], v[82:85]
	v_mfma_f32_16x16x32_bf16 v[70:73], v[226:229], v[218:221], v[70:73]
	v_mfma_f32_16x16x32_bf16 v[70:73], v[230:233], v[222:225], v[70:73]
	v_mfma_f32_16x16x32_bf16 v[66:69], v[234:237], v[218:221], v[66:69]
	s_barrier
	v_mfma_f32_16x16x32_bf16 v[66:69], v[238:241], v[222:225], v[66:69]
	s_setprio 0
	s_mov_b32 m0, s95
	ds_read_b128 v[194:197], v166 offset:16384
	ds_read_b128 v[198:201], v166 offset:17408
	ds_read_b128 v[202:205], v166 offset:18432
	ds_read_b128 v[206:209], v166 offset:19456
	ds_read_b128 v[210:213], v166 offset:20480
	ds_read_b128 v[214:217], v166 offset:21504
	ds_read_b128 v[218:221], v166 offset:22528
	ds_read_b128 v[222:225], v166 offset:23552
	global_load_lds_dwordx4 v136, vcc
	s_mov_b32 m0, s96
	s_nop 0
	global_load_lds_dwordx4 v132, vcc
	s_waitcnt vmcnt(8)
	s_barrier
	s_waitcnt lgkmcnt(0)
	s_setprio 1
	s_waitcnt lgkmcnt(0)
	v_mfma_f32_16x16x32_bf16 v[62:65], v[142:145], v[194:197], v[62:65]
	v_mfma_f32_16x16x32_bf16 v[62:65], v[182:185], v[198:201], v[62:65]
	v_mfma_f32_16x16x32_bf16 v[58:61], v[186:189], v[194:197], v[58:61]
	v_mfma_f32_16x16x32_bf16 v[58:61], v[190:193], v[198:201], v[58:61]
	v_mfma_f32_16x16x32_bf16 v[46:49], v[142:145], v[202:205], v[46:49]
	v_mfma_f32_16x16x32_bf16 v[46:49], v[182:185], v[206:209], v[46:49]
	v_mfma_f32_16x16x32_bf16 v[42:45], v[186:189], v[202:205], v[42:45]
	v_mfma_f32_16x16x32_bf16 v[42:45], v[190:193], v[206:209], v[42:45]
	v_mfma_f32_16x16x32_bf16 v[30:33], v[142:145], v[210:213], v[30:33]
	v_mfma_f32_16x16x32_bf16 v[30:33], v[182:185], v[214:217], v[30:33]
	v_mfma_f32_16x16x32_bf16 v[26:29], v[186:189], v[210:213], v[26:29]
	v_mfma_f32_16x16x32_bf16 v[26:29], v[190:193], v[214:217], v[26:29]
	v_mfma_f32_16x16x32_bf16 v[14:17], v[142:145], v[218:221], v[14:17]
	v_mfma_f32_16x16x32_bf16 v[14:17], v[182:185], v[222:225], v[14:17]
	v_mfma_f32_16x16x32_bf16 v[10:13], v[186:189], v[218:221], v[10:13]
	s_barrier
	v_mfma_f32_16x16x32_bf16 v[10:13], v[190:193], v[222:225], v[10:13]
	s_setprio 0
	s_add_u32 s24, s48, 0x40000
	s_addc_u32 s25, s49, 0
	s_add_i32 s39, s51, s94
	s_mov_b32 m0, s39
	s_nop 0
	global_load_lds_dwordx4 v134, s[24:25]
	s_add_i32 m0, s39, 0x2000
	s_nop 0
	global_load_lds_dwordx4 v130, s[24:25]
	s_waitcnt vmcnt(6)
	s_barrier
	s_setprio 1
	v_mfma_f32_16x16x32_bf16 v[54:57], v[226:229], v[194:197], v[54:57]
	ds_read_b128 v[142:145], v249 offset:32768
	ds_read_b128 v[182:185], v249 offset:33792
	v_mfma_f32_16x16x32_bf16 v[54:57], v[230:233], v[198:201], v[54:57]
	ds_read_b128 v[186:189], v249 offset:34816
	ds_read_b128 v[190:193], v249 offset:35840
	v_mfma_f32_16x16x32_bf16 v[50:53], v[234:237], v[194:197], v[50:53]
	ds_read_b128 v[194:197], v166 offset:32768
	v_mfma_f32_16x16x32_bf16 v[50:53], v[238:241], v[198:201], v[50:53]
	ds_read_b128 v[198:201], v166 offset:33792
	v_mfma_f32_16x16x32_bf16 v[38:41], v[226:229], v[202:205], v[38:41]
	v_mfma_f32_16x16x32_bf16 v[38:41], v[230:233], v[206:209], v[38:41]
	v_mfma_f32_16x16x32_bf16 v[34:37], v[234:237], v[202:205], v[34:37]
	ds_read_b128 v[202:205], v166 offset:34816
	v_mfma_f32_16x16x32_bf16 v[34:37], v[238:241], v[206:209], v[34:37]
	ds_read_b128 v[206:209], v166 offset:35840
	v_mfma_f32_16x16x32_bf16 v[22:25], v[226:229], v[210:213], v[22:25]
	v_mfma_f32_16x16x32_bf16 v[22:25], v[230:233], v[214:217], v[22:25]
	v_mfma_f32_16x16x32_bf16 v[18:21], v[234:237], v[210:213], v[18:21]
	v_mfma_f32_16x16x32_bf16 v[18:21], v[238:241], v[214:217], v[18:21]
	v_mfma_f32_16x16x32_bf16 v[6:9], v[226:229], v[218:221], v[6:9]
	v_mfma_f32_16x16x32_bf16 v[6:9], v[230:233], v[222:225], v[6:9]
	v_mfma_f32_16x16x32_bf16 v[2:5], v[234:237], v[218:221], v[2:5]
	s_barrier
	v_mfma_f32_16x16x32_bf16 v[2:5], v[238:241], v[222:225], v[2:5]
	s_setprio 0
	s_add_i32 s39, 0, 0x18000
	s_add_u32 s24, vcc_lo, 0x40000
	s_addc_u32 s25, vcc_hi, 0
	s_mov_b32 m0, s97
	ds_read_b128 v[210:213], v166 offset:36864
	ds_read_b128 v[214:217], v166 offset:37888
	ds_read_b128 v[218:221], v166 offset:38912
	ds_read_b128 v[222:225], v166 offset:39936
	global_load_lds_dwordx4 v136, s[24:25]
	s_mov_b32 m0, s98
	s_nop 0
	global_load_lds_dwordx4 v132, s[24:25]
	s_waitcnt lgkmcnt(8)
	s_barrier
	s_waitcnt lgkmcnt(0)
	s_setprio 1
	s_waitcnt lgkmcnt(0)
	v_mfma_f32_16x16x32_bf16 v[126:129], v[142:145], v[194:197], v[126:129]
	v_mfma_f32_16x16x32_bf16 v[126:129], v[182:185], v[198:201], v[126:129]
	v_mfma_f32_16x16x32_bf16 v[122:125], v[186:189], v[194:197], v[122:125]
	v_mfma_f32_16x16x32_bf16 v[122:125], v[190:193], v[198:201], v[122:125]
	v_mfma_f32_16x16x32_bf16 v[110:113], v[142:145], v[202:205], v[110:113]
	v_mfma_f32_16x16x32_bf16 v[110:113], v[182:185], v[206:209], v[110:113]
	v_mfma_f32_16x16x32_bf16 v[106:109], v[186:189], v[202:205], v[106:109]
	v_mfma_f32_16x16x32_bf16 v[106:109], v[190:193], v[206:209], v[106:109]
	v_mfma_f32_16x16x32_bf16 v[94:97], v[142:145], v[210:213], v[94:97]
	v_mfma_f32_16x16x32_bf16 v[94:97], v[182:185], v[214:217], v[94:97]
	v_mfma_f32_16x16x32_bf16 v[90:93], v[186:189], v[210:213], v[90:93]
	v_mfma_f32_16x16x32_bf16 v[90:93], v[190:193], v[214:217], v[90:93]
	v_mfma_f32_16x16x32_bf16 v[78:81], v[142:145], v[218:221], v[78:81]
	v_mfma_f32_16x16x32_bf16 v[78:81], v[182:185], v[222:225], v[78:81]
	v_mfma_f32_16x16x32_bf16 v[74:77], v[186:189], v[218:221], v[74:77]
	s_barrier
; #define PG8_STAGE(bufoff, gbase, voff) do { _Pragma("unroll") for (int _i = 0; _i < 2; ++_i) \
;         __builtin_amdgcn_global_load_lds((const unsigned*)((const char*)(gbase) + (voff)[_i]), (LAS unsigned*)(lds + (bufoff) + ldsw + _i * 8192), 16, 0, 0); } while (0)
; #define PG8_LDA(dst, b, h) do { _Pragma("unroll") for (int m = 0; m < 4; ++m) _Pragma("unroll") for (int k = 0; k < 2; ++k) dst[m][k] = *(const LAS bf16x8*)(lds + PG8_SA(b, h) + aoff + m * 2048 + k * 1024); } while (0)
; #define PG8_LDB(dst, b, h) do { _Pragma("unroll") for (int n = 0; n < 2; ++n) _Pragma("unroll") for (int k = 0; k < 2; ++k) dst[n][k] = *(const LAS bf16x8*)(lds + PG8_SB(b, h) + boff + n * 2048 + k * 1024); } while (0)
; #define PG8_MMA(ai, bj, At, Bt) do { __builtin_amdgcn_s_setprio(1); _Pragma("unroll") for (int m = 0; m < 4; ++m) _Pragma("unroll") for (int n = 0; n < 2; ++n) _Pragma("unroll") for (int k = 0; k < 2; ++k) \
;         acc[ai][bj][m][n] = __builtin_amdgcn_mfma_f32_16x16x32_bf16(Bt[n][k], At[m][k], acc[ai][bj][m][n], 0, 0, 0); __builtin_amdgcn_s_setprio(0); } while (0)
; #define PG8_WAIT_V(n) asm volatile("s_waitcnt vmcnt(" #n ")" ::: "memory")
; #define PG8_WAIT_L(n) asm volatile("s_waitcnt lgkmcnt(" #n ")" ::: "memory")
; #define PG8_BAR __builtin_amdgcn_s_barrier()
; #define PG8_SCHED __builtin_amdgcn_sched_barrier(0)
; template <class Epi, class Sched>
; __device__ __forceinline__ void gemm_phase(LAS unsigned char* lds, const Gemm g, const Sched& S, const Epi& E) {
;     ...
;             PG8_WAIT_L(8); PG8_BAR; PG8_WAIT_L(0); PG8_MMA(0, 0, At, B0); PG8_BAR; PG8_SCHED;
;             PG8_LDB(B1, 1, 1); PG8_STAGE(PG8_SB(1, 0), b3, voffB);
;             PG8_BAR; PG8_WAIT_L(0); PG8_MMA(0, 1, At, B1); PG8_BAR;
;             PG8_LDA(At, 1, 1); PG8_STAGE(PG8_SA(1, 0), a3, voffA);
;             PG8_BAR; PG8_WAIT_L(0); PG8_MMA(1, 0, At, B0); PG8_BAR; PG8_SCHED;
;             PG8_STAGE(PG8_SB(1, 1), b3 + hstep, voffB);
;             PG8_WAIT_V(6); PG8_BAR; PG8_MMA(1, 1, At, B1); PG8_BAR;
;         }
;         if (wr == 0) PG8_BAR;
	v_mfma_f32_16x16x32_bf16 v[74:77], v[190:193], v[222:225], v[74:77]
	s_setprio 0
	s_add_i32 s51, 0, 0x1c000
	s_add_i32 s24, s39, s94
	s_add_i32 m0, s24, 0xffffff80
	ds_read_b128 v[226:229], v249 offset:49152
	ds_read_b128 v[230:233], v249 offset:50176
	ds_read_b128 v[234:237], v249 offset:51200
	ds_read_b128 v[238:241], v249 offset:52224
	global_load_lds_dwordx4 v134, s[48:49] offset:128
	s_add_i32 m0, s24, 0x1f80
	s_nop 0
	global_load_lds_dwordx4 v130, s[48:49] offset:128
	s_barrier
	s_waitcnt lgkmcnt(0)
	s_setprio 1
	s_waitcnt lgkmcnt(0)
	v_mfma_f32_16x16x32_bf16 v[118:121], v[226:229], v[194:197], v[118:121]
	v_mfma_f32_16x16x32_bf16 v[118:121], v[230:233], v[198:201], v[118:121]
	v_mfma_f32_16x16x32_bf16 v[114:117], v[234:237], v[194:197], v[114:117]
	v_mfma_f32_16x16x32_bf16 v[114:117], v[238:241], v[198:201], v[114:117]
	v_mfma_f32_16x16x32_bf16 v[102:105], v[226:229], v[202:205], v[102:105]
	v_mfma_f32_16x16x32_bf16 v[102:105], v[230:233], v[206:209], v[102:105]
	v_mfma_f32_16x16x32_bf16 v[98:101], v[234:237], v[202:205], v[98:101]
	v_mfma_f32_16x16x32_bf16 v[98:101], v[238:241], v[206:209], v[98:101]
	v_mfma_f32_16x16x32_bf16 v[86:89], v[226:229], v[210:213], v[86:89]
	v_mfma_f32_16x16x32_bf16 v[86:89], v[230:233], v[214:217], v[86:89]
	v_mfma_f32_16x16x32_bf16 v[82:85], v[234:237], v[210:213], v[82:85]
	v_mfma_f32_16x16x32_bf16 v[82:85], v[238:241], v[214:217], v[82:85]
	v_mfma_f32_16x16x32_bf16 v[70:73], v[226:229], v[218:221], v[70:73]
	v_mfma_f32_16x16x32_bf16 v[70:73], v[230:233], v[222:225], v[70:73]
	v_mfma_f32_16x16x32_bf16 v[66:69], v[234:237], v[218:221], v[66:69]
	s_barrier
	v_mfma_f32_16x16x32_bf16 v[66:69], v[238:241], v[222:225], v[66:69]
	s_setprio 0
	s_add_i32 m0, s99, 0xffffff80
	ds_read_b128 v[194:197], v166 offset:49152
	ds_read_b128 v[198:201], v166 offset:50176
	ds_read_b128 v[202:205], v166 offset:51200
	ds_read_b128 v[206:209], v166 offset:52224
	ds_read_b128 v[210:213], v166 offset:53248
	ds_read_b128 v[214:217], v166 offset:54272
	ds_read_b128 v[218:221], v166 offset:55296
	ds_read_b128 v[222:225], v166 offset:56320
	global_load_lds_dwordx4 v136, vcc offset:128
	s_add_i32 m0, s82, 0xffffff80
	s_nop 0
	global_load_lds_dwordx4 v132, vcc offset:128
	s_waitcnt vmcnt(8)
	s_barrier
	s_waitcnt lgkmcnt(0)
	s_setprio 1
	s_waitcnt lgkmcnt(0)
	v_mfma_f32_16x16x32_bf16 v[62:65], v[142:145], v[194:197], v[62:65]
	v_mfma_f32_16x16x32_bf16 v[62:65], v[182:185], v[198:201], v[62:65]
	v_mfma_f32_16x16x32_bf16 v[58:61], v[186:189], v[194:197], v[58:61]
	v_mfma_f32_16x16x32_bf16 v[58:61], v[190:193], v[198:201], v[58:61]
	v_mfma_f32_16x16x32_bf16 v[46:49], v[142:145], v[202:205], v[46:49]
	v_mfma_f32_16x16x32_bf16 v[46:49], v[182:185], v[206:209], v[46:49]
	v_mfma_f32_16x16x32_bf16 v[42:45], v[186:189], v[202:205], v[42:45]
	v_mfma_f32_16x16x32_bf16 v[42:45], v[190:193], v[206:209], v[42:45]
	v_mfma_f32_16x16x32_bf16 v[30:33], v[142:145], v[210:213], v[30:33]
	v_mfma_f32_16x16x32_bf16 v[30:33], v[182:185], v[214:217], v[30:33]
	v_mfma_f32_16x16x32_bf16 v[26:29], v[186:189], v[210:213], v[26:29]
	v_mfma_f32_16x16x32_bf16 v[26:29], v[190:193], v[214:217], v[26:29]
	v_mfma_f32_16x16x32_bf16 v[14:17], v[142:145], v[218:221], v[14:17]
	v_mfma_f32_16x16x32_bf16 v[14:17], v[182:185], v[222:225], v[14:17]
	v_mfma_f32_16x16x32_bf16 v[10:13], v[186:189], v[218:221], v[10:13]
	s_barrier
	v_mfma_f32_16x16x32_bf16 v[10:13], v[190:193], v[222:225], v[10:13]
	s_setprio 0
	s_add_u32 s24, s48, 0x40080
	s_addc_u32 s25, s49, 0
	s_add_i32 s39, s51, s94
	s_mov_b32 m0, s39
	s_nop 0
	global_load_lds_dwordx4 v134, s[24:25]
	s_add_i32 m0, s39, 0x2000
	s_nop 0
	global_load_lds_dwordx4 v130, s[24:25]
	s_waitcnt vmcnt(6)
	s_barrier
	s_setprio 1
	v_mfma_f32_16x16x32_bf16 v[54:57], v[226:229], v[194:197], v[54:57]
	ds_read_b128 v[142:145], v249
	ds_read_b128 v[182:185], v249 offset:1024
	v_mfma_f32_16x16x32_bf16 v[54:57], v[230:233], v[198:201], v[54:57]
	ds_read_b128 v[186:189], v249 offset:2048
	ds_read_b128 v[190:193], v249 offset:3072
	v_mfma_f32_16x16x32_bf16 v[50:53], v[234:237], v[194:197], v[50:53]
	ds_read_b128 v[194:197], v166
	v_mfma_f32_16x16x32_bf16 v[50:53], v[238:241], v[198:201], v[50:53]
	ds_read_b128 v[198:201], v166 offset:1024
	v_mfma_f32_16x16x32_bf16 v[38:41], v[226:229], v[202:205], v[38:41]
	v_mfma_f32_16x16x32_bf16 v[38:41], v[230:233], v[206:209], v[38:41]
	v_mfma_f32_16x16x32_bf16 v[34:37], v[234:237], v[202:205], v[34:37]
	ds_read_b128 v[202:205], v166 offset:2048
	v_mfma_f32_16x16x32_bf16 v[34:37], v[238:241], v[206:209], v[34:37]
	ds_read_b128 v[206:209], v166 offset:3072
	v_mfma_f32_16x16x32_bf16 v[22:25], v[226:229], v[210:213], v[22:25]
	v_mfma_f32_16x16x32_bf16 v[22:25], v[230:233], v[214:217], v[22:25]
	v_mfma_f32_16x16x32_bf16 v[18:21], v[234:237], v[210:213], v[18:21]
	v_mfma_f32_16x16x32_bf16 v[18:21], v[238:241], v[214:217], v[18:21]
	v_mfma_f32_16x16x32_bf16 v[6:9], v[226:229], v[218:221], v[6:9]
	v_mfma_f32_16x16x32_bf16 v[6:9], v[230:233], v[222:225], v[6:9]
	v_mfma_f32_16x16x32_bf16 v[2:5], v[234:237], v[218:221], v[2:5]
	s_barrier
	v_mfma_f32_16x16x32_bf16 v[2:5], v[238:241], v[222:225], v[2:5]
	s_setprio 0
	s_add_i32 s38, s38, 2
	s_add_u32 s35, s35, 0x100
	s_addc_u32 s50, s50, 0
	s_add_u32 s0, s0, 0x100
	s_addc_u32 s1, s1, 0
	s_cmp_gt_u32 s38, 13
	s_cbranch_scc0 .LBB0_557
	s_waitcnt lgkmcnt(0)
	s_and_b64 vcc, exec, s[42:43]
	s_cbranch_vccz .LBB0_560
	s_barrier

; #define PG8_STAGE(bufoff, gbase, voff) do { _Pragma("unroll") for (int _i = 0; _i < 2; ++_i) \
;         __builtin_amdgcn_global_load_lds((const unsigned*)((const char*)(gbase) + (voff)[_i]), (LAS unsigned*)(lds + (bufoff) + ldsw + _i * 8192), 16, 0, 0); } while (0)
; #define PG8_LDA(dst, b, h) do { _Pragma("unroll") for (int m = 0; m < 4; ++m) _Pragma("unroll") for (int k = 0; k < 2; ++k) dst[m][k] = *(const LAS bf16x8*)(lds + PG8_SA(b, h) + aoff + m * 2048 + k * 1024); } while (0)
; #define PG8_LDB(dst, b, h) do { _Pragma("unroll") for (int n = 0; n < 2; ++n) _Pragma("unroll") for (int k = 0; k < 2; ++k) dst[n][k] = *(const LAS bf16x8*)(lds + PG8_SB(b, h) + boff + n * 2048 + k * 1024); } while (0)
; #define PG8_MMA(ai, bj, At, Bt) do { __builtin_amdgcn_s_setprio(1); _Pragma("unroll") for (int m = 0; m < 4; ++m) _Pragma("unroll") for (int n = 0; n < 2; ++n) _Pragma("unroll") for (int k = 0; k < 2; ++k) \
;         acc[ai][bj][m][n] = __builtin_amdgcn_mfma_f32_16x16x32_bf16(Bt[n][k], At[m][k], acc[ai][bj][m][n], 0, 0, 0); __builtin_amdgcn_s_setprio(0); } while (0)
; #define PG8_WAIT_L(n) asm volatile("s_waitcnt lgkmcnt(" #n ")" ::: "memory")
; template <class Epi, class Sched>
; __device__ __forceinline__ void gemm_phase(LAS unsigned char* lds, const Gemm g, const Sched& S, const Epi& E) {
;     ...
;         const bool has_next = S.next(ui + 1, nxt);
;         const char* nA = has_next ? PG8_APANEL(nxt.pm) : cA; const char* nB = has_next ? (const char*)g.Bt + (size_t)nxt.pn * tstep : cB;
;         for (int t = 0; t < nt; t += 2) {
;             const bool last = (t == nt - 2);
;             const char* a1 = cA + (size_t)(t + 1) * kstep;
;             const char* a2 = last ? nA : cA + (size_t)(t + 2) * kstep; const char* b2 = last ? nB : cB + (size_t)(t + 2) * kstep;
;             const char* a3 = a2 + kstep; const char* b3 = b2 + kstep;
;             PG8_LDB(B0, 0, 0); PG8_SCHED; PG8_LDA(At, 0, 0); PG8_STAGE(PG8_SA(1, 1), a1 + hstep, voffA);
;             PG8_WAIT_L(8); PG8_BAR; PG8_WAIT_L(0); PG8_MMA(0, 0, At, B0); PG8_BAR; PG8_SCHED;
;             PG8_LDB(B1, 0, 1); PG8_STAGE(PG8_SB(0, 0), b2, voffB);
;             PG8_BAR; PG8_WAIT_L(0); PG8_MMA(0, 1, At, B1); PG8_BAR;
;             PG8_LDA(At, 0, 1); PG8_STAGE(PG8_SA(0, 0), a2, voffA);
;             PG8_BAR; PG8_WAIT_L(0); PG8_MMA(1, 0, At, B0); PG8_BAR; PG8_SCHED;
.LBB0_626:
	s_ashr_i32 s43, s42, 31
	s_lshl_b64 s[24:25], s[42:43], 21
	s_add_u32 s60, s55, s24
	s_addc_u32 s61, s82, s25
	s_and_b64 s[0:1], s[0:1], exec
	s_cselect_b32 s43, s61, s49
	s_cselect_b32 s45, s60, s48
	s_add_u32 s35, s48, 0x100
	s_addc_u32 s50, s49, 0
	s_add_u32 s0, s76, 0x100080
	s_addc_u32 s1, s77, 0
	s_mov_b32 s98, -2
	v_add_u32_e32 v249, 0x10000, v144
	ds_read_b128 v[164:167], v249
	ds_read_b128 v[182:185], v249 offset:1024
	ds_read_b128 v[186:189], v249 offset:2048
	ds_read_b128 v[190:193], v249 offset:3072
	ds_read_b128 v[194:197], v162
	ds_read_b128 v[198:201], v162 offset:1024
	ds_read_b128 v[202:205], v162 offset:2048
	ds_read_b128 v[206:209], v162 offset:3072
	s_add_u32 s24, s0, 0xfff00080
	s_addc_u32 s25, s1, -1
	s_add_i32 s51, 0, 0x10000
	s_cmp_eq_u32 s98, 60
	s_cselect_b32 s77, s47, s25
	s_cselect_b32 s76, s46, s24
	s_cselect_b32 s49, s43, s50
	s_cselect_b32 s48, s45, s35
	s_add_i32 m0, s86, 0xc000
	ds_read_b128 v[210:213], v162 offset:4096
	ds_read_b128 v[214:217], v162 offset:5120
	ds_read_b128 v[218:221], v162 offset:6144
	ds_read_b128 v[222:225], v162 offset:7168
	global_load_lds_dwordx4 v140, s[0:1]
	s_add_i32 m0, s86, 0xe000
	s_nop 0
	global_load_lds_dwordx4 v138, s[0:1]
	s_waitcnt lgkmcnt(8)
	s_barrier
	s_waitcnt lgkmcnt(0)
	s_setprio 1
	s_waitcnt lgkmcnt(0)
	v_mfma_f32_16x16x32_bf16 v[126:129], v[164:167], v[194:197], 0
	v_mfma_f32_16x16x32_bf16 v[126:129], v[182:185], v[198:201], v[126:129]
	v_mfma_f32_16x16x32_bf16 v[122:125], v[186:189], v[194:197], 0
	v_mfma_f32_16x16x32_bf16 v[122:125], v[190:193], v[198:201], v[122:125]
	v_mfma_f32_16x16x32_bf16 v[118:121], v[164:167], v[202:205], 0
	v_mfma_f32_16x16x32_bf16 v[118:121], v[182:185], v[206:209], v[118:121]
	v_mfma_f32_16x16x32_bf16 v[110:113], v[186:189], v[202:205], 0
	v_mfma_f32_16x16x32_bf16 v[110:113], v[190:193], v[206:209], v[110:113]
	v_mfma_f32_16x16x32_bf16 v[102:105], v[164:167], v[210:213], 0
	v_mfma_f32_16x16x32_bf16 v[102:105], v[182:185], v[214:217], v[102:105]
	v_mfma_f32_16x16x32_bf16 v[94:97], v[186:189], v[210:213], 0
	v_mfma_f32_16x16x32_bf16 v[94:97], v[190:193], v[214:217], v[94:97]
	v_mfma_f32_16x16x32_bf16 v[86:89], v[164:167], v[218:221], 0
	v_mfma_f32_16x16x32_bf16 v[86:89], v[182:185], v[222:225], v[86:89]
	v_mfma_f32_16x16x32_bf16 v[78:81], v[186:189], v[218:221], 0
	s_barrier
	v_mfma_f32_16x16x32_bf16 v[78:81], v[190:193], v[222:225], v[78:81]
	s_setprio 0
	s_add_i32 s99, 0, 0x14000
	s_add_i32 s24, s51, s83
	ds_read_b128 v[226:229], v249 offset:16384
	ds_read_b128 v[230:233], v249 offset:17408
	ds_read_b128 v[234:237], v249 offset:18432
	ds_read_b128 v[238:241], v249 offset:19456
	s_mov_b32 m0, s24
	global_load_lds_dwordx4 v134, s[48:49]
	s_add_i32 m0, s24, 0x2000
	s_nop 0
	global_load_lds_dwordx4 v130, s[48:49]
	s_barrier
	s_waitcnt lgkmcnt(0)
	s_setprio 1
	s_waitcnt lgkmcnt(0)
	v_mfma_f32_16x16x32_bf16 v[114:117], v[226:229], v[194:197], 0
	v_mfma_f32_16x16x32_bf16 v[114:117], v[230:233], v[198:201], v[114:117]
	v_mfma_f32_16x16x32_bf16 v[106:109], v[234:237], v[194:197], 0
	v_mfma_f32_16x16x32_bf16 v[106:109], v[238:241], v[198:201], v[106:109]
	v_mfma_f32_16x16x32_bf16 v[98:101], v[226:229], v[202:205], 0
	v_mfma_f32_16x16x32_bf16 v[98:101], v[230:233], v[206:209], v[98:101]
	v_mfma_f32_16x16x32_bf16 v[90:93], v[234:237], v[202:205], 0
	v_mfma_f32_16x16x32_bf16 v[90:93], v[238:241], v[206:209], v[90:93]
	v_mfma_f32_16x16x32_bf16 v[82:85], v[226:229], v[210:213], 0
	v_mfma_f32_16x16x32_bf16 v[82:85], v[230:233], v[214:217], v[82:85]
	v_mfma_f32_16x16x32_bf16 v[74:77], v[234:237], v[210:213], 0
	v_mfma_f32_16x16x32_bf16 v[74:77], v[238:241], v[214:217], v[74:77]
	v_mfma_f32_16x16x32_bf16 v[70:73], v[226:229], v[218:221], 0
	v_mfma_f32_16x16x32_bf16 v[70:73], v[230:233], v[222:225], v[70:73]
	v_mfma_f32_16x16x32_bf16 v[66:69], v[234:237], v[218:221], 0
	s_barrier
	v_mfma_f32_16x16x32_bf16 v[66:69], v[238:241], v[222:225], v[66:69]
	s_setprio 0
	s_mov_b32 m0, s86
	s_mov_b64 s[100:101], s[76:77]
	ds_read_b128 v[194:197], v162 offset:16384
	ds_read_b128 v[198:201], v162 offset:17408
	ds_read_b128 v[202:205], v162 offset:18432
	ds_read_b128 v[206:209], v162 offset:19456
	ds_read_b128 v[210:213], v162 offset:20480
	ds_read_b128 v[214:217], v162 offset:21504
	ds_read_b128 v[218:221], v162 offset:22528
	ds_read_b128 v[222:225], v162 offset:23552
	global_load_lds_dwordx4 v136, s[76:77]
	s_mov_b64 s[100:101], s[76:77]
	s_mov_b32 m0, s92
	s_nop 0
	global_load_lds_dwordx4 v132, s[76:77]
	s_waitcnt vmcnt(8)
	s_barrier
	s_waitcnt lgkmcnt(0)
	s_setprio 1
	s_waitcnt lgkmcnt(0)
	v_mfma_f32_16x16x32_bf16 v[62:65], v[164:167], v[194:197], 0
	v_mfma_f32_16x16x32_bf16 v[62:65], v[182:185], v[198:201], v[62:65]
	v_mfma_f32_16x16x32_bf16 v[58:61], v[186:189], v[194:197], 0
	v_mfma_f32_16x16x32_bf16 v[58:61], v[190:193], v[198:201], v[58:61]
	v_mfma_f32_16x16x32_bf16 v[54:57], v[164:167], v[202:205], 0
	v_mfma_f32_16x16x32_bf16 v[54:57], v[182:185], v[206:209], v[54:57]
	v_mfma_f32_16x16x32_bf16 v[46:49], v[186:189], v[202:205], 0
	v_mfma_f32_16x16x32_bf16 v[46:49], v[190:193], v[206:209], v[46:49]
	v_mfma_f32_16x16x32_bf16 v[38:41], v[164:167], v[210:213], 0
	v_mfma_f32_16x16x32_bf16 v[38:41], v[182:185], v[214:217], v[38:41]
	v_mfma_f32_16x16x32_bf16 v[30:33], v[186:189], v[210:213], 0
	v_mfma_f32_16x16x32_bf16 v[30:33], v[190:193], v[214:217], v[30:33]
	v_mfma_f32_16x16x32_bf16 v[22:25], v[164:167], v[218:221], 0
	v_mfma_f32_16x16x32_bf16 v[22:25], v[182:185], v[222:225], v[22:25]
	v_mfma_f32_16x16x32_bf16 v[14:17], v[186:189], v[218:221], 0
	s_barrier
; #define PG8_STAGE(bufoff, gbase, voff) do { _Pragma("unroll") for (int _i = 0; _i < 2; ++_i) \
;         __builtin_amdgcn_global_load_lds((const unsigned*)((const char*)(gbase) + (voff)[_i]), (LAS unsigned*)(lds + (bufoff) + ldsw + _i * 8192), 16, 0, 0); } while (0)
; #define PG8_LDA(dst, b, h) do { _Pragma("unroll") for (int m = 0; m < 4; ++m) _Pragma("unroll") for (int k = 0; k < 2; ++k) dst[m][k] = *(const LAS bf16x8*)(lds + PG8_SA(b, h) + aoff + m * 2048 + k * 1024); } while (0)
; #define PG8_LDB(dst, b, h) do { _Pragma("unroll") for (int n = 0; n < 2; ++n) _Pragma("unroll") for (int k = 0; k < 2; ++k) dst[n][k] = *(const LAS bf16x8*)(lds + PG8_SB(b, h) + boff + n * 2048 + k * 1024); } while (0)
; #define PG8_MMA(ai, bj, At, Bt) do { __builtin_amdgcn_s_setprio(1); _Pragma("unroll") for (int m = 0; m < 4; ++m) _Pragma("unroll") for (int n = 0; n < 2; ++n) _Pragma("unroll") for (int k = 0; k < 2; ++k) \
;         acc[ai][bj][m][n] = __builtin_amdgcn_mfma_f32_16x16x32_bf16(Bt[n][k], At[m][k], acc[ai][bj][m][n], 0, 0, 0); __builtin_amdgcn_s_setprio(0); } while (0)
; #define PG8_WAIT_V(n) asm volatile("s_waitcnt vmcnt(" #n ")" ::: "memory")
; #define PG8_WAIT_L(n) asm volatile("s_waitcnt lgkmcnt(" #n ")" ::: "memory")
; #define PG8_BAR __builtin_amdgcn_s_barrier()
; #define PG8_SCHED __builtin_amdgcn_sched_barrier(0)
; template <class Epi, class Sched>
; __device__ __forceinline__ void gemm_phase(LAS unsigned char* lds, const Gemm g, const Sched& S, const Epi& E) {
;     ...
;             PG8_BAR; PG8_WAIT_L(0); PG8_MMA(1, 0, At, B0); PG8_BAR; PG8_SCHED;
;             PG8_STAGE(PG8_SB(0, 1), b2 + hstep, voffB);
;             PG8_WAIT_V(6); PG8_BAR; PG8_MMA(1, 1, At, B1); PG8_BAR;
;             PG8_LDB(B0, 1, 0); PG8_SCHED; PG8_LDA(At, 1, 0); PG8_STAGE(PG8_SA(0, 1), a2 + hstep, voffA);
;             PG8_WAIT_L(8); PG8_BAR; PG8_WAIT_L(0); PG8_MMA(0, 0, At, B0); PG8_BAR; PG8_SCHED;
;             PG8_LDB(B1, 1, 1); PG8_STAGE(PG8_SB(1, 0), b3, voffB);
;             PG8_BAR; PG8_WAIT_L(0); PG8_MMA(0, 1, At, B1); PG8_BAR;
;             PG8_LDA(At, 1, 1); PG8_STAGE(PG8_SA(1, 0), a3, voffA);
	v_mfma_f32_16x16x32_bf16 v[14:17], v[190:193], v[222:225], v[14:17]
	s_setprio 0
	s_add_u32 s24, s48, 0x100000
	s_addc_u32 s25, s49, 0
	s_add_i32 s51, s99, s83
	s_mov_b32 m0, s51
	s_nop 0
	global_load_lds_dwordx4 v134, s[24:25]
	s_add_i32 m0, s51, 0x2000
	s_nop 0
	global_load_lds_dwordx4 v130, s[24:25]
	s_waitcnt vmcnt(6)
	s_barrier
	s_setprio 1
	v_mfma_f32_16x16x32_bf16 v[50:53], v[226:229], v[194:197], 0
	ds_read_b128 v[164:167], v249 offset:32768
	ds_read_b128 v[182:185], v249 offset:33792
	v_mfma_f32_16x16x32_bf16 v[50:53], v[230:233], v[198:201], v[50:53]
	ds_read_b128 v[186:189], v249 offset:34816
	ds_read_b128 v[190:193], v249 offset:35840
	v_mfma_f32_16x16x32_bf16 v[42:45], v[234:237], v[194:197], 0
	ds_read_b128 v[194:197], v162 offset:32768
	v_mfma_f32_16x16x32_bf16 v[42:45], v[238:241], v[198:201], v[42:45]
	ds_read_b128 v[198:201], v162 offset:33792
	v_mfma_f32_16x16x32_bf16 v[34:37], v[226:229], v[202:205], 0
	v_mfma_f32_16x16x32_bf16 v[34:37], v[230:233], v[206:209], v[34:37]
	v_mfma_f32_16x16x32_bf16 v[26:29], v[234:237], v[202:205], 0
	ds_read_b128 v[202:205], v162 offset:34816
	v_mfma_f32_16x16x32_bf16 v[26:29], v[238:241], v[206:209], v[26:29]
	ds_read_b128 v[206:209], v162 offset:35840
	v_mfma_f32_16x16x32_bf16 v[18:21], v[226:229], v[210:213], 0
	v_mfma_f32_16x16x32_bf16 v[18:21], v[230:233], v[214:217], v[18:21]
	v_mfma_f32_16x16x32_bf16 v[10:13], v[234:237], v[210:213], 0
	v_mfma_f32_16x16x32_bf16 v[10:13], v[238:241], v[214:217], v[10:13]
	v_mfma_f32_16x16x32_bf16 v[6:9], v[226:229], v[218:221], 0
	v_mfma_f32_16x16x32_bf16 v[6:9], v[230:233], v[222:225], v[6:9]
	v_mfma_f32_16x16x32_bf16 v[2:5], v[234:237], v[218:221], 0
	s_barrier
	v_mfma_f32_16x16x32_bf16 v[2:5], v[238:241], v[222:225], v[2:5]
	s_setprio 0
	s_add_i32 s51, 0, 0x18000
	s_add_u32 s24, s76, 0x100000
	s_addc_u32 s25, s77, 0
	s_mov_b32 m0, s93
	ds_read_b128 v[210:213], v162 offset:36864
	ds_read_b128 v[214:217], v162 offset:37888
	ds_read_b128 v[218:221], v162 offset:38912
	ds_read_b128 v[222:225], v162 offset:39936
	global_load_lds_dwordx4 v136, s[24:25]
	s_mov_b32 m0, s94
	s_nop 0
	global_load_lds_dwordx4 v132, s[24:25]
	s_waitcnt lgkmcnt(8)
	s_barrier
	s_waitcnt lgkmcnt(0)
	s_setprio 1
	s_waitcnt lgkmcnt(0)
	v_mfma_f32_16x16x32_bf16 v[126:129], v[164:167], v[194:197], v[126:129]
	v_mfma_f32_16x16x32_bf16 v[126:129], v[182:185], v[198:201], v[126:129]
	v_mfma_f32_16x16x32_bf16 v[122:125], v[186:189], v[194:197], v[122:125]
	v_mfma_f32_16x16x32_bf16 v[122:125], v[190:193], v[198:201], v[122:125]
	v_mfma_f32_16x16x32_bf16 v[118:121], v[164:167], v[202:205], v[118:121]
	v_mfma_f32_16x16x32_bf16 v[118:121], v[182:185], v[206:209], v[118:121]
	v_mfma_f32_16x16x32_bf16 v[110:113], v[186:189], v[202:205], v[110:113]
	v_mfma_f32_16x16x32_bf16 v[110:113], v[190:193], v[206:209], v[110:113]
	v_mfma_f32_16x16x32_bf16 v[102:105], v[164:167], v[210:213], v[102:105]
	v_mfma_f32_16x16x32_bf16 v[102:105], v[182:185], v[214:217], v[102:105]
	v_mfma_f32_16x16x32_bf16 v[94:97], v[186:189], v[210:213], v[94:97]
	v_mfma_f32_16x16x32_bf16 v[94:97], v[190:193], v[214:217], v[94:97]
	v_mfma_f32_16x16x32_bf16 v[86:89], v[164:167], v[218:221], v[86:89]
	v_mfma_f32_16x16x32_bf16 v[86:89], v[182:185], v[222:225], v[86:89]
	v_mfma_f32_16x16x32_bf16 v[78:81], v[186:189], v[218:221], v[78:81]
	s_barrier
	v_mfma_f32_16x16x32_bf16 v[78:81], v[190:193], v[222:225], v[78:81]
	s_setprio 0
	s_add_i32 s76, 0, 0x1c000
	s_add_i32 s24, s51, s83
	s_add_i32 m0, s24, 0xffffff80
	ds_read_b128 v[226:229], v249 offset:49152
	ds_read_b128 v[230:233], v249 offset:50176
	ds_read_b128 v[234:237], v249 offset:51200
	ds_read_b128 v[238:241], v249 offset:52224
	global_load_lds_dwordx4 v134, s[48:49] offset:128
	s_add_i32 m0, s24, 0x1f80
	s_nop 0
	global_load_lds_dwordx4 v130, s[48:49] offset:128
	s_barrier
	s_waitcnt lgkmcnt(0)
	s_setprio 1
	s_waitcnt lgkmcnt(0)
	v_mfma_f32_16x16x32_bf16 v[114:117], v[226:229], v[194:197], v[114:117]
	v_mfma_f32_16x16x32_bf16 v[114:117], v[230:233], v[198:201], v[114:117]
	v_mfma_f32_16x16x32_bf16 v[106:109], v[234:237], v[194:197], v[106:109]
	v_mfma_f32_16x16x32_bf16 v[106:109], v[238:241], v[198:201], v[106:109]
	v_mfma_f32_16x16x32_bf16 v[98:101], v[226:229], v[202:205], v[98:101]
	v_mfma_f32_16x16x32_bf16 v[98:101], v[230:233], v[206:209], v[98:101]
	v_mfma_f32_16x16x32_bf16 v[90:93], v[234:237], v[202:205], v[90:93]
	v_mfma_f32_16x16x32_bf16 v[90:93], v[238:241], v[206:209], v[90:93]
	v_mfma_f32_16x16x32_bf16 v[82:85], v[226:229], v[210:213], v[82:85]
	v_mfma_f32_16x16x32_bf16 v[82:85], v[230:233], v[214:217], v[82:85]
	v_mfma_f32_16x16x32_bf16 v[74:77], v[234:237], v[210:213], v[74:77]
	v_mfma_f32_16x16x32_bf16 v[74:77], v[238:241], v[214:217], v[74:77]
	v_mfma_f32_16x16x32_bf16 v[70:73], v[226:229], v[218:221], v[70:73]
	v_mfma_f32_16x16x32_bf16 v[70:73], v[230:233], v[222:225], v[70:73]
	v_mfma_f32_16x16x32_bf16 v[66:69], v[234:237], v[218:221], v[66:69]
	s_barrier
	v_mfma_f32_16x16x32_bf16 v[66:69], v[238:241], v[222:225], v[66:69]
	s_setprio 0
	s_add_i32 m0, s95, 0xffffff80
	ds_read_b128 v[194:197], v162 offset:49152
	ds_read_b128 v[198:201], v162 offset:50176
	ds_read_b128 v[202:205], v162 offset:51200
	ds_read_b128 v[206:209], v162 offset:52224
	ds_read_b128 v[210:213], v162 offset:53248
	ds_read_b128 v[214:217], v162 offset:54272
	ds_read_b128 v[218:221], v162 offset:55296
	ds_read_b128 v[222:225], v162 offset:56320
	global_load_lds_dwordx4 v136, s[100:101] offset:128
	s_add_i32 m0, s96, 0xffffff80
	s_nop 0
	global_load_lds_dwordx4 v132, s[100:101] offset:128
	s_waitcnt vmcnt(8)
	s_barrier
; #define PG8_STAGE(bufoff, gbase, voff) do { _Pragma("unroll") for (int _i = 0; _i < 2; ++_i) \
;         __builtin_amdgcn_global_load_lds((const unsigned*)((const char*)(gbase) + (voff)[_i]), (LAS unsigned*)(lds + (bufoff) + ldsw + _i * 8192), 16, 0, 0); } while (0)
; #define PG8_LDA(dst, b, h) do { _Pragma("unroll") for (int m = 0; m < 4; ++m) _Pragma("unroll") for (int k = 0; k < 2; ++k) dst[m][k] = *(const LAS bf16x8*)(lds + PG8_SA(b, h) + aoff + m * 2048 + k * 1024); } while (0)
; #define PG8_LDB(dst, b, h) do { _Pragma("unroll") for (int n = 0; n < 2; ++n) _Pragma("unroll") for (int k = 0; k < 2; ++k) dst[n][k] = *(const LAS bf16x8*)(lds + PG8_SB(b, h) + boff + n * 2048 + k * 1024); } while (0)
; #define PG8_WAIT_V(n) asm volatile("s_waitcnt vmcnt(" #n ")" ::: "memory")
; #define PG8_WAIT_L(n) asm volatile("s_waitcnt lgkmcnt(" #n ")" ::: "memory")
; #define PG8_BAR __builtin_amdgcn_s_barrier()
; #define PG8_SCHED __builtin_amdgcn_sched_barrier(0)
; template <class Epi, class Sched>
; __device__ __forceinline__ void gemm_phase(LAS unsigned char* lds, const Gemm g, const Sched& S, const Epi& E) {
;     ...
;             PG8_LDB(B0, 0, 0); PG8_SCHED; PG8_LDA(At, 0, 0); PG8_STAGE(PG8_SA(1, 1), a1 + hstep, voffA);
;             PG8_WAIT_L(8); PG8_BAR; PG8_WAIT_L(0); PG8_MMA(0, 0, At, B0); PG8_BAR; PG8_SCHED;
;             PG8_LDB(B1, 0, 1); PG8_STAGE(PG8_SB(0, 0), b2, voffB);
;             PG8_BAR; PG8_WAIT_L(0); PG8_MMA(0, 1, At, B1); PG8_BAR;
;             PG8_LDA(At, 0, 1); PG8_STAGE(PG8_SA(0, 0), a2, voffA);
;             PG8_BAR; PG8_WAIT_L(0); PG8_MMA(1, 0, At, B0); PG8_BAR; PG8_SCHED;
;             PG8_STAGE(PG8_SB(0, 1), b2 + hstep, voffB);
;             PG8_WAIT_V(6); PG8_BAR; PG8_MMA(1, 1, At, B1); PG8_BAR;
;             PG8_LDB(B0, 1, 0); PG8_SCHED; PG8_LDA(At, 1, 0); PG8_STAGE(PG8_SA(0, 1), a2 + hstep, voffA);
;             PG8_WAIT_L(8); PG8_BAR; PG8_WAIT_L(0); PG8_MMA(0, 0, At, B0); PG8_BAR; PG8_SCHED;
;             PG8_LDB(B1, 1, 1); PG8_STAGE(PG8_SB(1, 0), b3, voffB);
;             PG8_BAR; PG8_WAIT_L(0); PG8_MMA(0, 1, At, B1); PG8_BAR;
;             PG8_LDA(At, 1, 1); PG8_STAGE(PG8_SA(1, 0), a3, voffA);
;             PG8_BAR; PG8_WAIT_L(0); PG8_MMA(1, 0, At, B0); PG8_BAR; PG8_SCHED;
;             PG8_STAGE(PG8_SB(1, 1), b3 + hstep, voffB);
;             PG8_WAIT_V(6); PG8_BAR; PG8_MMA(1, 1, At, B1); PG8_BAR;
	s_waitcnt lgkmcnt(0)
	s_setprio 1
	s_waitcnt lgkmcnt(0)
	v_mfma_f32_16x16x32_bf16 v[62:65], v[164:167], v[194:197], v[62:65]
	v_mfma_f32_16x16x32_bf16 v[62:65], v[182:185], v[198:201], v[62:65]
	v_mfma_f32_16x16x32_bf16 v[58:61], v[186:189], v[194:197], v[58:61]
	v_mfma_f32_16x16x32_bf16 v[58:61], v[190:193], v[198:201], v[58:61]
	v_mfma_f32_16x16x32_bf16 v[54:57], v[164:167], v[202:205], v[54:57]
	v_mfma_f32_16x16x32_bf16 v[54:57], v[182:185], v[206:209], v[54:57]
	v_mfma_f32_16x16x32_bf16 v[46:49], v[186:189], v[202:205], v[46:49]
	v_mfma_f32_16x16x32_bf16 v[46:49], v[190:193], v[206:209], v[46:49]
	v_mfma_f32_16x16x32_bf16 v[38:41], v[164:167], v[210:213], v[38:41]
	v_mfma_f32_16x16x32_bf16 v[38:41], v[182:185], v[214:217], v[38:41]
	v_mfma_f32_16x16x32_bf16 v[30:33], v[186:189], v[210:213], v[30:33]
	v_mfma_f32_16x16x32_bf16 v[30:33], v[190:193], v[214:217], v[30:33]
	v_mfma_f32_16x16x32_bf16 v[22:25], v[164:167], v[218:221], v[22:25]
	v_mfma_f32_16x16x32_bf16 v[22:25], v[182:185], v[222:225], v[22:25]
	v_mfma_f32_16x16x32_bf16 v[14:17], v[186:189], v[218:221], v[14:17]
	s_barrier
	v_mfma_f32_16x16x32_bf16 v[14:17], v[190:193], v[222:225], v[14:17]
	s_setprio 0
	s_add_u32 s24, s48, 0x100080
	s_addc_u32 s25, s49, 0
	s_add_i32 s48, s76, s83
	s_mov_b32 m0, s48
	s_nop 0
	global_load_lds_dwordx4 v134, s[24:25]
	s_add_i32 m0, s48, 0x2000
	s_nop 0
	global_load_lds_dwordx4 v130, s[24:25]
	s_waitcnt vmcnt(6)
	s_barrier
	s_setprio 1
	v_mfma_f32_16x16x32_bf16 v[50:53], v[226:229], v[194:197], v[50:53]
	ds_read_b128 v[164:167], v249
	ds_read_b128 v[182:185], v249 offset:1024
	v_mfma_f32_16x16x32_bf16 v[50:53], v[230:233], v[198:201], v[50:53]
	ds_read_b128 v[186:189], v249 offset:2048
	ds_read_b128 v[190:193], v249 offset:3072
	v_mfma_f32_16x16x32_bf16 v[42:45], v[234:237], v[194:197], v[42:45]
	ds_read_b128 v[194:197], v162
	v_mfma_f32_16x16x32_bf16 v[42:45], v[238:241], v[198:201], v[42:45]
	ds_read_b128 v[198:201], v162 offset:1024
	v_mfma_f32_16x16x32_bf16 v[34:37], v[226:229], v[202:205], v[34:37]
	v_mfma_f32_16x16x32_bf16 v[34:37], v[230:233], v[206:209], v[34:37]
	v_mfma_f32_16x16x32_bf16 v[26:29], v[234:237], v[202:205], v[26:29]
	ds_read_b128 v[202:205], v162 offset:2048
	v_mfma_f32_16x16x32_bf16 v[26:29], v[238:241], v[206:209], v[26:29]
	ds_read_b128 v[206:209], v162 offset:3072
	v_mfma_f32_16x16x32_bf16 v[18:21], v[226:229], v[210:213], v[18:21]
	v_mfma_f32_16x16x32_bf16 v[18:21], v[230:233], v[214:217], v[18:21]
	v_mfma_f32_16x16x32_bf16 v[10:13], v[234:237], v[210:213], v[10:13]
	v_mfma_f32_16x16x32_bf16 v[10:13], v[238:241], v[214:217], v[10:13]
	v_mfma_f32_16x16x32_bf16 v[6:9], v[226:229], v[218:221], v[6:9]
	v_mfma_f32_16x16x32_bf16 v[6:9], v[230:233], v[222:225], v[6:9]
	v_mfma_f32_16x16x32_bf16 v[2:5], v[234:237], v[218:221], v[2:5]
	s_barrier
	v_mfma_f32_16x16x32_bf16 v[2:5], v[238:241], v[222:225], v[2:5]
	s_setprio 0
	s_add_i32 s98, s98, 2
	s_add_u32 s35, s35, 0x100
	s_addc_u32 s50, s50, 0
	s_add_u32 s0, s0, 0x100
	s_addc_u32 s1, s1, 0
	s_cmp_gt_u32 s98, 61
.LBB0_627:
	s_add_u32 s24, s0, 0xfff00080
	s_addc_u32 s25, s1, -1
	s_add_i32 s51, 0, 0x10000
	s_cmp_eq_u32 s98, 60
	s_cselect_b32 s77, s47, s25
	s_cselect_b32 s76, s46, s24
	s_cselect_b32 s49, s43, s50
	s_cselect_b32 s48, s45, s35
	s_add_i32 m0, s86, 0xc000
	ds_read_b128 v[210:213], v162 offset:4096
	ds_read_b128 v[214:217], v162 offset:5120
	ds_read_b128 v[218:221], v162 offset:6144
	ds_read_b128 v[222:225], v162 offset:7168
	global_load_lds_dwordx4 v140, s[0:1]
	s_add_i32 m0, s86, 0xe000
	s_nop 0
	global_load_lds_dwordx4 v138, s[0:1]
	s_waitcnt lgkmcnt(8)
	s_barrier
	s_waitcnt lgkmcnt(0)
	s_setprio 1
	s_waitcnt lgkmcnt(0)
	v_mfma_f32_16x16x32_bf16 v[126:129], v[164:167], v[194:197], v[126:129]
	v_mfma_f32_16x16x32_bf16 v[126:129], v[182:185], v[198:201], v[126:129]
	v_mfma_f32_16x16x32_bf16 v[122:125], v[186:189], v[194:197], v[122:125]
	v_mfma_f32_16x16x32_bf16 v[122:125], v[190:193], v[198:201], v[122:125]
	v_mfma_f32_16x16x32_bf16 v[118:121], v[164:167], v[202:205], v[118:121]
	v_mfma_f32_16x16x32_bf16 v[118:121], v[182:185], v[206:209], v[118:121]
	v_mfma_f32_16x16x32_bf16 v[110:113], v[186:189], v[202:205], v[110:113]
	v_mfma_f32_16x16x32_bf16 v[110:113], v[190:193], v[206:209], v[110:113]
	v_mfma_f32_16x16x32_bf16 v[102:105], v[164:167], v[210:213], v[102:105]
	v_mfma_f32_16x16x32_bf16 v[102:105], v[182:185], v[214:217], v[102:105]
	v_mfma_f32_16x16x32_bf16 v[94:97], v[186:189], v[210:213], v[94:97]
	v_mfma_f32_16x16x32_bf16 v[94:97], v[190:193], v[214:217], v[94:97]
	v_mfma_f32_16x16x32_bf16 v[86:89], v[164:167], v[218:221], v[86:89]
	v_mfma_f32_16x16x32_bf16 v[86:89], v[182:185], v[222:225], v[86:89]
	v_mfma_f32_16x16x32_bf16 v[78:81], v[186:189], v[218:221], v[78:81]
	s_barrier
	v_mfma_f32_16x16x32_bf16 v[78:81], v[190:193], v[222:225], v[78:81]
	s_setprio 0
	s_add_i32 s99, 0, 0x14000
	s_add_i32 s24, s51, s83
	ds_read_b128 v[226:229], v249 offset:16384
	ds_read_b128 v[230:233], v249 offset:17408
	ds_read_b128 v[234:237], v249 offset:18432
	ds_read_b128 v[238:241], v249 offset:19456
	s_mov_b32 m0, s24
	global_load_lds_dwordx4 v134, s[48:49]
	s_add_i32 m0, s24, 0x2000
	s_nop 0
	global_load_lds_dwordx4 v130, s[48:49]
	s_barrier
; #define PG8_STAGE(bufoff, gbase, voff) do { _Pragma("unroll") for (int _i = 0; _i < 2; ++_i) \
;         __builtin_amdgcn_global_load_lds((const unsigned*)((const char*)(gbase) + (voff)[_i]), (LAS unsigned*)(lds + (bufoff) + ldsw + _i * 8192), 16, 0, 0); } while (0)
; #define PG8_LDA(dst, b, h) do { _Pragma("unroll") for (int m = 0; m < 4; ++m) _Pragma("unroll") for (int k = 0; k < 2; ++k) dst[m][k] = *(const LAS bf16x8*)(lds + PG8_SA(b, h) + aoff + m * 2048 + k * 1024); } while (0)
; #define PG8_LDB(dst, b, h) do { _Pragma("unroll") for (int n = 0; n < 2; ++n) _Pragma("unroll") for (int k = 0; k < 2; ++k) dst[n][k] = *(const LAS bf16x8*)(lds + PG8_SB(b, h) + boff + n * 2048 + k * 1024); } while (0)
; #define PG8_MMA(ai, bj, At, Bt) do { __builtin_amdgcn_s_setprio(1); _Pragma("unroll") for (int m = 0; m < 4; ++m) _Pragma("unroll") for (int n = 0; n < 2; ++n) _Pragma("unroll") for (int k = 0; k < 2; ++k) \
;         acc[ai][bj][m][n] = __builtin_amdgcn_mfma_f32_16x16x32_bf16(Bt[n][k], At[m][k], acc[ai][bj][m][n], 0, 0, 0); __builtin_amdgcn_s_setprio(0); } while (0)
; #define PG8_WAIT_V(n) asm volatile("s_waitcnt vmcnt(" #n ")" ::: "memory")
; #define PG8_WAIT_L(n) asm volatile("s_waitcnt lgkmcnt(" #n ")" ::: "memory")
; #define PG8_BAR __builtin_amdgcn_s_barrier()
; #define PG8_SCHED __builtin_amdgcn_sched_barrier(0)
; template <class Epi, class Sched>
; __device__ __forceinline__ void gemm_phase(LAS unsigned char* lds, const Gemm g, const Sched& S, const Epi& E) {
;     ...
;             PG8_BAR; PG8_WAIT_L(0); PG8_MMA(0, 1, At, B1); PG8_BAR;
;             PG8_LDA(At, 0, 1); PG8_STAGE(PG8_SA(0, 0), a2, voffA);
;             PG8_BAR; PG8_WAIT_L(0); PG8_MMA(1, 0, At, B0); PG8_BAR; PG8_SCHED;
;             PG8_STAGE(PG8_SB(0, 1), b2 + hstep, voffB);
;             PG8_WAIT_V(6); PG8_BAR; PG8_MMA(1, 1, At, B1); PG8_BAR;
;             PG8_LDB(B0, 1, 0); PG8_SCHED; PG8_LDA(At, 1, 0); PG8_STAGE(PG8_SA(0, 1), a2 + hstep, voffA);
;             PG8_WAIT_L(8); PG8_BAR; PG8_WAIT_L(0); PG8_MMA(0, 0, At, B0); PG8_BAR; PG8_SCHED;
	s_waitcnt lgkmcnt(0)
	s_setprio 1
	s_waitcnt lgkmcnt(0)
	v_mfma_f32_16x16x32_bf16 v[114:117], v[226:229], v[194:197], v[114:117]
	v_mfma_f32_16x16x32_bf16 v[114:117], v[230:233], v[198:201], v[114:117]
	v_mfma_f32_16x16x32_bf16 v[106:109], v[234:237], v[194:197], v[106:109]
	v_mfma_f32_16x16x32_bf16 v[106:109], v[238:241], v[198:201], v[106:109]
	v_mfma_f32_16x16x32_bf16 v[98:101], v[226:229], v[202:205], v[98:101]
	v_mfma_f32_16x16x32_bf16 v[98:101], v[230:233], v[206:209], v[98:101]
	v_mfma_f32_16x16x32_bf16 v[90:93], v[234:237], v[202:205], v[90:93]
	v_mfma_f32_16x16x32_bf16 v[90:93], v[238:241], v[206:209], v[90:93]
	v_mfma_f32_16x16x32_bf16 v[82:85], v[226:229], v[210:213], v[82:85]
	v_mfma_f32_16x16x32_bf16 v[82:85], v[230:233], v[214:217], v[82:85]
	v_mfma_f32_16x16x32_bf16 v[74:77], v[234:237], v[210:213], v[74:77]
	v_mfma_f32_16x16x32_bf16 v[74:77], v[238:241], v[214:217], v[74:77]
	v_mfma_f32_16x16x32_bf16 v[70:73], v[226:229], v[218:221], v[70:73]
	v_mfma_f32_16x16x32_bf16 v[70:73], v[230:233], v[222:225], v[70:73]
	v_mfma_f32_16x16x32_bf16 v[66:69], v[234:237], v[218:221], v[66:69]
	s_barrier
	v_mfma_f32_16x16x32_bf16 v[66:69], v[238:241], v[222:225], v[66:69]
	s_setprio 0
	s_mov_b32 m0, s86
	s_mov_b64 s[100:101], s[76:77]
	ds_read_b128 v[194:197], v162 offset:16384
	ds_read_b128 v[198:201], v162 offset:17408
	ds_read_b128 v[202:205], v162 offset:18432
	ds_read_b128 v[206:209], v162 offset:19456
	ds_read_b128 v[210:213], v162 offset:20480
	ds_read_b128 v[214:217], v162 offset:21504
	ds_read_b128 v[218:221], v162 offset:22528
	ds_read_b128 v[222:225], v162 offset:23552
	global_load_lds_dwordx4 v136, s[76:77]
	s_mov_b64 s[100:101], s[76:77]
	s_mov_b32 m0, s92
	s_nop 0
	global_load_lds_dwordx4 v132, s[76:77]
	s_waitcnt vmcnt(8)
	s_barrier
	s_waitcnt lgkmcnt(0)
	s_setprio 1
	s_waitcnt lgkmcnt(0)
	v_mfma_f32_16x16x32_bf16 v[62:65], v[164:167], v[194:197], v[62:65]
	v_mfma_f32_16x16x32_bf16 v[62:65], v[182:185], v[198:201], v[62:65]
	v_mfma_f32_16x16x32_bf16 v[58:61], v[186:189], v[194:197], v[58:61]
	v_mfma_f32_16x16x32_bf16 v[58:61], v[190:193], v[198:201], v[58:61]
	v_mfma_f32_16x16x32_bf16 v[54:57], v[164:167], v[202:205], v[54:57]
	v_mfma_f32_16x16x32_bf16 v[54:57], v[182:185], v[206:209], v[54:57]
	v_mfma_f32_16x16x32_bf16 v[46:49], v[186:189], v[202:205], v[46:49]
	v_mfma_f32_16x16x32_bf16 v[46:49], v[190:193], v[206:209], v[46:49]
	v_mfma_f32_16x16x32_bf16 v[38:41], v[164:167], v[210:213], v[38:41]
	v_mfma_f32_16x16x32_bf16 v[38:41], v[182:185], v[214:217], v[38:41]
	v_mfma_f32_16x16x32_bf16 v[30:33], v[186:189], v[210:213], v[30:33]
	v_mfma_f32_16x16x32_bf16 v[30:33], v[190:193], v[214:217], v[30:33]
	v_mfma_f32_16x16x32_bf16 v[22:25], v[164:167], v[218:221], v[22:25]
	v_mfma_f32_16x16x32_bf16 v[22:25], v[182:185], v[222:225], v[22:25]
	v_mfma_f32_16x16x32_bf16 v[14:17], v[186:189], v[218:221], v[14:17]
	s_barrier
	v_mfma_f32_16x16x32_bf16 v[14:17], v[190:193], v[222:225], v[14:17]
	s_setprio 0
	s_add_u32 s24, s48, 0x100000
	s_addc_u32 s25, s49, 0
	s_add_i32 s51, s99, s83
	s_mov_b32 m0, s51
	s_nop 0
	global_load_lds_dwordx4 v134, s[24:25]
	s_add_i32 m0, s51, 0x2000
	s_nop 0
	global_load_lds_dwordx4 v130, s[24:25]
	s_waitcnt vmcnt(6)
	s_barrier
	s_setprio 1
	v_mfma_f32_16x16x32_bf16 v[50:53], v[226:229], v[194:197], v[50:53]
	ds_read_b128 v[164:167], v249 offset:32768
	ds_read_b128 v[182:185], v249 offset:33792
	v_mfma_f32_16x16x32_bf16 v[50:53], v[230:233], v[198:201], v[50:53]
	ds_read_b128 v[186:189], v249 offset:34816
	ds_read_b128 v[190:193], v249 offset:35840
	v_mfma_f32_16x16x32_bf16 v[42:45], v[234:237], v[194:197], v[42:45]
	ds_read_b128 v[194:197], v162 offset:32768
	v_mfma_f32_16x16x32_bf16 v[42:45], v[238:241], v[198:201], v[42:45]
	ds_read_b128 v[198:201], v162 offset:33792
	v_mfma_f32_16x16x32_bf16 v[34:37], v[226:229], v[202:205], v[34:37]
	v_mfma_f32_16x16x32_bf16 v[34:37], v[230:233], v[206:209], v[34:37]
	v_mfma_f32_16x16x32_bf16 v[26:29], v[234:237], v[202:205], v[26:29]
	ds_read_b128 v[202:205], v162 offset:34816
	v_mfma_f32_16x16x32_bf16 v[26:29], v[238:241], v[206:209], v[26:29]
	ds_read_b128 v[206:209], v162 offset:35840
	v_mfma_f32_16x16x32_bf16 v[18:21], v[226:229], v[210:213], v[18:21]
	v_mfma_f32_16x16x32_bf16 v[18:21], v[230:233], v[214:217], v[18:21]
	v_mfma_f32_16x16x32_bf16 v[10:13], v[234:237], v[210:213], v[10:13]
	v_mfma_f32_16x16x32_bf16 v[10:13], v[238:241], v[214:217], v[10:13]
	v_mfma_f32_16x16x32_bf16 v[6:9], v[226:229], v[218:221], v[6:9]
	v_mfma_f32_16x16x32_bf16 v[6:9], v[230:233], v[222:225], v[6:9]
	v_mfma_f32_16x16x32_bf16 v[2:5], v[234:237], v[218:221], v[2:5]
	s_barrier
	v_mfma_f32_16x16x32_bf16 v[2:5], v[238:241], v[222:225], v[2:5]
	s_setprio 0
	s_add_i32 s51, 0, 0x18000
	s_add_u32 s24, s76, 0x100000
	s_addc_u32 s25, s77, 0
	s_mov_b32 m0, s93
	ds_read_b128 v[210:213], v162 offset:36864
	ds_read_b128 v[214:217], v162 offset:37888
	ds_read_b128 v[218:221], v162 offset:38912
	ds_read_b128 v[222:225], v162 offset:39936
	global_load_lds_dwordx4 v136, s[24:25]
	s_mov_b32 m0, s94
	s_nop 0
	global_load_lds_dwordx4 v132, s[24:25]
	s_waitcnt lgkmcnt(8)
	s_barrier
; #define PG8_STAGE(bufoff, gbase, voff) do { _Pragma("unroll") for (int _i = 0; _i < 2; ++_i) \
;         __builtin_amdgcn_global_load_lds((const unsigned*)((const char*)(gbase) + (voff)[_i]), (LAS unsigned*)(lds + (bufoff) + ldsw + _i * 8192), 16, 0, 0); } while (0)
; #define PG8_LDA(dst, b, h) do { _Pragma("unroll") for (int m = 0; m < 4; ++m) _Pragma("unroll") for (int k = 0; k < 2; ++k) dst[m][k] = *(const LAS bf16x8*)(lds + PG8_SA(b, h) + aoff + m * 2048 + k * 1024); } while (0)
; #define PG8_LDB(dst, b, h) do { _Pragma("unroll") for (int n = 0; n < 2; ++n) _Pragma("unroll") for (int k = 0; k < 2; ++k) dst[n][k] = *(const LAS bf16x8*)(lds + PG8_SB(b, h) + boff + n * 2048 + k * 1024); } while (0)
; #define PG8_MMA(ai, bj, At, Bt) do { __builtin_amdgcn_s_setprio(1); _Pragma("unroll") for (int m = 0; m < 4; ++m) _Pragma("unroll") for (int n = 0; n < 2; ++n) _Pragma("unroll") for (int k = 0; k < 2; ++k) \
;         acc[ai][bj][m][n] = __builtin_amdgcn_mfma_f32_16x16x32_bf16(Bt[n][k], At[m][k], acc[ai][bj][m][n], 0, 0, 0); __builtin_amdgcn_s_setprio(0); } while (0)
; #define PG8_WAIT_V(n) asm volatile("s_waitcnt vmcnt(" #n ")" ::: "memory")
; #define PG8_WAIT_L(n) asm volatile("s_waitcnt lgkmcnt(" #n ")" ::: "memory")
; #define PG8_BAR __builtin_amdgcn_s_barrier()
; #define PG8_SCHED __builtin_amdgcn_sched_barrier(0)
; template <class Epi, class Sched>
; __device__ __forceinline__ void gemm_phase(LAS unsigned char* lds, const Gemm g, const Sched& S, const Epi& E) {
;     ...
;             PG8_WAIT_L(8); PG8_BAR; PG8_WAIT_L(0); PG8_MMA(0, 0, At, B0); PG8_BAR; PG8_SCHED;
;             PG8_LDB(B1, 1, 1); PG8_STAGE(PG8_SB(1, 0), b3, voffB);
;             PG8_BAR; PG8_WAIT_L(0); PG8_MMA(0, 1, At, B1); PG8_BAR;
;             PG8_LDA(At, 1, 1); PG8_STAGE(PG8_SA(1, 0), a3, voffA);
;             PG8_BAR; PG8_WAIT_L(0); PG8_MMA(1, 0, At, B0); PG8_BAR; PG8_SCHED;
;             PG8_STAGE(PG8_SB(1, 1), b3 + hstep, voffB);
;             PG8_WAIT_V(6); PG8_BAR; PG8_MMA(1, 1, At, B1); PG8_BAR;
;         }
;         if (wr == 0) PG8_BAR;
	s_waitcnt lgkmcnt(0)
	s_setprio 1
	s_waitcnt lgkmcnt(0)
	v_mfma_f32_16x16x32_bf16 v[126:129], v[164:167], v[194:197], v[126:129]
	v_mfma_f32_16x16x32_bf16 v[126:129], v[182:185], v[198:201], v[126:129]
	v_mfma_f32_16x16x32_bf16 v[122:125], v[186:189], v[194:197], v[122:125]
	v_mfma_f32_16x16x32_bf16 v[122:125], v[190:193], v[198:201], v[122:125]
	v_mfma_f32_16x16x32_bf16 v[118:121], v[164:167], v[202:205], v[118:121]
	v_mfma_f32_16x16x32_bf16 v[118:121], v[182:185], v[206:209], v[118:121]
	v_mfma_f32_16x16x32_bf16 v[110:113], v[186:189], v[202:205], v[110:113]
	v_mfma_f32_16x16x32_bf16 v[110:113], v[190:193], v[206:209], v[110:113]
	v_mfma_f32_16x16x32_bf16 v[102:105], v[164:167], v[210:213], v[102:105]
	v_mfma_f32_16x16x32_bf16 v[102:105], v[182:185], v[214:217], v[102:105]
	v_mfma_f32_16x16x32_bf16 v[94:97], v[186:189], v[210:213], v[94:97]
	v_mfma_f32_16x16x32_bf16 v[94:97], v[190:193], v[214:217], v[94:97]
	v_mfma_f32_16x16x32_bf16 v[86:89], v[164:167], v[218:221], v[86:89]
	v_mfma_f32_16x16x32_bf16 v[86:89], v[182:185], v[222:225], v[86:89]
	v_mfma_f32_16x16x32_bf16 v[78:81], v[186:189], v[218:221], v[78:81]
	s_barrier
	v_mfma_f32_16x16x32_bf16 v[78:81], v[190:193], v[222:225], v[78:81]
	s_setprio 0
	s_add_i32 s76, 0, 0x1c000
	s_add_i32 s24, s51, s83
	s_add_i32 m0, s24, 0xffffff80
	ds_read_b128 v[226:229], v249 offset:49152
	ds_read_b128 v[230:233], v249 offset:50176
	ds_read_b128 v[234:237], v249 offset:51200
	ds_read_b128 v[238:241], v249 offset:52224
	global_load_lds_dwordx4 v134, s[48:49] offset:128
	s_add_i32 m0, s24, 0x1f80
	s_nop 0
	global_load_lds_dwordx4 v130, s[48:49] offset:128
	s_barrier
	s_waitcnt lgkmcnt(0)
	s_setprio 1
	s_waitcnt lgkmcnt(0)
	v_mfma_f32_16x16x32_bf16 v[114:117], v[226:229], v[194:197], v[114:117]
	v_mfma_f32_16x16x32_bf16 v[114:117], v[230:233], v[198:201], v[114:117]
	v_mfma_f32_16x16x32_bf16 v[106:109], v[234:237], v[194:197], v[106:109]
	v_mfma_f32_16x16x32_bf16 v[106:109], v[238:241], v[198:201], v[106:109]
	v_mfma_f32_16x16x32_bf16 v[98:101], v[226:229], v[202:205], v[98:101]
	v_mfma_f32_16x16x32_bf16 v[98:101], v[230:233], v[206:209], v[98:101]
	v_mfma_f32_16x16x32_bf16 v[90:93], v[234:237], v[202:205], v[90:93]
	v_mfma_f32_16x16x32_bf16 v[90:93], v[238:241], v[206:209], v[90:93]
	v_mfma_f32_16x16x32_bf16 v[82:85], v[226:229], v[210:213], v[82:85]
	v_mfma_f32_16x16x32_bf16 v[82:85], v[230:233], v[214:217], v[82:85]
	v_mfma_f32_16x16x32_bf16 v[74:77], v[234:237], v[210:213], v[74:77]
	v_mfma_f32_16x16x32_bf16 v[74:77], v[238:241], v[214:217], v[74:77]
	v_mfma_f32_16x16x32_bf16 v[70:73], v[226:229], v[218:221], v[70:73]
	v_mfma_f32_16x16x32_bf16 v[70:73], v[230:233], v[222:225], v[70:73]
	v_mfma_f32_16x16x32_bf16 v[66:69], v[234:237], v[218:221], v[66:69]
	s_barrier
	v_mfma_f32_16x16x32_bf16 v[66:69], v[238:241], v[222:225], v[66:69]
	s_setprio 0
	s_add_i32 m0, s95, 0xffffff80
	ds_read_b128 v[194:197], v162 offset:49152
	ds_read_b128 v[198:201], v162 offset:50176
	ds_read_b128 v[202:205], v162 offset:51200
	ds_read_b128 v[206:209], v162 offset:52224
	ds_read_b128 v[210:213], v162 offset:53248
	ds_read_b128 v[214:217], v162 offset:54272
	ds_read_b128 v[218:221], v162 offset:55296
	ds_read_b128 v[222:225], v162 offset:56320
	global_load_lds_dwordx4 v136, s[100:101] offset:128
	s_add_i32 m0, s96, 0xffffff80
	s_nop 0
	global_load_lds_dwordx4 v132, s[100:101] offset:128
	s_waitcnt vmcnt(8)
	s_barrier
	s_waitcnt lgkmcnt(0)
	s_setprio 1
	s_waitcnt lgkmcnt(0)
	v_mfma_f32_16x16x32_bf16 v[62:65], v[164:167], v[194:197], v[62:65]
	v_mfma_f32_16x16x32_bf16 v[62:65], v[182:185], v[198:201], v[62:65]
	v_mfma_f32_16x16x32_bf16 v[58:61], v[186:189], v[194:197], v[58:61]
	v_mfma_f32_16x16x32_bf16 v[58:61], v[190:193], v[198:201], v[58:61]
	v_mfma_f32_16x16x32_bf16 v[54:57], v[164:167], v[202:205], v[54:57]
	v_mfma_f32_16x16x32_bf16 v[54:57], v[182:185], v[206:209], v[54:57]
	v_mfma_f32_16x16x32_bf16 v[46:49], v[186:189], v[202:205], v[46:49]
	v_mfma_f32_16x16x32_bf16 v[46:49], v[190:193], v[206:209], v[46:49]
	v_mfma_f32_16x16x32_bf16 v[38:41], v[164:167], v[210:213], v[38:41]
	v_mfma_f32_16x16x32_bf16 v[38:41], v[182:185], v[214:217], v[38:41]
	v_mfma_f32_16x16x32_bf16 v[30:33], v[186:189], v[210:213], v[30:33]
	v_mfma_f32_16x16x32_bf16 v[30:33], v[190:193], v[214:217], v[30:33]
	v_mfma_f32_16x16x32_bf16 v[22:25], v[164:167], v[218:221], v[22:25]
	v_mfma_f32_16x16x32_bf16 v[22:25], v[182:185], v[222:225], v[22:25]
	v_mfma_f32_16x16x32_bf16 v[14:17], v[186:189], v[218:221], v[14:17]
	s_barrier
	v_mfma_f32_16x16x32_bf16 v[14:17], v[190:193], v[222:225], v[14:17]
	s_setprio 0
	s_add_u32 s24, s48, 0x100080
	s_addc_u32 s25, s49, 0
	s_add_i32 s48, s76, s83
	s_mov_b32 m0, s48
	s_nop 0
	global_load_lds_dwordx4 v134, s[24:25]
	s_add_i32 m0, s48, 0x2000
	s_nop 0
	global_load_lds_dwordx4 v130, s[24:25]
	s_waitcnt vmcnt(6)
	s_barrier
	s_setprio 1
	v_mfma_f32_16x16x32_bf16 v[50:53], v[226:229], v[194:197], v[50:53]
	ds_read_b128 v[164:167], v249
	ds_read_b128 v[182:185], v249 offset:1024
	v_mfma_f32_16x16x32_bf16 v[50:53], v[230:233], v[198:201], v[50:53]
	ds_read_b128 v[186:189], v249 offset:2048
	ds_read_b128 v[190:193], v249 offset:3072
	v_mfma_f32_16x16x32_bf16 v[42:45], v[234:237], v[194:197], v[42:45]
	ds_read_b128 v[194:197], v162
	v_mfma_f32_16x16x32_bf16 v[42:45], v[238:241], v[198:201], v[42:45]
	ds_read_b128 v[198:201], v162 offset:1024
	v_mfma_f32_16x16x32_bf16 v[34:37], v[226:229], v[202:205], v[34:37]
	v_mfma_f32_16x16x32_bf16 v[34:37], v[230:233], v[206:209], v[34:37]
	v_mfma_f32_16x16x32_bf16 v[26:29], v[234:237], v[202:205], v[26:29]
	ds_read_b128 v[202:205], v162 offset:2048
	v_mfma_f32_16x16x32_bf16 v[26:29], v[238:241], v[206:209], v[26:29]
	ds_read_b128 v[206:209], v162 offset:3072
	v_mfma_f32_16x16x32_bf16 v[18:21], v[226:229], v[210:213], v[18:21]
	v_mfma_f32_16x16x32_bf16 v[18:21], v[230:233], v[214:217], v[18:21]
	v_mfma_f32_16x16x32_bf16 v[10:13], v[234:237], v[210:213], v[10:13]
	v_mfma_f32_16x16x32_bf16 v[10:13], v[238:241], v[214:217], v[10:13]
	v_mfma_f32_16x16x32_bf16 v[6:9], v[226:229], v[218:221], v[6:9]
	v_mfma_f32_16x16x32_bf16 v[6:9], v[230:233], v[222:225], v[6:9]
	v_mfma_f32_16x16x32_bf16 v[2:5], v[234:237], v[218:221], v[2:5]
	s_barrier
	v_mfma_f32_16x16x32_bf16 v[2:5], v[238:241], v[222:225], v[2:5]
	s_setprio 0
	s_add_i32 s98, s98, 2
	s_add_u32 s35, s35, 0x100
	s_addc_u32 s50, s50, 0
	s_add_u32 s0, s0, 0x100
	s_addc_u32 s1, s1, 0
	s_cmp_gt_u32 s98, 61
	s_cbranch_scc0 .LBB0_627
	s_waitcnt lgkmcnt(0)
	s_and_b64 vcc, exec, s[40:41]
	s_cbranch_vccz .LBB0_630
	s_barrier
